# v66 + rw_post: LDS fill wait split per 4-row group (lgkmcnt(12) before group 0, lgkmcnt(0) before group 1)
# speedup vs baseline: 1.0020x; 1.0020x over previous
; #define LAS __attribute__((address_space(3)))
; __device__ __forceinline__ float bf2f(bf16 x) { return __uint_as_float(((unsigned)x) << 16); }
; __device__ __forceinline__ unsigned f2bf(float f) { return cvt_pk_bf16(f, 0.f) & 0xffffu; }
; #define POST_LD(Y_, V_, G_, R_, C_, t) do { _Pragma("unroll") for (int q = 0; q < 8; ++q) { const size_t o_ = (size_t)((t) + q) * DH; Y_[q] = yp[o_]; V_[q] = vp[o_]; G_[q] = gp[o_]; R_[q] = rp[((t) + q) * 32]; C_[q] = cp[o_]; } } while (0)
; __device__ __forceinline__ void rw_post(Frame& F) {
;     ...
;         for (int t0 = 0; t0 < 64; t0 += 8) {
;             float ny[8], nv[8], nr[8], nc[8]; bf16 ng[8];
;             const int tn = t0 + 8 < 64 ? t0 + 8 : t0;
;             POST_LD(ny, nv, ng, nr, nc, tn);
;             if (k > 0) {
;                 LAS float* cs = (LAS float*)(F.lds + 131072 + F.wave * 1024);
; #pragma unroll
;                 for (int hf = 0; hf < 2; ++hf) {
; #pragma unroll
;                     for (int q = 0; q < 4; ++q) cs[q * 64 + lane] = cc[4 * hf + q];
;                     asm volatile("s_waitcnt lgkmcnt(0)" ::: "memory");
; #pragma unroll
;                     for (int q = 0; q < 4; ++q) { f32x4 a = (f32x4){0.f, 0.f, 0.f, 0.f};
; #pragma unroll
;                         for (int i = 0; i < 16; ++i) a = __builtin_elementwise_fma(Sr[i], *(const LAS f32x4*)(cs + q * 64 + 4 * i), a);
;                         y[4 * hf + q] += (a[0] + a[1]) + (a[2] + a[3]); }
;                     asm volatile("s_waitcnt lgkmcnt(0)" ::: "memory"); }
;             }
; #pragma unroll
;             for (int q = 0; q < 8; ++q) { const int row = rb0 + t0 + q;
;                 const float mean = wsum(y[q]) * (1.f / 64.f); const float dv = y[q] - mean; const float var = wsum(dv * dv) * (1.f / 64.f);
;                 const float yn = dv * (1.f / sqrtf(var + 64e-5f)) * g_ + b_;
;                 OB[(size_t)row * DH + col] = (bf16)f2bf((yn + rk[q] * vv[q]) * bf2f(gg[q])); }
.Lpo_s1done:
	s_barrier
	global_load_dwordx4 v[120:123], v11, s[6:7]
	global_load_dwordx4 v[124:127], v11, s[6:7] offset:1024
	global_load_dwordx4 v[128:131], v11, s[8:9]
	global_load_dwordx4 v[132:135], v11, s[8:9] offset:1024
	global_load_dwordx4 v[136:139], v11, s[10:11]
	global_load_dword v159, v158, s[12:13]
	s_add_u32 s6, s6, 0x10000
	s_addc_u32 s7, s7, 0
	s_add_u32 s8, s8, 0x10000
	s_addc_u32 s9, s9, 0
	s_add_u32 s10, s10, 0x8000
	s_addc_u32 s11, s11, 0
	s_add_u32 s12, s12, 0x400
	s_addc_u32 s13, s13, 0
	s_waitcnt vmcnt(0)
	s_waitcnt vmcnt(8)
	ds_write_b128 v12, v[120:123] offset:0
	ds_write_b128 v12, v[124:127] offset:1024
	ds_write_b128 v12, v[128:131] offset:16384
	ds_write_b128 v12, v[132:135] offset:17408
	ds_write_b128 v14, v[136:139]
	v_readlane_b32 s69, v159, 0
	v_readlane_b32 s70, v159, 1
	v_readlane_b32 s71, v159, 2
	v_readlane_b32 s72, v159, 3
	v_readlane_b32 s73, v159, 4
	v_readlane_b32 s26, v159, 5
	v_readlane_b32 s27, v159, 6
	v_readlane_b32 s32, v159, 7
	global_load_dwordx4 v[120:123], v11, s[6:7]
	global_load_dwordx4 v[124:127], v11, s[6:7] offset:1024
	global_load_dwordx4 v[128:131], v11, s[8:9]
	global_load_dwordx4 v[132:135], v11, s[8:9] offset:1024
	global_load_dwordx4 v[136:139], v11, s[10:11]
	global_load_dword v159, v158, s[12:13]
	s_add_u32 s6, s6, 0x10000
	s_addc_u32 s7, s7, 0
	s_add_u32 s8, s8, 0x10000
	s_addc_u32 s9, s9, 0
	s_add_u32 s10, s10, 0x8000
	s_addc_u32 s11, s11, 0
	s_add_u32 s12, s12, 0x400
	s_addc_u32 s13, s13, 0
	s_waitcnt lgkmcnt(0)
	s_barrier
	ds_read_b32 v80, v154 offset:0
	ds_read_b32 v81, v154 offset:16384
	ds_read_u16 v83, v156 offset:0
	ds_read_b32 v85, v154 offset:2048
	ds_read_b32 v86, v154 offset:18432
	ds_read_u16 v88, v156 offset:1024
	ds_read_b32 v90, v154 offset:4096
	ds_read_b32 v91, v154 offset:20480
	ds_read_u16 v93, v156 offset:2048
	ds_read_b32 v95, v154 offset:6144
	ds_read_b32 v96, v154 offset:22528
	ds_read_u16 v98, v156 offset:3072
	ds_read_b32 v100, v154 offset:8192
	ds_read_b32 v101, v154 offset:24576
	ds_read_u16 v103, v156 offset:4096
	ds_read_b32 v105, v154 offset:10240
	ds_read_b32 v106, v154 offset:26624
	ds_read_u16 v108, v156 offset:5120
	ds_read_b32 v110, v154 offset:12288
	ds_read_b32 v111, v154 offset:28672
	ds_read_u16 v113, v156 offset:6144
	ds_read_b32 v115, v154 offset:14336
	ds_read_b32 v116, v154 offset:30720
	ds_read_u16 v118, v156 offset:7168
	s_waitcnt lgkmcnt(12)
	v_add_f32_e32 v80, v80, v16
	v_add_f32_e32 v85, v85, v17
	v_add_f32_e32 v90, v90, v18
	v_add_f32_e32 v95, v95, v19
	v_add_f32_dpp v168, v80, v80 quad_perm:[1,0,3,2] row_mask:0xf bank_mask:0xf bound_ctrl:1
	v_add_f32_dpp v174, v85, v85 quad_perm:[1,0,3,2] row_mask:0xf bank_mask:0xf bound_ctrl:1
	v_add_f32_dpp v241, v90, v90 quad_perm:[1,0,3,2] row_mask:0xf bank_mask:0xf bound_ctrl:1
	v_add_f32_dpp v247, v95, v95 quad_perm:[1,0,3,2] row_mask:0xf bank_mask:0xf bound_ctrl:1
	v_add_f32_dpp v168, v168, v168 quad_perm:[2,3,0,1] row_mask:0xf bank_mask:0xf bound_ctrl:1
	v_add_f32_dpp v174, v174, v174 quad_perm:[2,3,0,1] row_mask:0xf bank_mask:0xf bound_ctrl:1
	v_add_f32_dpp v241, v241, v241 quad_perm:[2,3,0,1] row_mask:0xf bank_mask:0xf bound_ctrl:1
	v_add_f32_dpp v247, v247, v247 quad_perm:[2,3,0,1] row_mask:0xf bank_mask:0xf bound_ctrl:1
	v_add_f32_dpp v168, v168, v168 row_half_mirror row_mask:0xf bank_mask:0xf bound_ctrl:1
	v_add_f32_dpp v174, v174, v174 row_half_mirror row_mask:0xf bank_mask:0xf bound_ctrl:1
	v_add_f32_dpp v241, v241, v241 row_half_mirror row_mask:0xf bank_mask:0xf bound_ctrl:1
	v_add_f32_dpp v247, v247, v247 row_half_mirror row_mask:0xf bank_mask:0xf bound_ctrl:1
	v_add_f32_dpp v168, v168, v168 row_mirror row_mask:0xf bank_mask:0xf bound_ctrl:1
	v_add_f32_dpp v174, v174, v174 row_mirror row_mask:0xf bank_mask:0xf bound_ctrl:1
	v_add_f32_dpp v241, v241, v241 row_mirror row_mask:0xf bank_mask:0xf bound_ctrl:1
	v_add_f32_dpp v247, v247, v247 row_mirror row_mask:0xf bank_mask:0xf bound_ctrl:1
	v_readlane_b32 s36, v168, 16
	v_readlane_b32 s40, v174, 16
	v_readlane_b32 s44, v241, 16
	v_readlane_b32 s48, v247, 16
	v_readlane_b32 s37, v168, 48
	v_readlane_b32 s41, v174, 48
	v_readlane_b32 s45, v241, 48
	v_readlane_b32 s49, v247, 48
	v_readlane_b32 s38, v168, 0
	v_readlane_b32 s42, v174, 0
	v_readlane_b32 s46, v241, 0
	v_readlane_b32 s50, v247, 0
	v_readlane_b32 s39, v168, 32
	v_readlane_b32 s43, v174, 32
	v_readlane_b32 s47, v241, 32
	v_readlane_b32 s51, v247, 32
	v_mov_b32_e32 v168, s36
	v_mov_b32_e32 v174, s40
	v_mov_b32_e32 v241, s44
	v_mov_b32_e32 v247, s48
	v_mov_b32_e32 v169, s37
	v_mov_b32_e32 v175, s41
	v_mov_b32_e32 v242, s45
	v_mov_b32_e32 v248, s49
	v_add_f32_e32 v168, s38, v168
	v_add_f32_e32 v174, s42, v174
	v_add_f32_e32 v241, s46, v241
	v_add_f32_e32 v247, s50, v247
	v_add_f32_e32 v169, s39, v169
	v_add_f32_e32 v175, s43, v175
	v_add_f32_e32 v242, s47, v242
	v_add_f32_e32 v248, s51, v248
	v_add_f32_e32 v168, v168, v169
	v_add_f32_e32 v174, v174, v175
	v_add_f32_e32 v241, v241, v242
	v_add_f32_e32 v247, v247, v248
	v_fmamk_f32 v80, v168, 0xbc800000, v80
	v_fmamk_f32 v85, v174, 0xbc800000, v85
	v_fmamk_f32 v90, v241, 0xbc800000, v90
	v_fmamk_f32 v95, v247, 0xbc800000, v95
	v_mul_f32_e32 v168, v80, v80
	v_mul_f32_e32 v174, v85, v85
	v_mul_f32_e32 v241, v90, v90
	v_mul_f32_e32 v247, v95, v95
	v_mov_b32_dpp v168, v168 quad_perm:[1,0,3,2] row_mask:0xf bank_mask:0xf bound_ctrl:1
	v_mov_b32_dpp v174, v174 quad_perm:[1,0,3,2] row_mask:0xf bank_mask:0xf bound_ctrl:1
	v_mov_b32_dpp v241, v241 quad_perm:[1,0,3,2] row_mask:0xf bank_mask:0xf bound_ctrl:1
	v_mov_b32_dpp v247, v247 quad_perm:[1,0,3,2] row_mask:0xf bank_mask:0xf bound_ctrl:1
	v_fmac_f32_e32 v168, v80, v80
; __device__ __forceinline__ float bf2f(bf16 x) { return __uint_as_float(((unsigned)x) << 16); }
; __device__ __forceinline__ unsigned f2bf(float f) { return cvt_pk_bf16(f, 0.f) & 0xffffu; }
; __device__ __forceinline__ void rw_post(Frame& F) {
;     ...
;             for (int q = 0; q < 8; ++q) { const int row = rb0 + t0 + q;
;                 const float mean = wsum(y[q]) * (1.f / 64.f); const float dv = y[q] - mean; const float var = wsum(dv * dv) * (1.f / 64.f);
;                 const float yn = dv * (1.f / sqrtf(var + 64e-5f)) * g_ + b_;
;                 OB[(size_t)row * DH + col] = (bf16)f2bf((yn + rk[q] * vv[q]) * bf2f(gg[q])); }
	v_fmac_f32_e32 v174, v85, v85
	v_fmac_f32_e32 v241, v90, v90
	v_fmac_f32_e32 v247, v95, v95
	v_add_f32_dpp v168, v168, v168 quad_perm:[2,3,0,1] row_mask:0xf bank_mask:0xf bound_ctrl:1
	v_add_f32_dpp v174, v174, v174 quad_perm:[2,3,0,1] row_mask:0xf bank_mask:0xf bound_ctrl:1
	v_add_f32_dpp v241, v241, v241 quad_perm:[2,3,0,1] row_mask:0xf bank_mask:0xf bound_ctrl:1
	v_add_f32_dpp v247, v247, v247 quad_perm:[2,3,0,1] row_mask:0xf bank_mask:0xf bound_ctrl:1
	v_add_f32_dpp v168, v168, v168 row_half_mirror row_mask:0xf bank_mask:0xf bound_ctrl:1
	v_add_f32_dpp v174, v174, v174 row_half_mirror row_mask:0xf bank_mask:0xf bound_ctrl:1
	v_add_f32_dpp v241, v241, v241 row_half_mirror row_mask:0xf bank_mask:0xf bound_ctrl:1
	v_add_f32_dpp v247, v247, v247 row_half_mirror row_mask:0xf bank_mask:0xf bound_ctrl:1
	v_add_f32_dpp v168, v168, v168 row_mirror row_mask:0xf bank_mask:0xf bound_ctrl:1
	v_add_f32_dpp v174, v174, v174 row_mirror row_mask:0xf bank_mask:0xf bound_ctrl:1
	v_add_f32_dpp v241, v241, v241 row_mirror row_mask:0xf bank_mask:0xf bound_ctrl:1
	v_add_f32_dpp v247, v247, v247 row_mirror row_mask:0xf bank_mask:0xf bound_ctrl:1
	v_readlane_b32 s36, v168, 16
	v_readlane_b32 s40, v174, 16
	v_readlane_b32 s44, v241, 16
	v_readlane_b32 s48, v247, 16
	v_readlane_b32 s37, v168, 48
	v_readlane_b32 s41, v174, 48
	v_readlane_b32 s45, v241, 48
	v_readlane_b32 s49, v247, 48
	v_readlane_b32 s38, v168, 0
	v_readlane_b32 s42, v174, 0
	v_readlane_b32 s46, v241, 0
	v_readlane_b32 s50, v247, 0
	v_readlane_b32 s39, v168, 32
	v_readlane_b32 s43, v174, 32
	v_readlane_b32 s47, v241, 32
	v_readlane_b32 s51, v247, 32
	v_mov_b32_e32 v168, s36
	v_mov_b32_e32 v174, s40
	v_mov_b32_e32 v241, s44
	v_mov_b32_e32 v247, s48
	v_mov_b32_e32 v169, s37
	v_mov_b32_e32 v175, s41
	v_mov_b32_e32 v242, s45
	v_mov_b32_e32 v248, s49
	v_add_f32_e32 v168, s38, v168
	v_add_f32_e32 v174, s42, v174
	v_add_f32_e32 v241, s46, v241
	v_add_f32_e32 v247, s50, v247
	v_add_f32_e32 v169, s39, v169
	v_add_f32_e32 v175, s43, v175
	v_add_f32_e32 v242, s47, v242
	v_add_f32_e32 v248, s51, v248
	v_add_f32_e32 v168, v168, v169
	v_add_f32_e32 v174, v174, v175
	v_add_f32_e32 v241, v241, v242
	v_add_f32_e32 v247, v247, v248
	v_fmamk_f32 v168, v168, 0x3c800000, v9
	v_fmamk_f32 v174, v174, 0x3c800000, v9
	v_fmamk_f32 v241, v241, 0x3c800000, v9
	v_fmamk_f32 v247, v247, 0x3c800000, v9
	v_readfirstlane_b32 s40, v174
	v_readfirstlane_b32 s44, v241
	v_readfirstlane_b32 s48, v247
	v_writelane_b32 v168, s40, 1
	v_writelane_b32 v168, s44, 2
	v_writelane_b32 v168, s48, 3
	v_mul_f32_e32 v169, 0x4f800000, v168
	v_cmp_gt_f32_e64 s[52:53], s68, v168
	v_mov_b32_e32 v170, v168
	s_nop 1
	v_cndmask_b32_e64 v168, v170, v169, s[52:53]
	v_sqrt_f32_e32 v169, v168
	s_nop 0
	v_add_u32_e32 v170, -1, v169
	v_fma_f32 v171, -v170, v169, v168
	v_cmp_ge_f32_e64 s[60:61], 0, v171
	v_add_u32_e32 v171, 1, v169
	s_nop 1
	v_cndmask_b32_e64 v170, v169, v170, s[60:61]
	v_fma_f32 v169, -v171, v169, v168
	v_cmp_lt_f32_e64 s[60:61], 0, v169
	s_nop 1
	v_cndmask_b32_e64 v169, v170, v171, s[60:61]
	v_mul_f32_e32 v170, 0x37800000, v169
	v_cndmask_b32_e64 v169, v169, v170, s[52:53]
	v_cmp_class_f32_e64 s[60:61], v168, v8
	s_nop 1
	v_cndmask_b32_e64 v168, v169, v168, s[60:61]
	v_div_scale_f32 v169, s[60:61], v168, v168, 1.0
	v_rcp_f32_e32 v170, v169
	s_nop 0
	v_fma_f32 v171, -v169, v170, 1.0
	v_fmac_f32_e32 v170, v171, v170
	v_div_scale_f32 v171, vcc, 1.0, v168, 1.0
	v_mul_f32_e32 v172, v171, v170
	v_fma_f32 v173, -v169, v172, v171
	v_fmac_f32_e32 v172, v173, v170
	v_fma_f32 v169, -v169, v172, v171
	v_div_fmas_f32 v169, v169, v170, v172
	v_div_fixup_f32 v168, v169, v168, 1.0
	s_nop 0
	v_readlane_b32 s37, v168, 0
	v_readlane_b32 s41, v168, 1
	v_readlane_b32 s45, v168, 2
	v_readlane_b32 s49, v168, 3
	v_mul_f32_e32 v80, s37, v80
	v_mul_f32_e32 v85, s41, v85
	v_mul_f32_e32 v90, s45, v90
	v_mul_f32_e32 v95, s49, v95
	v_lshlrev_b32_e32 v83, 16, v83
	v_lshlrev_b32_e32 v88, 16, v88
	v_lshlrev_b32_e32 v93, 16, v93
	v_lshlrev_b32_e32 v98, 16, v98
	v_fma_f32 v80, v6, v80, v7
	v_fma_f32 v85, v6, v85, v7
	v_fma_f32 v90, v6, v90, v7
	v_fma_f32 v95, v6, v95, v7
	v_fmac_f32_e32 v80, s69, v81
	v_fmac_f32_e32 v85, s70, v86
	v_fmac_f32_e32 v90, s71, v91
	v_fmac_f32_e32 v95, s72, v96
	v_mul_f32_e32 v80, v80, v83
	v_mul_f32_e32 v85, v85, v88
	v_mul_f32_e32 v90, v90, v93
	v_mul_f32_e32 v95, v95, v98
	v_cvt_pk_bf16_f32 v169, v80, v80
	v_cvt_pk_bf16_f32 v175, v85, v85
	v_cvt_pk_bf16_f32 v242, v90, v90
	v_cvt_pk_bf16_f32 v248, v95, v95
	global_store_short v2, v169, s[28:29]
	s_add_u32 s28, s28, 0x1000
	s_addc_u32 s29, s29, 0
	global_store_short v2, v175, s[28:29]
	s_add_u32 s28, s28, 0x1000
	s_addc_u32 s29, s29, 0
	global_store_short v2, v242, s[28:29]
	s_add_u32 s28, s28, 0x1000
	s_addc_u32 s29, s29, 0
	global_store_short v2, v248, s[28:29]
	s_add_u32 s28, s28, 0x1000
	s_addc_u32 s29, s29, 0
	s_waitcnt lgkmcnt(0)
; __device__ __forceinline__ void rw_post(Frame& F) {
;     ...
;             for (int q = 0; q < 8; ++q) { const int row = rb0 + t0 + q;
;                 const float mean = wsum(y[q]) * (1.f / 64.f); const float dv = y[q] - mean; const float var = wsum(dv * dv) * (1.f / 64.f);
;                 const float yn = dv * (1.f / sqrtf(var + 64e-5f)) * g_ + b_;
	v_add_f32_e32 v100, v100, v32
	v_add_f32_e32 v105, v105, v33
	v_add_f32_e32 v110, v110, v34
	v_add_f32_e32 v115, v115, v35
	v_add_f32_dpp v168, v100, v100 quad_perm:[1,0,3,2] row_mask:0xf bank_mask:0xf bound_ctrl:1
	v_add_f32_dpp v174, v105, v105 quad_perm:[1,0,3,2] row_mask:0xf bank_mask:0xf bound_ctrl:1
	v_add_f32_dpp v241, v110, v110 quad_perm:[1,0,3,2] row_mask:0xf bank_mask:0xf bound_ctrl:1
	v_add_f32_dpp v247, v115, v115 quad_perm:[1,0,3,2] row_mask:0xf bank_mask:0xf bound_ctrl:1
	v_add_f32_dpp v168, v168, v168 quad_perm:[2,3,0,1] row_mask:0xf bank_mask:0xf bound_ctrl:1
	v_add_f32_dpp v174, v174, v174 quad_perm:[2,3,0,1] row_mask:0xf bank_mask:0xf bound_ctrl:1
	v_add_f32_dpp v241, v241, v241 quad_perm:[2,3,0,1] row_mask:0xf bank_mask:0xf bound_ctrl:1
	v_add_f32_dpp v247, v247, v247 quad_perm:[2,3,0,1] row_mask:0xf bank_mask:0xf bound_ctrl:1
	v_add_f32_dpp v168, v168, v168 row_half_mirror row_mask:0xf bank_mask:0xf bound_ctrl:1
	v_add_f32_dpp v174, v174, v174 row_half_mirror row_mask:0xf bank_mask:0xf bound_ctrl:1
	v_add_f32_dpp v241, v241, v241 row_half_mirror row_mask:0xf bank_mask:0xf bound_ctrl:1
	v_add_f32_dpp v247, v247, v247 row_half_mirror row_mask:0xf bank_mask:0xf bound_ctrl:1
	v_add_f32_dpp v168, v168, v168 row_mirror row_mask:0xf bank_mask:0xf bound_ctrl:1
	v_add_f32_dpp v174, v174, v174 row_mirror row_mask:0xf bank_mask:0xf bound_ctrl:1
	v_add_f32_dpp v241, v241, v241 row_mirror row_mask:0xf bank_mask:0xf bound_ctrl:1
	v_add_f32_dpp v247, v247, v247 row_mirror row_mask:0xf bank_mask:0xf bound_ctrl:1
	v_readlane_b32 s36, v168, 16
	v_readlane_b32 s40, v174, 16
	v_readlane_b32 s44, v241, 16
	v_readlane_b32 s48, v247, 16
	v_readlane_b32 s37, v168, 48
	v_readlane_b32 s41, v174, 48
	v_readlane_b32 s45, v241, 48
	v_readlane_b32 s49, v247, 48
	v_readlane_b32 s38, v168, 0
	v_readlane_b32 s42, v174, 0
	v_readlane_b32 s46, v241, 0
	v_readlane_b32 s50, v247, 0
	v_readlane_b32 s39, v168, 32
	v_readlane_b32 s43, v174, 32
	v_readlane_b32 s47, v241, 32
	v_readlane_b32 s51, v247, 32
	v_mov_b32_e32 v168, s36
	v_mov_b32_e32 v174, s40
	v_mov_b32_e32 v241, s44
	v_mov_b32_e32 v247, s48
	v_mov_b32_e32 v169, s37
	v_mov_b32_e32 v175, s41
	v_mov_b32_e32 v242, s45
	v_mov_b32_e32 v248, s49
	v_add_f32_e32 v168, s38, v168
	v_add_f32_e32 v174, s42, v174
	v_add_f32_e32 v241, s46, v241
	v_add_f32_e32 v247, s50, v247
	v_add_f32_e32 v169, s39, v169
	v_add_f32_e32 v175, s43, v175
	v_add_f32_e32 v242, s47, v242
	v_add_f32_e32 v248, s51, v248
	v_add_f32_e32 v168, v168, v169
	v_add_f32_e32 v174, v174, v175
	v_add_f32_e32 v241, v241, v242
	v_add_f32_e32 v247, v247, v248
	v_fmamk_f32 v100, v168, 0xbc800000, v100
	v_fmamk_f32 v105, v174, 0xbc800000, v105
	v_fmamk_f32 v110, v241, 0xbc800000, v110
	v_fmamk_f32 v115, v247, 0xbc800000, v115
	v_mul_f32_e32 v168, v100, v100
	v_mul_f32_e32 v174, v105, v105
	v_mul_f32_e32 v241, v110, v110
	v_mul_f32_e32 v247, v115, v115
	v_mov_b32_dpp v168, v168 quad_perm:[1,0,3,2] row_mask:0xf bank_mask:0xf bound_ctrl:1
	v_mov_b32_dpp v174, v174 quad_perm:[1,0,3,2] row_mask:0xf bank_mask:0xf bound_ctrl:1
	v_mov_b32_dpp v241, v241 quad_perm:[1,0,3,2] row_mask:0xf bank_mask:0xf bound_ctrl:1
	v_mov_b32_dpp v247, v247 quad_perm:[1,0,3,2] row_mask:0xf bank_mask:0xf bound_ctrl:1
	v_fmac_f32_e32 v168, v100, v100
	v_fmac_f32_e32 v174, v105, v105
	v_fmac_f32_e32 v241, v110, v110
	v_fmac_f32_e32 v247, v115, v115
	v_add_f32_dpp v168, v168, v168 quad_perm:[2,3,0,1] row_mask:0xf bank_mask:0xf bound_ctrl:1
	v_add_f32_dpp v174, v174, v174 quad_perm:[2,3,0,1] row_mask:0xf bank_mask:0xf bound_ctrl:1
	v_add_f32_dpp v241, v241, v241 quad_perm:[2,3,0,1] row_mask:0xf bank_mask:0xf bound_ctrl:1
	v_add_f32_dpp v247, v247, v247 quad_perm:[2,3,0,1] row_mask:0xf bank_mask:0xf bound_ctrl:1
	v_add_f32_dpp v168, v168, v168 row_half_mirror row_mask:0xf bank_mask:0xf bound_ctrl:1
	v_add_f32_dpp v174, v174, v174 row_half_mirror row_mask:0xf bank_mask:0xf bound_ctrl:1
	v_add_f32_dpp v241, v241, v241 row_half_mirror row_mask:0xf bank_mask:0xf bound_ctrl:1
	v_add_f32_dpp v247, v247, v247 row_half_mirror row_mask:0xf bank_mask:0xf bound_ctrl:1
	v_add_f32_dpp v168, v168, v168 row_mirror row_mask:0xf bank_mask:0xf bound_ctrl:1
	v_add_f32_dpp v174, v174, v174 row_mirror row_mask:0xf bank_mask:0xf bound_ctrl:1
	v_add_f32_dpp v241, v241, v241 row_mirror row_mask:0xf bank_mask:0xf bound_ctrl:1
	v_add_f32_dpp v247, v247, v247 row_mirror row_mask:0xf bank_mask:0xf bound_ctrl:1
	v_readlane_b32 s36, v168, 16
	v_readlane_b32 s40, v174, 16
	v_readlane_b32 s44, v241, 16
	v_readlane_b32 s48, v247, 16
	v_readlane_b32 s37, v168, 48
	v_readlane_b32 s41, v174, 48
	v_readlane_b32 s45, v241, 48
	v_readlane_b32 s49, v247, 48
	v_readlane_b32 s38, v168, 0
	v_readlane_b32 s42, v174, 0
	v_readlane_b32 s46, v241, 0
	v_readlane_b32 s50, v247, 0
	v_readlane_b32 s39, v168, 32
	v_readlane_b32 s43, v174, 32
	v_readlane_b32 s47, v241, 32
	v_readlane_b32 s51, v247, 32
	v_mov_b32_e32 v168, s36
	v_mov_b32_e32 v174, s40
	v_mov_b32_e32 v241, s44
	v_mov_b32_e32 v247, s48
	v_mov_b32_e32 v169, s37
	v_mov_b32_e32 v175, s41
	v_mov_b32_e32 v242, s45
	v_mov_b32_e32 v248, s49
	v_add_f32_e32 v168, s38, v168
	v_add_f32_e32 v174, s42, v174
	v_add_f32_e32 v241, s46, v241
	v_add_f32_e32 v247, s50, v247
	v_add_f32_e32 v169, s39, v169
	v_add_f32_e32 v175, s43, v175
	v_add_f32_e32 v242, s47, v242
	v_add_f32_e32 v248, s51, v248
	v_add_f32_e32 v168, v168, v169
	v_add_f32_e32 v174, v174, v175
	v_add_f32_e32 v241, v241, v242
	v_add_f32_e32 v247, v247, v248
	v_fmamk_f32 v168, v168, 0x3c800000, v9
	v_fmamk_f32 v174, v174, 0x3c800000, v9
	v_fmamk_f32 v241, v241, 0x3c800000, v9
	v_fmamk_f32 v247, v247, 0x3c800000, v9
; __device__ __forceinline__ float bf2f(bf16 x) { return __uint_as_float(((unsigned)x) << 16); }
; __device__ __forceinline__ unsigned f2bf(float f) { return cvt_pk_bf16(f, 0.f) & 0xffffu; }
; #define POST_LD(Y_, V_, G_, R_, C_, t) do { _Pragma("unroll") for (int q = 0; q < 8; ++q) { const size_t o_ = (size_t)((t) + q) * DH; Y_[q] = yp[o_]; V_[q] = vp[o_]; G_[q] = gp[o_]; R_[q] = rp[((t) + q) * 32]; C_[q] = cp[o_]; } } while (0)
; __device__ __forceinline__ void rw_post(Frame& F) {
;     ...
;         POST_LD(y, vv, gg, rk, cc, 0);
;         for (int t0 = 0; t0 < 64; t0 += 8) {
;             float ny[8], nv[8], nr[8], nc[8]; bf16 ng[8];
;             const int tn = t0 + 8 < 64 ? t0 + 8 : t0;
;             POST_LD(ny, nv, ng, nr, nc, tn);
;     ...
;             for (int q = 0; q < 8; ++q) { const int row = rb0 + t0 + q;
;                 const float mean = wsum(y[q]) * (1.f / 64.f); const float dv = y[q] - mean; const float var = wsum(dv * dv) * (1.f / 64.f);
;                 const float yn = dv * (1.f / sqrtf(var + 64e-5f)) * g_ + b_;
;                 OB[(size_t)row * DH + col] = (bf16)f2bf((yn + rk[q] * vv[q]) * bf2f(gg[q])); }
; #pragma unroll
;             for (int q = 0; q < 8; ++q) { y[q] = ny[q]; vv[q] = nv[q]; gg[q] = ng[q]; rk[q] = nr[q]; cc[q] = nc[q]; }
	v_readfirstlane_b32 s40, v174
	v_readfirstlane_b32 s44, v241
	v_readfirstlane_b32 s48, v247
	v_writelane_b32 v168, s40, 1
	v_writelane_b32 v168, s44, 2
	v_writelane_b32 v168, s48, 3
	v_mul_f32_e32 v169, 0x4f800000, v168
	v_cmp_gt_f32_e64 s[52:53], s68, v168
	v_mov_b32_e32 v170, v168
	s_nop 1
	v_cndmask_b32_e64 v168, v170, v169, s[52:53]
	v_sqrt_f32_e32 v169, v168
	s_nop 0
	v_add_u32_e32 v170, -1, v169
	v_fma_f32 v171, -v170, v169, v168
	v_cmp_ge_f32_e64 s[60:61], 0, v171
	v_add_u32_e32 v171, 1, v169
	s_nop 1
	v_cndmask_b32_e64 v170, v169, v170, s[60:61]
	v_fma_f32 v169, -v171, v169, v168
	v_cmp_lt_f32_e64 s[60:61], 0, v169
	s_nop 1
	v_cndmask_b32_e64 v169, v170, v171, s[60:61]
	v_mul_f32_e32 v170, 0x37800000, v169
	v_cndmask_b32_e64 v169, v169, v170, s[52:53]
	v_cmp_class_f32_e64 s[60:61], v168, v8
	s_nop 1
	v_cndmask_b32_e64 v168, v169, v168, s[60:61]
	v_div_scale_f32 v169, s[60:61], v168, v168, 1.0
	v_rcp_f32_e32 v170, v169
	s_nop 0
	v_fma_f32 v171, -v169, v170, 1.0
	v_fmac_f32_e32 v170, v171, v170
	v_div_scale_f32 v171, vcc, 1.0, v168, 1.0
	v_mul_f32_e32 v172, v171, v170
	v_fma_f32 v173, -v169, v172, v171
	v_fmac_f32_e32 v172, v173, v170
	v_fma_f32 v169, -v169, v172, v171
	v_div_fmas_f32 v169, v169, v170, v172
	v_div_fixup_f32 v168, v169, v168, 1.0
	s_nop 0
	v_readlane_b32 s37, v168, 0
	v_readlane_b32 s41, v168, 1
	v_readlane_b32 s45, v168, 2
	v_readlane_b32 s49, v168, 3
	v_mul_f32_e32 v100, s37, v100
	v_mul_f32_e32 v105, s41, v105
	v_mul_f32_e32 v110, s45, v110
	v_mul_f32_e32 v115, s49, v115
	v_lshlrev_b32_e32 v103, 16, v103
	v_lshlrev_b32_e32 v108, 16, v108
	v_lshlrev_b32_e32 v113, 16, v113
	v_lshlrev_b32_e32 v118, 16, v118
	v_fma_f32 v100, v6, v100, v7
	v_fma_f32 v105, v6, v105, v7
	v_fma_f32 v110, v6, v110, v7
	v_fma_f32 v115, v6, v115, v7
	v_fmac_f32_e32 v100, s73, v101
	v_fmac_f32_e32 v105, s26, v106
	v_fmac_f32_e32 v110, s27, v111
	v_fmac_f32_e32 v115, s32, v116
	v_mul_f32_e32 v100, v100, v103
	v_mul_f32_e32 v105, v105, v108
	v_mul_f32_e32 v110, v110, v113
	v_mul_f32_e32 v115, v115, v118
	v_cvt_pk_bf16_f32 v169, v100, v100
	v_cvt_pk_bf16_f32 v175, v105, v105
	v_cvt_pk_bf16_f32 v242, v110, v110
	v_cvt_pk_bf16_f32 v248, v115, v115
	global_store_short v2, v169, s[28:29]
	s_add_u32 s28, s28, 0x1000
	s_addc_u32 s29, s29, 0
	global_store_short v2, v175, s[28:29]
	s_add_u32 s28, s28, 0x1000
	s_addc_u32 s29, s29, 0
	global_store_short v2, v242, s[28:29]
	s_add_u32 s28, s28, 0x1000
	s_addc_u32 s29, s29, 0
	global_store_short v2, v248, s[28:29]
	s_add_u32 s28, s28, 0x1000
	s_addc_u32 s29, s29, 0
	s_waitcnt vmcnt(8)
	ds_write_b128 v13, v[120:123] offset:0
	ds_write_b128 v13, v[124:127] offset:1024
	ds_write_b128 v13, v[128:131] offset:16384
	ds_write_b128 v13, v[132:135] offset:17408
	ds_write_b128 v15, v[136:139]
	v_readlane_b32 s69, v159, 0
	v_readlane_b32 s70, v159, 1
	v_readlane_b32 s71, v159, 2
	v_readlane_b32 s72, v159, 3
	v_readlane_b32 s73, v159, 4
	v_readlane_b32 s26, v159, 5
	v_readlane_b32 s27, v159, 6
	v_readlane_b32 s32, v159, 7
	global_load_dwordx4 v[120:123], v11, s[6:7]
	global_load_dwordx4 v[124:127], v11, s[6:7] offset:1024
	global_load_dwordx4 v[128:131], v11, s[8:9]
	global_load_dwordx4 v[132:135], v11, s[8:9] offset:1024
	global_load_dwordx4 v[136:139], v11, s[10:11]
	global_load_dword v159, v158, s[12:13]
	s_add_u32 s6, s6, 0x10000
	s_addc_u32 s7, s7, 0
	s_add_u32 s8, s8, 0x10000
	s_addc_u32 s9, s9, 0
	s_add_u32 s10, s10, 0x8000
	s_addc_u32 s11, s11, 0
	s_add_u32 s12, s12, 0x400
	s_addc_u32 s13, s13, 0
	s_waitcnt lgkmcnt(0)
	s_barrier
	ds_read_b32 v80, v155 offset:0
	ds_read_b32 v81, v155 offset:16384
	ds_read_u16 v83, v157 offset:0
	ds_read_b32 v85, v155 offset:2048
	ds_read_b32 v86, v155 offset:18432
	ds_read_u16 v88, v157 offset:1024
	ds_read_b32 v90, v155 offset:4096
	ds_read_b32 v91, v155 offset:20480
	ds_read_u16 v93, v157 offset:2048
	ds_read_b32 v95, v155 offset:6144
	ds_read_b32 v96, v155 offset:22528
	ds_read_u16 v98, v157 offset:3072
	ds_read_b32 v100, v155 offset:8192
	ds_read_b32 v101, v155 offset:24576
	ds_read_u16 v103, v157 offset:4096
	ds_read_b32 v105, v155 offset:10240
	ds_read_b32 v106, v155 offset:26624
	ds_read_u16 v108, v157 offset:5120
	ds_read_b32 v110, v155 offset:12288
	ds_read_b32 v111, v155 offset:28672
	ds_read_u16 v113, v157 offset:6144
	ds_read_b32 v115, v155 offset:14336
	ds_read_b32 v116, v155 offset:30720
	ds_read_u16 v118, v157 offset:7168
	s_waitcnt lgkmcnt(12)
; __device__ __forceinline__ void rw_post(Frame& F) {
;     ...
;             for (int q = 0; q < 8; ++q) { const int row = rb0 + t0 + q;
;                 const float mean = wsum(y[q]) * (1.f / 64.f); const float dv = y[q] - mean; const float var = wsum(dv * dv) * (1.f / 64.f);
;                 const float yn = dv * (1.f / sqrtf(var + 64e-5f)) * g_ + b_;
	v_add_f32_e32 v80, v80, v20
	v_add_f32_e32 v85, v85, v21
	v_add_f32_e32 v90, v90, v22
	v_add_f32_e32 v95, v95, v23
	v_add_f32_dpp v168, v80, v80 quad_perm:[1,0,3,2] row_mask:0xf bank_mask:0xf bound_ctrl:1
	v_add_f32_dpp v174, v85, v85 quad_perm:[1,0,3,2] row_mask:0xf bank_mask:0xf bound_ctrl:1
	v_add_f32_dpp v241, v90, v90 quad_perm:[1,0,3,2] row_mask:0xf bank_mask:0xf bound_ctrl:1
	v_add_f32_dpp v247, v95, v95 quad_perm:[1,0,3,2] row_mask:0xf bank_mask:0xf bound_ctrl:1
	v_add_f32_dpp v168, v168, v168 quad_perm:[2,3,0,1] row_mask:0xf bank_mask:0xf bound_ctrl:1
	v_add_f32_dpp v174, v174, v174 quad_perm:[2,3,0,1] row_mask:0xf bank_mask:0xf bound_ctrl:1
	v_add_f32_dpp v241, v241, v241 quad_perm:[2,3,0,1] row_mask:0xf bank_mask:0xf bound_ctrl:1
	v_add_f32_dpp v247, v247, v247 quad_perm:[2,3,0,1] row_mask:0xf bank_mask:0xf bound_ctrl:1
	v_add_f32_dpp v168, v168, v168 row_half_mirror row_mask:0xf bank_mask:0xf bound_ctrl:1
	v_add_f32_dpp v174, v174, v174 row_half_mirror row_mask:0xf bank_mask:0xf bound_ctrl:1
	v_add_f32_dpp v241, v241, v241 row_half_mirror row_mask:0xf bank_mask:0xf bound_ctrl:1
	v_add_f32_dpp v247, v247, v247 row_half_mirror row_mask:0xf bank_mask:0xf bound_ctrl:1
	v_add_f32_dpp v168, v168, v168 row_mirror row_mask:0xf bank_mask:0xf bound_ctrl:1
	v_add_f32_dpp v174, v174, v174 row_mirror row_mask:0xf bank_mask:0xf bound_ctrl:1
	v_add_f32_dpp v241, v241, v241 row_mirror row_mask:0xf bank_mask:0xf bound_ctrl:1
	v_add_f32_dpp v247, v247, v247 row_mirror row_mask:0xf bank_mask:0xf bound_ctrl:1
	v_readlane_b32 s36, v168, 16
	v_readlane_b32 s40, v174, 16
	v_readlane_b32 s44, v241, 16
	v_readlane_b32 s48, v247, 16
	v_readlane_b32 s37, v168, 48
	v_readlane_b32 s41, v174, 48
	v_readlane_b32 s45, v241, 48
	v_readlane_b32 s49, v247, 48
	v_readlane_b32 s38, v168, 0
	v_readlane_b32 s42, v174, 0
	v_readlane_b32 s46, v241, 0
	v_readlane_b32 s50, v247, 0
	v_readlane_b32 s39, v168, 32
	v_readlane_b32 s43, v174, 32
	v_readlane_b32 s47, v241, 32
	v_readlane_b32 s51, v247, 32
	v_mov_b32_e32 v168, s36
	v_mov_b32_e32 v174, s40
	v_mov_b32_e32 v241, s44
	v_mov_b32_e32 v247, s48
	v_mov_b32_e32 v169, s37
	v_mov_b32_e32 v175, s41
	v_mov_b32_e32 v242, s45
	v_mov_b32_e32 v248, s49
	v_add_f32_e32 v168, s38, v168
	v_add_f32_e32 v174, s42, v174
	v_add_f32_e32 v241, s46, v241
	v_add_f32_e32 v247, s50, v247
	v_add_f32_e32 v169, s39, v169
	v_add_f32_e32 v175, s43, v175
	v_add_f32_e32 v242, s47, v242
	v_add_f32_e32 v248, s51, v248
	v_add_f32_e32 v168, v168, v169
	v_add_f32_e32 v174, v174, v175
	v_add_f32_e32 v241, v241, v242
	v_add_f32_e32 v247, v247, v248
	v_fmamk_f32 v80, v168, 0xbc800000, v80
	v_fmamk_f32 v85, v174, 0xbc800000, v85
	v_fmamk_f32 v90, v241, 0xbc800000, v90
	v_fmamk_f32 v95, v247, 0xbc800000, v95
	v_mul_f32_e32 v168, v80, v80
	v_mul_f32_e32 v174, v85, v85
	v_mul_f32_e32 v241, v90, v90
	v_mul_f32_e32 v247, v95, v95
	v_mov_b32_dpp v168, v168 quad_perm:[1,0,3,2] row_mask:0xf bank_mask:0xf bound_ctrl:1
	v_mov_b32_dpp v174, v174 quad_perm:[1,0,3,2] row_mask:0xf bank_mask:0xf bound_ctrl:1
	v_mov_b32_dpp v241, v241 quad_perm:[1,0,3,2] row_mask:0xf bank_mask:0xf bound_ctrl:1
	v_mov_b32_dpp v247, v247 quad_perm:[1,0,3,2] row_mask:0xf bank_mask:0xf bound_ctrl:1
	v_fmac_f32_e32 v168, v80, v80
	v_fmac_f32_e32 v174, v85, v85
	v_fmac_f32_e32 v241, v90, v90
	v_fmac_f32_e32 v247, v95, v95
	v_add_f32_dpp v168, v168, v168 quad_perm:[2,3,0,1] row_mask:0xf bank_mask:0xf bound_ctrl:1
	v_add_f32_dpp v174, v174, v174 quad_perm:[2,3,0,1] row_mask:0xf bank_mask:0xf bound_ctrl:1
	v_add_f32_dpp v241, v241, v241 quad_perm:[2,3,0,1] row_mask:0xf bank_mask:0xf bound_ctrl:1
	v_add_f32_dpp v247, v247, v247 quad_perm:[2,3,0,1] row_mask:0xf bank_mask:0xf bound_ctrl:1
	v_add_f32_dpp v168, v168, v168 row_half_mirror row_mask:0xf bank_mask:0xf bound_ctrl:1
	v_add_f32_dpp v174, v174, v174 row_half_mirror row_mask:0xf bank_mask:0xf bound_ctrl:1
	v_add_f32_dpp v241, v241, v241 row_half_mirror row_mask:0xf bank_mask:0xf bound_ctrl:1
	v_add_f32_dpp v247, v247, v247 row_half_mirror row_mask:0xf bank_mask:0xf bound_ctrl:1
	v_add_f32_dpp v168, v168, v168 row_mirror row_mask:0xf bank_mask:0xf bound_ctrl:1
	v_add_f32_dpp v174, v174, v174 row_mirror row_mask:0xf bank_mask:0xf bound_ctrl:1
	v_add_f32_dpp v241, v241, v241 row_mirror row_mask:0xf bank_mask:0xf bound_ctrl:1
	v_add_f32_dpp v247, v247, v247 row_mirror row_mask:0xf bank_mask:0xf bound_ctrl:1
	v_readlane_b32 s36, v168, 16
	v_readlane_b32 s40, v174, 16
	v_readlane_b32 s44, v241, 16
	v_readlane_b32 s48, v247, 16
	v_readlane_b32 s37, v168, 48
	v_readlane_b32 s41, v174, 48
	v_readlane_b32 s45, v241, 48
	v_readlane_b32 s49, v247, 48
	v_readlane_b32 s38, v168, 0
	v_readlane_b32 s42, v174, 0
	v_readlane_b32 s46, v241, 0
	v_readlane_b32 s50, v247, 0
	v_readlane_b32 s39, v168, 32
	v_readlane_b32 s43, v174, 32
	v_readlane_b32 s47, v241, 32
	v_readlane_b32 s51, v247, 32
	v_mov_b32_e32 v168, s36
	v_mov_b32_e32 v174, s40
	v_mov_b32_e32 v241, s44
	v_mov_b32_e32 v247, s48
	v_mov_b32_e32 v169, s37
	v_mov_b32_e32 v175, s41
	v_mov_b32_e32 v242, s45
	v_mov_b32_e32 v248, s49
	v_add_f32_e32 v168, s38, v168
	v_add_f32_e32 v174, s42, v174
	v_add_f32_e32 v241, s46, v241
	v_add_f32_e32 v247, s50, v247
	v_add_f32_e32 v169, s39, v169
	v_add_f32_e32 v175, s43, v175
	v_add_f32_e32 v242, s47, v242
	v_add_f32_e32 v248, s51, v248
	v_add_f32_e32 v168, v168, v169
	v_add_f32_e32 v174, v174, v175
	v_add_f32_e32 v241, v241, v242
	v_add_f32_e32 v247, v247, v248
	v_fmamk_f32 v168, v168, 0x3c800000, v9
	v_fmamk_f32 v174, v174, 0x3c800000, v9
	v_fmamk_f32 v241, v241, 0x3c800000, v9
	v_fmamk_f32 v247, v247, 0x3c800000, v9
	v_readfirstlane_b32 s40, v174
	v_readfirstlane_b32 s44, v241
; __device__ __forceinline__ float bf2f(bf16 x) { return __uint_as_float(((unsigned)x) << 16); }
; __device__ __forceinline__ unsigned f2bf(float f) { return cvt_pk_bf16(f, 0.f) & 0xffffu; }
; __device__ __forceinline__ void rw_post(Frame& F) {
;     ...
;             for (int q = 0; q < 8; ++q) { const int row = rb0 + t0 + q;
;                 const float mean = wsum(y[q]) * (1.f / 64.f); const float dv = y[q] - mean; const float var = wsum(dv * dv) * (1.f / 64.f);
;                 const float yn = dv * (1.f / sqrtf(var + 64e-5f)) * g_ + b_;
;                 OB[(size_t)row * DH + col] = (bf16)f2bf((yn + rk[q] * vv[q]) * bf2f(gg[q])); }
	v_readfirstlane_b32 s48, v247
	v_writelane_b32 v168, s40, 1
	v_writelane_b32 v168, s44, 2
	v_writelane_b32 v168, s48, 3
	v_mul_f32_e32 v169, 0x4f800000, v168
	v_cmp_gt_f32_e64 s[52:53], s68, v168
	v_mov_b32_e32 v170, v168
	s_nop 1
	v_cndmask_b32_e64 v168, v170, v169, s[52:53]
	v_sqrt_f32_e32 v169, v168
	s_nop 0
	v_add_u32_e32 v170, -1, v169
	v_fma_f32 v171, -v170, v169, v168
	v_cmp_ge_f32_e64 s[60:61], 0, v171
	v_add_u32_e32 v171, 1, v169
	s_nop 1
	v_cndmask_b32_e64 v170, v169, v170, s[60:61]
	v_fma_f32 v169, -v171, v169, v168
	v_cmp_lt_f32_e64 s[60:61], 0, v169
	s_nop 1
	v_cndmask_b32_e64 v169, v170, v171, s[60:61]
	v_mul_f32_e32 v170, 0x37800000, v169
	v_cndmask_b32_e64 v169, v169, v170, s[52:53]
	v_cmp_class_f32_e64 s[60:61], v168, v8
	s_nop 1
	v_cndmask_b32_e64 v168, v169, v168, s[60:61]
	v_div_scale_f32 v169, s[60:61], v168, v168, 1.0
	v_rcp_f32_e32 v170, v169
	s_nop 0
	v_fma_f32 v171, -v169, v170, 1.0
	v_fmac_f32_e32 v170, v171, v170
	v_div_scale_f32 v171, vcc, 1.0, v168, 1.0
	v_mul_f32_e32 v172, v171, v170
	v_fma_f32 v173, -v169, v172, v171
	v_fmac_f32_e32 v172, v173, v170
	v_fma_f32 v169, -v169, v172, v171
	v_div_fmas_f32 v169, v169, v170, v172
	v_div_fixup_f32 v168, v169, v168, 1.0
	s_nop 0
	v_readlane_b32 s37, v168, 0
	v_readlane_b32 s41, v168, 1
	v_readlane_b32 s45, v168, 2
	v_readlane_b32 s49, v168, 3
	v_mul_f32_e32 v80, s37, v80
	v_mul_f32_e32 v85, s41, v85
	v_mul_f32_e32 v90, s45, v90
	v_mul_f32_e32 v95, s49, v95
	v_lshlrev_b32_e32 v83, 16, v83
	v_lshlrev_b32_e32 v88, 16, v88
	v_lshlrev_b32_e32 v93, 16, v93
	v_lshlrev_b32_e32 v98, 16, v98
	v_fma_f32 v80, v6, v80, v7
	v_fma_f32 v85, v6, v85, v7
	v_fma_f32 v90, v6, v90, v7
	v_fma_f32 v95, v6, v95, v7
	v_fmac_f32_e32 v80, s69, v81
	v_fmac_f32_e32 v85, s70, v86
	v_fmac_f32_e32 v90, s71, v91
	v_fmac_f32_e32 v95, s72, v96
	v_mul_f32_e32 v80, v80, v83
	v_mul_f32_e32 v85, v85, v88
	v_mul_f32_e32 v90, v90, v93
	v_mul_f32_e32 v95, v95, v98
	v_cvt_pk_bf16_f32 v169, v80, v80
	v_cvt_pk_bf16_f32 v175, v85, v85
	v_cvt_pk_bf16_f32 v242, v90, v90
	v_cvt_pk_bf16_f32 v248, v95, v95
	global_store_short v2, v169, s[28:29]
	s_add_u32 s28, s28, 0x1000
	s_addc_u32 s29, s29, 0
	global_store_short v2, v175, s[28:29]
	s_add_u32 s28, s28, 0x1000
	s_addc_u32 s29, s29, 0
	global_store_short v2, v242, s[28:29]
	s_add_u32 s28, s28, 0x1000
	s_addc_u32 s29, s29, 0
	global_store_short v2, v248, s[28:29]
	s_add_u32 s28, s28, 0x1000
	s_addc_u32 s29, s29, 0
	s_waitcnt lgkmcnt(0)
	v_add_f32_e32 v100, v100, v36
	v_add_f32_e32 v105, v105, v37
	v_add_f32_e32 v110, v110, v38
	v_add_f32_e32 v115, v115, v39
	v_add_f32_dpp v168, v100, v100 quad_perm:[1,0,3,2] row_mask:0xf bank_mask:0xf bound_ctrl:1
	v_add_f32_dpp v174, v105, v105 quad_perm:[1,0,3,2] row_mask:0xf bank_mask:0xf bound_ctrl:1
	v_add_f32_dpp v241, v110, v110 quad_perm:[1,0,3,2] row_mask:0xf bank_mask:0xf bound_ctrl:1
	v_add_f32_dpp v247, v115, v115 quad_perm:[1,0,3,2] row_mask:0xf bank_mask:0xf bound_ctrl:1
	v_add_f32_dpp v168, v168, v168 quad_perm:[2,3,0,1] row_mask:0xf bank_mask:0xf bound_ctrl:1
	v_add_f32_dpp v174, v174, v174 quad_perm:[2,3,0,1] row_mask:0xf bank_mask:0xf bound_ctrl:1
	v_add_f32_dpp v241, v241, v241 quad_perm:[2,3,0,1] row_mask:0xf bank_mask:0xf bound_ctrl:1
	v_add_f32_dpp v247, v247, v247 quad_perm:[2,3,0,1] row_mask:0xf bank_mask:0xf bound_ctrl:1
	v_add_f32_dpp v168, v168, v168 row_half_mirror row_mask:0xf bank_mask:0xf bound_ctrl:1
	v_add_f32_dpp v174, v174, v174 row_half_mirror row_mask:0xf bank_mask:0xf bound_ctrl:1
	v_add_f32_dpp v241, v241, v241 row_half_mirror row_mask:0xf bank_mask:0xf bound_ctrl:1
	v_add_f32_dpp v247, v247, v247 row_half_mirror row_mask:0xf bank_mask:0xf bound_ctrl:1
	v_add_f32_dpp v168, v168, v168 row_mirror row_mask:0xf bank_mask:0xf bound_ctrl:1
	v_add_f32_dpp v174, v174, v174 row_mirror row_mask:0xf bank_mask:0xf bound_ctrl:1
	v_add_f32_dpp v241, v241, v241 row_mirror row_mask:0xf bank_mask:0xf bound_ctrl:1
	v_add_f32_dpp v247, v247, v247 row_mirror row_mask:0xf bank_mask:0xf bound_ctrl:1
	v_readlane_b32 s36, v168, 16
	v_readlane_b32 s40, v174, 16
	v_readlane_b32 s44, v241, 16
	v_readlane_b32 s48, v247, 16
	v_readlane_b32 s37, v168, 48
	v_readlane_b32 s41, v174, 48
	v_readlane_b32 s45, v241, 48
	v_readlane_b32 s49, v247, 48
	v_readlane_b32 s38, v168, 0
	v_readlane_b32 s42, v174, 0
	v_readlane_b32 s46, v241, 0
	v_readlane_b32 s50, v247, 0
	v_readlane_b32 s39, v168, 32
	v_readlane_b32 s43, v174, 32
	v_readlane_b32 s47, v241, 32
	v_readlane_b32 s51, v247, 32
	v_mov_b32_e32 v168, s36
	v_mov_b32_e32 v174, s40
	v_mov_b32_e32 v241, s44
	v_mov_b32_e32 v247, s48
	v_mov_b32_e32 v169, s37
	v_mov_b32_e32 v175, s41
	v_mov_b32_e32 v242, s45
	v_mov_b32_e32 v248, s49
	v_add_f32_e32 v168, s38, v168
	v_add_f32_e32 v174, s42, v174
	v_add_f32_e32 v241, s46, v241
	v_add_f32_e32 v247, s50, v247
	v_add_f32_e32 v169, s39, v169
	v_add_f32_e32 v175, s43, v175
	v_add_f32_e32 v242, s47, v242
	v_add_f32_e32 v248, s51, v248
	v_add_f32_e32 v168, v168, v169
	v_add_f32_e32 v174, v174, v175
	v_add_f32_e32 v241, v241, v242
	v_add_f32_e32 v247, v247, v248
	v_fmamk_f32 v100, v168, 0xbc800000, v100
	v_fmamk_f32 v105, v174, 0xbc800000, v105
	v_fmamk_f32 v110, v241, 0xbc800000, v110
	v_fmamk_f32 v115, v247, 0xbc800000, v115
	v_mul_f32_e32 v168, v100, v100
	v_mul_f32_e32 v174, v105, v105
	v_mul_f32_e32 v241, v110, v110
	v_mul_f32_e32 v247, v115, v115
	v_mov_b32_dpp v168, v168 quad_perm:[1,0,3,2] row_mask:0xf bank_mask:0xf bound_ctrl:1
	v_mov_b32_dpp v174, v174 quad_perm:[1,0,3,2] row_mask:0xf bank_mask:0xf bound_ctrl:1
	v_mov_b32_dpp v241, v241 quad_perm:[1,0,3,2] row_mask:0xf bank_mask:0xf bound_ctrl:1
; __device__ __forceinline__ float bf2f(bf16 x) { return __uint_as_float(((unsigned)x) << 16); }
; __device__ __forceinline__ unsigned f2bf(float f) { return cvt_pk_bf16(f, 0.f) & 0xffffu; }
; __device__ __forceinline__ void rw_post(Frame& F) {
;     ...
;             for (int q = 0; q < 8; ++q) { const int row = rb0 + t0 + q;
;                 const float mean = wsum(y[q]) * (1.f / 64.f); const float dv = y[q] - mean; const float var = wsum(dv * dv) * (1.f / 64.f);
;                 const float yn = dv * (1.f / sqrtf(var + 64e-5f)) * g_ + b_;
;                 OB[(size_t)row * DH + col] = (bf16)f2bf((yn + rk[q] * vv[q]) * bf2f(gg[q])); }
; #pragma unroll
;             for (int q = 0; q < 8; ++q) { y[q] = ny[q]; vv[q] = nv[q]; gg[q] = ng[q]; rk[q] = nr[q]; cc[q] = nc[q]; }
	v_mov_b32_dpp v247, v247 quad_perm:[1,0,3,2] row_mask:0xf bank_mask:0xf bound_ctrl:1
	v_fmac_f32_e32 v168, v100, v100
	v_fmac_f32_e32 v174, v105, v105
	v_fmac_f32_e32 v241, v110, v110
	v_fmac_f32_e32 v247, v115, v115
	v_add_f32_dpp v168, v168, v168 quad_perm:[2,3,0,1] row_mask:0xf bank_mask:0xf bound_ctrl:1
	v_add_f32_dpp v174, v174, v174 quad_perm:[2,3,0,1] row_mask:0xf bank_mask:0xf bound_ctrl:1
	v_add_f32_dpp v241, v241, v241 quad_perm:[2,3,0,1] row_mask:0xf bank_mask:0xf bound_ctrl:1
	v_add_f32_dpp v247, v247, v247 quad_perm:[2,3,0,1] row_mask:0xf bank_mask:0xf bound_ctrl:1
	v_add_f32_dpp v168, v168, v168 row_half_mirror row_mask:0xf bank_mask:0xf bound_ctrl:1
	v_add_f32_dpp v174, v174, v174 row_half_mirror row_mask:0xf bank_mask:0xf bound_ctrl:1
	v_add_f32_dpp v241, v241, v241 row_half_mirror row_mask:0xf bank_mask:0xf bound_ctrl:1
	v_add_f32_dpp v247, v247, v247 row_half_mirror row_mask:0xf bank_mask:0xf bound_ctrl:1
	v_add_f32_dpp v168, v168, v168 row_mirror row_mask:0xf bank_mask:0xf bound_ctrl:1
	v_add_f32_dpp v174, v174, v174 row_mirror row_mask:0xf bank_mask:0xf bound_ctrl:1
	v_add_f32_dpp v241, v241, v241 row_mirror row_mask:0xf bank_mask:0xf bound_ctrl:1
	v_add_f32_dpp v247, v247, v247 row_mirror row_mask:0xf bank_mask:0xf bound_ctrl:1
	v_readlane_b32 s36, v168, 16
	v_readlane_b32 s40, v174, 16
	v_readlane_b32 s44, v241, 16
	v_readlane_b32 s48, v247, 16
	v_readlane_b32 s37, v168, 48
	v_readlane_b32 s41, v174, 48
	v_readlane_b32 s45, v241, 48
	v_readlane_b32 s49, v247, 48
	v_readlane_b32 s38, v168, 0
	v_readlane_b32 s42, v174, 0
	v_readlane_b32 s46, v241, 0
	v_readlane_b32 s50, v247, 0
	v_readlane_b32 s39, v168, 32
	v_readlane_b32 s43, v174, 32
	v_readlane_b32 s47, v241, 32
	v_readlane_b32 s51, v247, 32
	v_mov_b32_e32 v168, s36
	v_mov_b32_e32 v174, s40
	v_mov_b32_e32 v241, s44
	v_mov_b32_e32 v247, s48
	v_mov_b32_e32 v169, s37
	v_mov_b32_e32 v175, s41
	v_mov_b32_e32 v242, s45
	v_mov_b32_e32 v248, s49
	v_add_f32_e32 v168, s38, v168
	v_add_f32_e32 v174, s42, v174
	v_add_f32_e32 v241, s46, v241
	v_add_f32_e32 v247, s50, v247
	v_add_f32_e32 v169, s39, v169
	v_add_f32_e32 v175, s43, v175
	v_add_f32_e32 v242, s47, v242
	v_add_f32_e32 v248, s51, v248
	v_add_f32_e32 v168, v168, v169
	v_add_f32_e32 v174, v174, v175
	v_add_f32_e32 v241, v241, v242
	v_add_f32_e32 v247, v247, v248
	v_fmamk_f32 v168, v168, 0x3c800000, v9
	v_fmamk_f32 v174, v174, 0x3c800000, v9
	v_fmamk_f32 v241, v241, 0x3c800000, v9
	v_fmamk_f32 v247, v247, 0x3c800000, v9
	v_readfirstlane_b32 s40, v174
	v_readfirstlane_b32 s44, v241
	v_readfirstlane_b32 s48, v247
	v_writelane_b32 v168, s40, 1
	v_writelane_b32 v168, s44, 2
	v_writelane_b32 v168, s48, 3
	v_mul_f32_e32 v169, 0x4f800000, v168
	v_cmp_gt_f32_e64 s[52:53], s68, v168
	v_mov_b32_e32 v170, v168
	s_nop 1
	v_cndmask_b32_e64 v168, v170, v169, s[52:53]
	v_sqrt_f32_e32 v169, v168
	s_nop 0
	v_add_u32_e32 v170, -1, v169
	v_fma_f32 v171, -v170, v169, v168
	v_cmp_ge_f32_e64 s[60:61], 0, v171
	v_add_u32_e32 v171, 1, v169
	s_nop 1
	v_cndmask_b32_e64 v170, v169, v170, s[60:61]
	v_fma_f32 v169, -v171, v169, v168
	v_cmp_lt_f32_e64 s[60:61], 0, v169
	s_nop 1
	v_cndmask_b32_e64 v169, v170, v171, s[60:61]
	v_mul_f32_e32 v170, 0x37800000, v169
	v_cndmask_b32_e64 v169, v169, v170, s[52:53]
	v_cmp_class_f32_e64 s[60:61], v168, v8
	s_nop 1
	v_cndmask_b32_e64 v168, v169, v168, s[60:61]
	v_div_scale_f32 v169, s[60:61], v168, v168, 1.0
	v_rcp_f32_e32 v170, v169
	s_nop 0
	v_fma_f32 v171, -v169, v170, 1.0
	v_fmac_f32_e32 v170, v171, v170
	v_div_scale_f32 v171, vcc, 1.0, v168, 1.0
	v_mul_f32_e32 v172, v171, v170
	v_fma_f32 v173, -v169, v172, v171
	v_fmac_f32_e32 v172, v173, v170
	v_fma_f32 v169, -v169, v172, v171
	v_div_fmas_f32 v169, v169, v170, v172
	v_div_fixup_f32 v168, v169, v168, 1.0
	s_nop 0
	v_readlane_b32 s37, v168, 0
	v_readlane_b32 s41, v168, 1
	v_readlane_b32 s45, v168, 2
	v_readlane_b32 s49, v168, 3
	v_mul_f32_e32 v100, s37, v100
	v_mul_f32_e32 v105, s41, v105
	v_mul_f32_e32 v110, s45, v110
	v_mul_f32_e32 v115, s49, v115
	v_lshlrev_b32_e32 v103, 16, v103
	v_lshlrev_b32_e32 v108, 16, v108
	v_lshlrev_b32_e32 v113, 16, v113
	v_lshlrev_b32_e32 v118, 16, v118
	v_fma_f32 v100, v6, v100, v7
	v_fma_f32 v105, v6, v105, v7
	v_fma_f32 v110, v6, v110, v7
	v_fma_f32 v115, v6, v115, v7
	v_fmac_f32_e32 v100, s73, v101
	v_fmac_f32_e32 v105, s26, v106
	v_fmac_f32_e32 v110, s27, v111
	v_fmac_f32_e32 v115, s32, v116
	v_mul_f32_e32 v100, v100, v103
	v_mul_f32_e32 v105, v105, v108
	v_mul_f32_e32 v110, v110, v113
	v_mul_f32_e32 v115, v115, v118
	v_cvt_pk_bf16_f32 v169, v100, v100
	v_cvt_pk_bf16_f32 v175, v105, v105
	v_cvt_pk_bf16_f32 v242, v110, v110
	v_cvt_pk_bf16_f32 v248, v115, v115
	global_store_short v2, v169, s[28:29]
	s_add_u32 s28, s28, 0x1000
	s_addc_u32 s29, s29, 0
	global_store_short v2, v175, s[28:29]
	s_add_u32 s28, s28, 0x1000
	s_addc_u32 s29, s29, 0
	global_store_short v2, v242, s[28:29]
	s_add_u32 s28, s28, 0x1000
	s_addc_u32 s29, s29, 0
	global_store_short v2, v248, s[28:29]
	s_add_u32 s28, s28, 0x1000
	s_addc_u32 s29, s29, 0
	s_waitcnt vmcnt(8)
	ds_write_b128 v12, v[120:123] offset:0
	ds_write_b128 v12, v[124:127] offset:1024
	ds_write_b128 v12, v[128:131] offset:16384
	ds_write_b128 v12, v[132:135] offset:17408
	ds_write_b128 v14, v[136:139]
	v_readlane_b32 s69, v159, 0
	v_readlane_b32 s70, v159, 1
	v_readlane_b32 s71, v159, 2
	v_readlane_b32 s72, v159, 3
	v_readlane_b32 s73, v159, 4
	v_readlane_b32 s26, v159, 5
	v_readlane_b32 s27, v159, 6
	v_readlane_b32 s32, v159, 7
	global_load_dwordx4 v[120:123], v11, s[6:7]
	global_load_dwordx4 v[124:127], v11, s[6:7] offset:1024
	global_load_dwordx4 v[128:131], v11, s[8:9]
	global_load_dwordx4 v[132:135], v11, s[8:9] offset:1024
	global_load_dwordx4 v[136:139], v11, s[10:11]
	global_load_dword v159, v158, s[12:13]
	s_add_u32 s6, s6, 0x10000
	s_addc_u32 s7, s7, 0
	s_add_u32 s8, s8, 0x10000
	s_addc_u32 s9, s9, 0
	s_add_u32 s10, s10, 0x8000
	s_addc_u32 s11, s11, 0
	s_add_u32 s12, s12, 0x400
	s_addc_u32 s13, s13, 0
	s_waitcnt lgkmcnt(0)
	s_barrier
; __device__ __forceinline__ void rw_post(Frame& F) {
;     ...
;             for (int q = 0; q < 8; ++q) { const int row = rb0 + t0 + q;
;                 const float mean = wsum(y[q]) * (1.f / 64.f); const float dv = y[q] - mean; const float var = wsum(dv * dv) * (1.f / 64.f);
;                 const float yn = dv * (1.f / sqrtf(var + 64e-5f)) * g_ + b_;
	ds_read_b32 v80, v154 offset:0
	ds_read_b32 v81, v154 offset:16384
	ds_read_u16 v83, v156 offset:0
	ds_read_b32 v85, v154 offset:2048
	ds_read_b32 v86, v154 offset:18432
	ds_read_u16 v88, v156 offset:1024
	ds_read_b32 v90, v154 offset:4096
	ds_read_b32 v91, v154 offset:20480
	ds_read_u16 v93, v156 offset:2048
	ds_read_b32 v95, v154 offset:6144
	ds_read_b32 v96, v154 offset:22528
	ds_read_u16 v98, v156 offset:3072
	ds_read_b32 v100, v154 offset:8192
	ds_read_b32 v101, v154 offset:24576
	ds_read_u16 v103, v156 offset:4096
	ds_read_b32 v105, v154 offset:10240
	ds_read_b32 v106, v154 offset:26624
	ds_read_u16 v108, v156 offset:5120
	ds_read_b32 v110, v154 offset:12288
	ds_read_b32 v111, v154 offset:28672
	ds_read_u16 v113, v156 offset:6144
	ds_read_b32 v115, v154 offset:14336
	ds_read_b32 v116, v154 offset:30720
	ds_read_u16 v118, v156 offset:7168
	s_waitcnt lgkmcnt(12)
	v_add_f32_e32 v80, v80, v24
	v_add_f32_e32 v85, v85, v25
	v_add_f32_e32 v90, v90, v26
	v_add_f32_e32 v95, v95, v27
	v_add_f32_dpp v168, v80, v80 quad_perm:[1,0,3,2] row_mask:0xf bank_mask:0xf bound_ctrl:1
	v_add_f32_dpp v174, v85, v85 quad_perm:[1,0,3,2] row_mask:0xf bank_mask:0xf bound_ctrl:1
	v_add_f32_dpp v241, v90, v90 quad_perm:[1,0,3,2] row_mask:0xf bank_mask:0xf bound_ctrl:1
	v_add_f32_dpp v247, v95, v95 quad_perm:[1,0,3,2] row_mask:0xf bank_mask:0xf bound_ctrl:1
	v_add_f32_dpp v168, v168, v168 quad_perm:[2,3,0,1] row_mask:0xf bank_mask:0xf bound_ctrl:1
	v_add_f32_dpp v174, v174, v174 quad_perm:[2,3,0,1] row_mask:0xf bank_mask:0xf bound_ctrl:1
	v_add_f32_dpp v241, v241, v241 quad_perm:[2,3,0,1] row_mask:0xf bank_mask:0xf bound_ctrl:1
	v_add_f32_dpp v247, v247, v247 quad_perm:[2,3,0,1] row_mask:0xf bank_mask:0xf bound_ctrl:1
	v_add_f32_dpp v168, v168, v168 row_half_mirror row_mask:0xf bank_mask:0xf bound_ctrl:1
	v_add_f32_dpp v174, v174, v174 row_half_mirror row_mask:0xf bank_mask:0xf bound_ctrl:1
	v_add_f32_dpp v241, v241, v241 row_half_mirror row_mask:0xf bank_mask:0xf bound_ctrl:1
	v_add_f32_dpp v247, v247, v247 row_half_mirror row_mask:0xf bank_mask:0xf bound_ctrl:1
	v_add_f32_dpp v168, v168, v168 row_mirror row_mask:0xf bank_mask:0xf bound_ctrl:1
	v_add_f32_dpp v174, v174, v174 row_mirror row_mask:0xf bank_mask:0xf bound_ctrl:1
	v_add_f32_dpp v241, v241, v241 row_mirror row_mask:0xf bank_mask:0xf bound_ctrl:1
	v_add_f32_dpp v247, v247, v247 row_mirror row_mask:0xf bank_mask:0xf bound_ctrl:1
	v_readlane_b32 s36, v168, 16
	v_readlane_b32 s40, v174, 16
	v_readlane_b32 s44, v241, 16
	v_readlane_b32 s48, v247, 16
	v_readlane_b32 s37, v168, 48
	v_readlane_b32 s41, v174, 48
	v_readlane_b32 s45, v241, 48
	v_readlane_b32 s49, v247, 48
	v_readlane_b32 s38, v168, 0
	v_readlane_b32 s42, v174, 0
	v_readlane_b32 s46, v241, 0
	v_readlane_b32 s50, v247, 0
	v_readlane_b32 s39, v168, 32
	v_readlane_b32 s43, v174, 32
	v_readlane_b32 s47, v241, 32
	v_readlane_b32 s51, v247, 32
	v_mov_b32_e32 v168, s36
	v_mov_b32_e32 v174, s40
	v_mov_b32_e32 v241, s44
	v_mov_b32_e32 v247, s48
	v_mov_b32_e32 v169, s37
	v_mov_b32_e32 v175, s41
	v_mov_b32_e32 v242, s45
	v_mov_b32_e32 v248, s49
	v_add_f32_e32 v168, s38, v168
	v_add_f32_e32 v174, s42, v174
	v_add_f32_e32 v241, s46, v241
	v_add_f32_e32 v247, s50, v247
	v_add_f32_e32 v169, s39, v169
	v_add_f32_e32 v175, s43, v175
	v_add_f32_e32 v242, s47, v242
	v_add_f32_e32 v248, s51, v248
	v_add_f32_e32 v168, v168, v169
	v_add_f32_e32 v174, v174, v175
	v_add_f32_e32 v241, v241, v242
	v_add_f32_e32 v247, v247, v248
	v_fmamk_f32 v80, v168, 0xbc800000, v80
	v_fmamk_f32 v85, v174, 0xbc800000, v85
	v_fmamk_f32 v90, v241, 0xbc800000, v90
	v_fmamk_f32 v95, v247, 0xbc800000, v95
	v_mul_f32_e32 v168, v80, v80
	v_mul_f32_e32 v174, v85, v85
	v_mul_f32_e32 v241, v90, v90
	v_mul_f32_e32 v247, v95, v95
	v_mov_b32_dpp v168, v168 quad_perm:[1,0,3,2] row_mask:0xf bank_mask:0xf bound_ctrl:1
	v_mov_b32_dpp v174, v174 quad_perm:[1,0,3,2] row_mask:0xf bank_mask:0xf bound_ctrl:1
	v_mov_b32_dpp v241, v241 quad_perm:[1,0,3,2] row_mask:0xf bank_mask:0xf bound_ctrl:1
	v_mov_b32_dpp v247, v247 quad_perm:[1,0,3,2] row_mask:0xf bank_mask:0xf bound_ctrl:1
	v_fmac_f32_e32 v168, v80, v80
	v_fmac_f32_e32 v174, v85, v85
	v_fmac_f32_e32 v241, v90, v90
	v_fmac_f32_e32 v247, v95, v95
	v_add_f32_dpp v168, v168, v168 quad_perm:[2,3,0,1] row_mask:0xf bank_mask:0xf bound_ctrl:1
	v_add_f32_dpp v174, v174, v174 quad_perm:[2,3,0,1] row_mask:0xf bank_mask:0xf bound_ctrl:1
	v_add_f32_dpp v241, v241, v241 quad_perm:[2,3,0,1] row_mask:0xf bank_mask:0xf bound_ctrl:1
	v_add_f32_dpp v247, v247, v247 quad_perm:[2,3,0,1] row_mask:0xf bank_mask:0xf bound_ctrl:1
	v_add_f32_dpp v168, v168, v168 row_half_mirror row_mask:0xf bank_mask:0xf bound_ctrl:1
	v_add_f32_dpp v174, v174, v174 row_half_mirror row_mask:0xf bank_mask:0xf bound_ctrl:1
	v_add_f32_dpp v241, v241, v241 row_half_mirror row_mask:0xf bank_mask:0xf bound_ctrl:1
	v_add_f32_dpp v247, v247, v247 row_half_mirror row_mask:0xf bank_mask:0xf bound_ctrl:1
	v_add_f32_dpp v168, v168, v168 row_mirror row_mask:0xf bank_mask:0xf bound_ctrl:1
	v_add_f32_dpp v174, v174, v174 row_mirror row_mask:0xf bank_mask:0xf bound_ctrl:1
	v_add_f32_dpp v241, v241, v241 row_mirror row_mask:0xf bank_mask:0xf bound_ctrl:1
	v_add_f32_dpp v247, v247, v247 row_mirror row_mask:0xf bank_mask:0xf bound_ctrl:1
	v_readlane_b32 s36, v168, 16
	v_readlane_b32 s40, v174, 16
	v_readlane_b32 s44, v241, 16
	v_readlane_b32 s48, v247, 16
	v_readlane_b32 s37, v168, 48
	v_readlane_b32 s41, v174, 48
	v_readlane_b32 s45, v241, 48
	v_readlane_b32 s49, v247, 48
	v_readlane_b32 s38, v168, 0
	v_readlane_b32 s42, v174, 0
	v_readlane_b32 s46, v241, 0
	v_readlane_b32 s50, v247, 0
	v_readlane_b32 s39, v168, 32
; __device__ __forceinline__ float bf2f(bf16 x) { return __uint_as_float(((unsigned)x) << 16); }
; __device__ __forceinline__ unsigned f2bf(float f) { return cvt_pk_bf16(f, 0.f) & 0xffffu; }
; __device__ __forceinline__ void rw_post(Frame& F) {
;     ...
;             for (int q = 0; q < 8; ++q) { const int row = rb0 + t0 + q;
;                 const float mean = wsum(y[q]) * (1.f / 64.f); const float dv = y[q] - mean; const float var = wsum(dv * dv) * (1.f / 64.f);
;                 const float yn = dv * (1.f / sqrtf(var + 64e-5f)) * g_ + b_;
;                 OB[(size_t)row * DH + col] = (bf16)f2bf((yn + rk[q] * vv[q]) * bf2f(gg[q])); }
	v_readlane_b32 s43, v174, 32
	v_readlane_b32 s47, v241, 32
	v_readlane_b32 s51, v247, 32
	v_mov_b32_e32 v168, s36
	v_mov_b32_e32 v174, s40
	v_mov_b32_e32 v241, s44
	v_mov_b32_e32 v247, s48
	v_mov_b32_e32 v169, s37
	v_mov_b32_e32 v175, s41
	v_mov_b32_e32 v242, s45
	v_mov_b32_e32 v248, s49
	v_add_f32_e32 v168, s38, v168
	v_add_f32_e32 v174, s42, v174
	v_add_f32_e32 v241, s46, v241
	v_add_f32_e32 v247, s50, v247
	v_add_f32_e32 v169, s39, v169
	v_add_f32_e32 v175, s43, v175
	v_add_f32_e32 v242, s47, v242
	v_add_f32_e32 v248, s51, v248
	v_add_f32_e32 v168, v168, v169
	v_add_f32_e32 v174, v174, v175
	v_add_f32_e32 v241, v241, v242
	v_add_f32_e32 v247, v247, v248
	v_fmamk_f32 v168, v168, 0x3c800000, v9
	v_fmamk_f32 v174, v174, 0x3c800000, v9
	v_fmamk_f32 v241, v241, 0x3c800000, v9
	v_fmamk_f32 v247, v247, 0x3c800000, v9
	v_readfirstlane_b32 s40, v174
	v_readfirstlane_b32 s44, v241
	v_readfirstlane_b32 s48, v247
	v_writelane_b32 v168, s40, 1
	v_writelane_b32 v168, s44, 2
	v_writelane_b32 v168, s48, 3
	v_mul_f32_e32 v169, 0x4f800000, v168
	v_cmp_gt_f32_e64 s[52:53], s68, v168
	v_mov_b32_e32 v170, v168
	s_nop 1
	v_cndmask_b32_e64 v168, v170, v169, s[52:53]
	v_sqrt_f32_e32 v169, v168
	s_nop 0
	v_add_u32_e32 v170, -1, v169
	v_fma_f32 v171, -v170, v169, v168
	v_cmp_ge_f32_e64 s[60:61], 0, v171
	v_add_u32_e32 v171, 1, v169
	s_nop 1
	v_cndmask_b32_e64 v170, v169, v170, s[60:61]
	v_fma_f32 v169, -v171, v169, v168
	v_cmp_lt_f32_e64 s[60:61], 0, v169
	s_nop 1
	v_cndmask_b32_e64 v169, v170, v171, s[60:61]
	v_mul_f32_e32 v170, 0x37800000, v169
	v_cndmask_b32_e64 v169, v169, v170, s[52:53]
	v_cmp_class_f32_e64 s[60:61], v168, v8
	s_nop 1
	v_cndmask_b32_e64 v168, v169, v168, s[60:61]
	v_div_scale_f32 v169, s[60:61], v168, v168, 1.0
	v_rcp_f32_e32 v170, v169
	s_nop 0
	v_fma_f32 v171, -v169, v170, 1.0
	v_fmac_f32_e32 v170, v171, v170
	v_div_scale_f32 v171, vcc, 1.0, v168, 1.0
	v_mul_f32_e32 v172, v171, v170
	v_fma_f32 v173, -v169, v172, v171
	v_fmac_f32_e32 v172, v173, v170
	v_fma_f32 v169, -v169, v172, v171
	v_div_fmas_f32 v169, v169, v170, v172
	v_div_fixup_f32 v168, v169, v168, 1.0
	s_nop 0
	v_readlane_b32 s37, v168, 0
	v_readlane_b32 s41, v168, 1
	v_readlane_b32 s45, v168, 2
	v_readlane_b32 s49, v168, 3
	v_mul_f32_e32 v80, s37, v80
	v_mul_f32_e32 v85, s41, v85
	v_mul_f32_e32 v90, s45, v90
	v_mul_f32_e32 v95, s49, v95
	v_lshlrev_b32_e32 v83, 16, v83
	v_lshlrev_b32_e32 v88, 16, v88
	v_lshlrev_b32_e32 v93, 16, v93
	v_lshlrev_b32_e32 v98, 16, v98
	v_fma_f32 v80, v6, v80, v7
	v_fma_f32 v85, v6, v85, v7
	v_fma_f32 v90, v6, v90, v7
	v_fma_f32 v95, v6, v95, v7
	v_fmac_f32_e32 v80, s69, v81
	v_fmac_f32_e32 v85, s70, v86
	v_fmac_f32_e32 v90, s71, v91
	v_fmac_f32_e32 v95, s72, v96
	v_mul_f32_e32 v80, v80, v83
	v_mul_f32_e32 v85, v85, v88
	v_mul_f32_e32 v90, v90, v93
	v_mul_f32_e32 v95, v95, v98
	v_cvt_pk_bf16_f32 v169, v80, v80
	v_cvt_pk_bf16_f32 v175, v85, v85
	v_cvt_pk_bf16_f32 v242, v90, v90
	v_cvt_pk_bf16_f32 v248, v95, v95
	global_store_short v2, v169, s[28:29]
	s_add_u32 s28, s28, 0x1000
	s_addc_u32 s29, s29, 0
	global_store_short v2, v175, s[28:29]
	s_add_u32 s28, s28, 0x1000
	s_addc_u32 s29, s29, 0
	global_store_short v2, v242, s[28:29]
	s_add_u32 s28, s28, 0x1000
	s_addc_u32 s29, s29, 0
	global_store_short v2, v248, s[28:29]
	s_add_u32 s28, s28, 0x1000
	s_addc_u32 s29, s29, 0
	s_waitcnt lgkmcnt(0)
	v_add_f32_e32 v100, v100, v40
	v_add_f32_e32 v105, v105, v41
	v_add_f32_e32 v110, v110, v42
	v_add_f32_e32 v115, v115, v43
	v_add_f32_dpp v168, v100, v100 quad_perm:[1,0,3,2] row_mask:0xf bank_mask:0xf bound_ctrl:1
	v_add_f32_dpp v174, v105, v105 quad_perm:[1,0,3,2] row_mask:0xf bank_mask:0xf bound_ctrl:1
	v_add_f32_dpp v241, v110, v110 quad_perm:[1,0,3,2] row_mask:0xf bank_mask:0xf bound_ctrl:1
	v_add_f32_dpp v247, v115, v115 quad_perm:[1,0,3,2] row_mask:0xf bank_mask:0xf bound_ctrl:1
	v_add_f32_dpp v168, v168, v168 quad_perm:[2,3,0,1] row_mask:0xf bank_mask:0xf bound_ctrl:1
	v_add_f32_dpp v174, v174, v174 quad_perm:[2,3,0,1] row_mask:0xf bank_mask:0xf bound_ctrl:1
	v_add_f32_dpp v241, v241, v241 quad_perm:[2,3,0,1] row_mask:0xf bank_mask:0xf bound_ctrl:1
	v_add_f32_dpp v247, v247, v247 quad_perm:[2,3,0,1] row_mask:0xf bank_mask:0xf bound_ctrl:1
	v_add_f32_dpp v168, v168, v168 row_half_mirror row_mask:0xf bank_mask:0xf bound_ctrl:1
	v_add_f32_dpp v174, v174, v174 row_half_mirror row_mask:0xf bank_mask:0xf bound_ctrl:1
	v_add_f32_dpp v241, v241, v241 row_half_mirror row_mask:0xf bank_mask:0xf bound_ctrl:1
	v_add_f32_dpp v247, v247, v247 row_half_mirror row_mask:0xf bank_mask:0xf bound_ctrl:1
	v_add_f32_dpp v168, v168, v168 row_mirror row_mask:0xf bank_mask:0xf bound_ctrl:1
	v_add_f32_dpp v174, v174, v174 row_mirror row_mask:0xf bank_mask:0xf bound_ctrl:1
	v_add_f32_dpp v241, v241, v241 row_mirror row_mask:0xf bank_mask:0xf bound_ctrl:1
	v_add_f32_dpp v247, v247, v247 row_mirror row_mask:0xf bank_mask:0xf bound_ctrl:1
	v_readlane_b32 s36, v168, 16
	v_readlane_b32 s40, v174, 16
	v_readlane_b32 s44, v241, 16
	v_readlane_b32 s48, v247, 16
	v_readlane_b32 s37, v168, 48
	v_readlane_b32 s41, v174, 48
	v_readlane_b32 s45, v241, 48
	v_readlane_b32 s49, v247, 48
	v_readlane_b32 s38, v168, 0
	v_readlane_b32 s42, v174, 0
	v_readlane_b32 s46, v241, 0
	v_readlane_b32 s50, v247, 0
	v_readlane_b32 s39, v168, 32
	v_readlane_b32 s43, v174, 32
	v_readlane_b32 s47, v241, 32
	v_readlane_b32 s51, v247, 32
	v_mov_b32_e32 v168, s36
	v_mov_b32_e32 v174, s40
	v_mov_b32_e32 v241, s44
	v_mov_b32_e32 v247, s48
	v_mov_b32_e32 v169, s37
	v_mov_b32_e32 v175, s41
	v_mov_b32_e32 v242, s45
	v_mov_b32_e32 v248, s49
	v_add_f32_e32 v168, s38, v168
	v_add_f32_e32 v174, s42, v174
	v_add_f32_e32 v241, s46, v241
; __device__ __forceinline__ float bf2f(bf16 x) { return __uint_as_float(((unsigned)x) << 16); }
; __device__ __forceinline__ unsigned f2bf(float f) { return cvt_pk_bf16(f, 0.f) & 0xffffu; }
; #define POST_LD(Y_, V_, G_, R_, C_, t) do { _Pragma("unroll") for (int q = 0; q < 8; ++q) { const size_t o_ = (size_t)((t) + q) * DH; Y_[q] = yp[o_]; V_[q] = vp[o_]; G_[q] = gp[o_]; R_[q] = rp[((t) + q) * 32]; C_[q] = cp[o_]; } } while (0)
; __device__ __forceinline__ void rw_post(Frame& F) {
;     ...
;         POST_LD(y, vv, gg, rk, cc, 0);
;         for (int t0 = 0; t0 < 64; t0 += 8) {
;             float ny[8], nv[8], nr[8], nc[8]; bf16 ng[8];
;             const int tn = t0 + 8 < 64 ? t0 + 8 : t0;
;             POST_LD(ny, nv, ng, nr, nc, tn);
;     ...
;             for (int q = 0; q < 8; ++q) { const int row = rb0 + t0 + q;
;                 const float mean = wsum(y[q]) * (1.f / 64.f); const float dv = y[q] - mean; const float var = wsum(dv * dv) * (1.f / 64.f);
;                 const float yn = dv * (1.f / sqrtf(var + 64e-5f)) * g_ + b_;
;                 OB[(size_t)row * DH + col] = (bf16)f2bf((yn + rk[q] * vv[q]) * bf2f(gg[q])); }
	v_add_f32_e32 v247, s50, v247
	v_add_f32_e32 v169, s39, v169
	v_add_f32_e32 v175, s43, v175
	v_add_f32_e32 v242, s47, v242
	v_add_f32_e32 v248, s51, v248
	v_add_f32_e32 v168, v168, v169
	v_add_f32_e32 v174, v174, v175
	v_add_f32_e32 v241, v241, v242
	v_add_f32_e32 v247, v247, v248
	v_fmamk_f32 v100, v168, 0xbc800000, v100
	v_fmamk_f32 v105, v174, 0xbc800000, v105
	v_fmamk_f32 v110, v241, 0xbc800000, v110
	v_fmamk_f32 v115, v247, 0xbc800000, v115
	v_mul_f32_e32 v168, v100, v100
	v_mul_f32_e32 v174, v105, v105
	v_mul_f32_e32 v241, v110, v110
	v_mul_f32_e32 v247, v115, v115
	v_mov_b32_dpp v168, v168 quad_perm:[1,0,3,2] row_mask:0xf bank_mask:0xf bound_ctrl:1
	v_mov_b32_dpp v174, v174 quad_perm:[1,0,3,2] row_mask:0xf bank_mask:0xf bound_ctrl:1
	v_mov_b32_dpp v241, v241 quad_perm:[1,0,3,2] row_mask:0xf bank_mask:0xf bound_ctrl:1
	v_mov_b32_dpp v247, v247 quad_perm:[1,0,3,2] row_mask:0xf bank_mask:0xf bound_ctrl:1
	v_fmac_f32_e32 v168, v100, v100
	v_fmac_f32_e32 v174, v105, v105
	v_fmac_f32_e32 v241, v110, v110
	v_fmac_f32_e32 v247, v115, v115
	v_add_f32_dpp v168, v168, v168 quad_perm:[2,3,0,1] row_mask:0xf bank_mask:0xf bound_ctrl:1
	v_add_f32_dpp v174, v174, v174 quad_perm:[2,3,0,1] row_mask:0xf bank_mask:0xf bound_ctrl:1
	v_add_f32_dpp v241, v241, v241 quad_perm:[2,3,0,1] row_mask:0xf bank_mask:0xf bound_ctrl:1
	v_add_f32_dpp v247, v247, v247 quad_perm:[2,3,0,1] row_mask:0xf bank_mask:0xf bound_ctrl:1
	v_add_f32_dpp v168, v168, v168 row_half_mirror row_mask:0xf bank_mask:0xf bound_ctrl:1
	v_add_f32_dpp v174, v174, v174 row_half_mirror row_mask:0xf bank_mask:0xf bound_ctrl:1
	v_add_f32_dpp v241, v241, v241 row_half_mirror row_mask:0xf bank_mask:0xf bound_ctrl:1
	v_add_f32_dpp v247, v247, v247 row_half_mirror row_mask:0xf bank_mask:0xf bound_ctrl:1
	v_add_f32_dpp v168, v168, v168 row_mirror row_mask:0xf bank_mask:0xf bound_ctrl:1
	v_add_f32_dpp v174, v174, v174 row_mirror row_mask:0xf bank_mask:0xf bound_ctrl:1
	v_add_f32_dpp v241, v241, v241 row_mirror row_mask:0xf bank_mask:0xf bound_ctrl:1
	v_add_f32_dpp v247, v247, v247 row_mirror row_mask:0xf bank_mask:0xf bound_ctrl:1
	v_readlane_b32 s36, v168, 16
	v_readlane_b32 s40, v174, 16
	v_readlane_b32 s44, v241, 16
	v_readlane_b32 s48, v247, 16
	v_readlane_b32 s37, v168, 48
	v_readlane_b32 s41, v174, 48
	v_readlane_b32 s45, v241, 48
	v_readlane_b32 s49, v247, 48
	v_readlane_b32 s38, v168, 0
	v_readlane_b32 s42, v174, 0
	v_readlane_b32 s46, v241, 0
	v_readlane_b32 s50, v247, 0
	v_readlane_b32 s39, v168, 32
	v_readlane_b32 s43, v174, 32
	v_readlane_b32 s47, v241, 32
	v_readlane_b32 s51, v247, 32
	v_mov_b32_e32 v168, s36
	v_mov_b32_e32 v174, s40
	v_mov_b32_e32 v241, s44
	v_mov_b32_e32 v247, s48
	v_mov_b32_e32 v169, s37
	v_mov_b32_e32 v175, s41
	v_mov_b32_e32 v242, s45
	v_mov_b32_e32 v248, s49
	v_add_f32_e32 v168, s38, v168
	v_add_f32_e32 v174, s42, v174
	v_add_f32_e32 v241, s46, v241
	v_add_f32_e32 v247, s50, v247
	v_add_f32_e32 v169, s39, v169
	v_add_f32_e32 v175, s43, v175
	v_add_f32_e32 v242, s47, v242
	v_add_f32_e32 v248, s51, v248
	v_add_f32_e32 v168, v168, v169
	v_add_f32_e32 v174, v174, v175
	v_add_f32_e32 v241, v241, v242
	v_add_f32_e32 v247, v247, v248
	v_fmamk_f32 v168, v168, 0x3c800000, v9
	v_fmamk_f32 v174, v174, 0x3c800000, v9
	v_fmamk_f32 v241, v241, 0x3c800000, v9
	v_fmamk_f32 v247, v247, 0x3c800000, v9
	v_readfirstlane_b32 s40, v174
	v_readfirstlane_b32 s44, v241
	v_readfirstlane_b32 s48, v247
	v_writelane_b32 v168, s40, 1
	v_writelane_b32 v168, s44, 2
	v_writelane_b32 v168, s48, 3
	v_mul_f32_e32 v169, 0x4f800000, v168
	v_cmp_gt_f32_e64 s[52:53], s68, v168
	v_mov_b32_e32 v170, v168
	s_nop 1
	v_cndmask_b32_e64 v168, v170, v169, s[52:53]
	v_sqrt_f32_e32 v169, v168
	s_nop 0
	v_add_u32_e32 v170, -1, v169
	v_fma_f32 v171, -v170, v169, v168
	v_cmp_ge_f32_e64 s[60:61], 0, v171
	v_add_u32_e32 v171, 1, v169
	s_nop 1
	v_cndmask_b32_e64 v170, v169, v170, s[60:61]
	v_fma_f32 v169, -v171, v169, v168
	v_cmp_lt_f32_e64 s[60:61], 0, v169
	s_nop 1
	v_cndmask_b32_e64 v169, v170, v171, s[60:61]
	v_mul_f32_e32 v170, 0x37800000, v169
	v_cndmask_b32_e64 v169, v169, v170, s[52:53]
	v_cmp_class_f32_e64 s[60:61], v168, v8
	s_nop 1
	v_cndmask_b32_e64 v168, v169, v168, s[60:61]
	v_div_scale_f32 v169, s[60:61], v168, v168, 1.0
	v_rcp_f32_e32 v170, v169
	s_nop 0
	v_fma_f32 v171, -v169, v170, 1.0
	v_fmac_f32_e32 v170, v171, v170
	v_div_scale_f32 v171, vcc, 1.0, v168, 1.0
	v_mul_f32_e32 v172, v171, v170
	v_fma_f32 v173, -v169, v172, v171
	v_fmac_f32_e32 v172, v173, v170
	v_fma_f32 v169, -v169, v172, v171
	v_div_fmas_f32 v169, v169, v170, v172
	v_div_fixup_f32 v168, v169, v168, 1.0
	s_nop 0
	v_readlane_b32 s37, v168, 0
	v_readlane_b32 s41, v168, 1
	v_readlane_b32 s45, v168, 2
	v_readlane_b32 s49, v168, 3
	v_mul_f32_e32 v100, s37, v100
	v_mul_f32_e32 v105, s41, v105
	v_mul_f32_e32 v110, s45, v110
	v_mul_f32_e32 v115, s49, v115
	v_lshlrev_b32_e32 v103, 16, v103
	v_lshlrev_b32_e32 v108, 16, v108
	v_lshlrev_b32_e32 v113, 16, v113
	v_lshlrev_b32_e32 v118, 16, v118
	v_fma_f32 v100, v6, v100, v7
	v_fma_f32 v105, v6, v105, v7
	v_fma_f32 v110, v6, v110, v7
	v_fma_f32 v115, v6, v115, v7
	v_fmac_f32_e32 v100, s73, v101
	v_fmac_f32_e32 v105, s26, v106
	v_fmac_f32_e32 v110, s27, v111
	v_fmac_f32_e32 v115, s32, v116
	v_mul_f32_e32 v100, v100, v103
	v_mul_f32_e32 v105, v105, v108
	v_mul_f32_e32 v110, v110, v113
	v_mul_f32_e32 v115, v115, v118
	v_cvt_pk_bf16_f32 v169, v100, v100
	v_cvt_pk_bf16_f32 v175, v105, v105
	v_cvt_pk_bf16_f32 v242, v110, v110
	v_cvt_pk_bf16_f32 v248, v115, v115
	global_store_short v2, v169, s[28:29]
	s_add_u32 s28, s28, 0x1000
	s_addc_u32 s29, s29, 0
	global_store_short v2, v175, s[28:29]
	s_add_u32 s28, s28, 0x1000
	s_addc_u32 s29, s29, 0
	global_store_short v2, v242, s[28:29]
	s_add_u32 s28, s28, 0x1000
	s_addc_u32 s29, s29, 0
	global_store_short v2, v248, s[28:29]
	s_add_u32 s28, s28, 0x1000
	s_addc_u32 s29, s29, 0
	s_waitcnt vmcnt(8)
	ds_write_b128 v13, v[120:123] offset:0
	ds_write_b128 v13, v[124:127] offset:1024
	ds_write_b128 v13, v[128:131] offset:16384
	ds_write_b128 v13, v[132:135] offset:17408
	ds_write_b128 v15, v[136:139]
	v_readlane_b32 s69, v159, 0
	v_readlane_b32 s70, v159, 1
	v_readlane_b32 s71, v159, 2
	v_readlane_b32 s72, v159, 3
	v_readlane_b32 s73, v159, 4
	v_readlane_b32 s26, v159, 5
	v_readlane_b32 s27, v159, 6
	v_readlane_b32 s32, v159, 7
	global_load_dwordx4 v[120:123], v11, s[6:7]
	global_load_dwordx4 v[124:127], v11, s[6:7] offset:1024
	global_load_dwordx4 v[128:131], v11, s[8:9]
	global_load_dwordx4 v[132:135], v11, s[8:9] offset:1024
	global_load_dwordx4 v[136:139], v11, s[10:11]
	global_load_dword v159, v158, s[12:13]
	s_add_u32 s6, s6, 0x10000
	s_addc_u32 s7, s7, 0
	s_add_u32 s8, s8, 0x10000
	s_addc_u32 s9, s9, 0
	s_add_u32 s10, s10, 0x8000
	s_addc_u32 s11, s11, 0
	s_add_u32 s12, s12, 0x400
	s_addc_u32 s13, s13, 0
	s_waitcnt lgkmcnt(0)
	s_barrier
; __device__ __forceinline__ float bf2f(bf16 x) { return __uint_as_float(((unsigned)x) << 16); }
; __device__ __forceinline__ unsigned f2bf(float f) { return cvt_pk_bf16(f, 0.f) & 0xffffu; }
; __device__ __forceinline__ void rw_post(Frame& F) {
;     ...
;             for (int q = 0; q < 8; ++q) { const int row = rb0 + t0 + q;
;                 const float mean = wsum(y[q]) * (1.f / 64.f); const float dv = y[q] - mean; const float var = wsum(dv * dv) * (1.f / 64.f);
;                 const float yn = dv * (1.f / sqrtf(var + 64e-5f)) * g_ + b_;
;                 OB[(size_t)row * DH + col] = (bf16)f2bf((yn + rk[q] * vv[q]) * bf2f(gg[q])); }
	ds_read_b32 v80, v155 offset:0
	ds_read_b32 v81, v155 offset:16384
	ds_read_u16 v83, v157 offset:0
	ds_read_b32 v85, v155 offset:2048
	ds_read_b32 v86, v155 offset:18432
	ds_read_u16 v88, v157 offset:1024
	ds_read_b32 v90, v155 offset:4096
	ds_read_b32 v91, v155 offset:20480
	ds_read_u16 v93, v157 offset:2048
	ds_read_b32 v95, v155 offset:6144
	ds_read_b32 v96, v155 offset:22528
	ds_read_u16 v98, v157 offset:3072
	ds_read_b32 v100, v155 offset:8192
	ds_read_b32 v101, v155 offset:24576
	ds_read_u16 v103, v157 offset:4096
	ds_read_b32 v105, v155 offset:10240
	ds_read_b32 v106, v155 offset:26624
	ds_read_u16 v108, v157 offset:5120
	ds_read_b32 v110, v155 offset:12288
	ds_read_b32 v111, v155 offset:28672
	ds_read_u16 v113, v157 offset:6144
	ds_read_b32 v115, v155 offset:14336
	ds_read_b32 v116, v155 offset:30720
	ds_read_u16 v118, v157 offset:7168
	s_waitcnt lgkmcnt(12)
	v_add_f32_e32 v80, v80, v28
	v_add_f32_e32 v85, v85, v29
	v_add_f32_e32 v90, v90, v30
	v_add_f32_e32 v95, v95, v31
	v_add_f32_dpp v168, v80, v80 quad_perm:[1,0,3,2] row_mask:0xf bank_mask:0xf bound_ctrl:1
	v_add_f32_dpp v174, v85, v85 quad_perm:[1,0,3,2] row_mask:0xf bank_mask:0xf bound_ctrl:1
	v_add_f32_dpp v241, v90, v90 quad_perm:[1,0,3,2] row_mask:0xf bank_mask:0xf bound_ctrl:1
	v_add_f32_dpp v247, v95, v95 quad_perm:[1,0,3,2] row_mask:0xf bank_mask:0xf bound_ctrl:1
	v_add_f32_dpp v168, v168, v168 quad_perm:[2,3,0,1] row_mask:0xf bank_mask:0xf bound_ctrl:1
	v_add_f32_dpp v174, v174, v174 quad_perm:[2,3,0,1] row_mask:0xf bank_mask:0xf bound_ctrl:1
	v_add_f32_dpp v241, v241, v241 quad_perm:[2,3,0,1] row_mask:0xf bank_mask:0xf bound_ctrl:1
	v_add_f32_dpp v247, v247, v247 quad_perm:[2,3,0,1] row_mask:0xf bank_mask:0xf bound_ctrl:1
	v_add_f32_dpp v168, v168, v168 row_half_mirror row_mask:0xf bank_mask:0xf bound_ctrl:1
	v_add_f32_dpp v174, v174, v174 row_half_mirror row_mask:0xf bank_mask:0xf bound_ctrl:1
	v_add_f32_dpp v241, v241, v241 row_half_mirror row_mask:0xf bank_mask:0xf bound_ctrl:1
	v_add_f32_dpp v247, v247, v247 row_half_mirror row_mask:0xf bank_mask:0xf bound_ctrl:1
	v_add_f32_dpp v168, v168, v168 row_mirror row_mask:0xf bank_mask:0xf bound_ctrl:1
	v_add_f32_dpp v174, v174, v174 row_mirror row_mask:0xf bank_mask:0xf bound_ctrl:1
	v_add_f32_dpp v241, v241, v241 row_mirror row_mask:0xf bank_mask:0xf bound_ctrl:1
	v_add_f32_dpp v247, v247, v247 row_mirror row_mask:0xf bank_mask:0xf bound_ctrl:1
	v_readlane_b32 s36, v168, 16
	v_readlane_b32 s40, v174, 16
	v_readlane_b32 s44, v241, 16
	v_readlane_b32 s48, v247, 16
	v_readlane_b32 s37, v168, 48
	v_readlane_b32 s41, v174, 48
	v_readlane_b32 s45, v241, 48
	v_readlane_b32 s49, v247, 48
	v_readlane_b32 s38, v168, 0
	v_readlane_b32 s42, v174, 0
	v_readlane_b32 s46, v241, 0
	v_readlane_b32 s50, v247, 0
	v_readlane_b32 s39, v168, 32
	v_readlane_b32 s43, v174, 32
	v_readlane_b32 s47, v241, 32
	v_readlane_b32 s51, v247, 32
	v_mov_b32_e32 v168, s36
	v_mov_b32_e32 v174, s40
	v_mov_b32_e32 v241, s44
	v_mov_b32_e32 v247, s48
	v_mov_b32_e32 v169, s37
	v_mov_b32_e32 v175, s41
	v_mov_b32_e32 v242, s45
	v_mov_b32_e32 v248, s49
	v_add_f32_e32 v168, s38, v168
	v_add_f32_e32 v174, s42, v174
	v_add_f32_e32 v241, s46, v241
	v_add_f32_e32 v247, s50, v247
	v_add_f32_e32 v169, s39, v169
	v_add_f32_e32 v175, s43, v175
	v_add_f32_e32 v242, s47, v242
	v_add_f32_e32 v248, s51, v248
	v_add_f32_e32 v168, v168, v169
	v_add_f32_e32 v174, v174, v175
	v_add_f32_e32 v241, v241, v242
	v_add_f32_e32 v247, v247, v248
	v_fmamk_f32 v80, v168, 0xbc800000, v80
	v_fmamk_f32 v85, v174, 0xbc800000, v85
	v_fmamk_f32 v90, v241, 0xbc800000, v90
	v_fmamk_f32 v95, v247, 0xbc800000, v95
	v_mul_f32_e32 v168, v80, v80
	v_mul_f32_e32 v174, v85, v85
	v_mul_f32_e32 v241, v90, v90
	v_mul_f32_e32 v247, v95, v95
	v_mov_b32_dpp v168, v168 quad_perm:[1,0,3,2] row_mask:0xf bank_mask:0xf bound_ctrl:1
	v_mov_b32_dpp v174, v174 quad_perm:[1,0,3,2] row_mask:0xf bank_mask:0xf bound_ctrl:1
	v_mov_b32_dpp v241, v241 quad_perm:[1,0,3,2] row_mask:0xf bank_mask:0xf bound_ctrl:1
	v_mov_b32_dpp v247, v247 quad_perm:[1,0,3,2] row_mask:0xf bank_mask:0xf bound_ctrl:1
	v_fmac_f32_e32 v168, v80, v80
	v_fmac_f32_e32 v174, v85, v85
	v_fmac_f32_e32 v241, v90, v90
	v_fmac_f32_e32 v247, v95, v95
	v_add_f32_dpp v168, v168, v168 quad_perm:[2,3,0,1] row_mask:0xf bank_mask:0xf bound_ctrl:1
	v_add_f32_dpp v174, v174, v174 quad_perm:[2,3,0,1] row_mask:0xf bank_mask:0xf bound_ctrl:1
	v_add_f32_dpp v241, v241, v241 quad_perm:[2,3,0,1] row_mask:0xf bank_mask:0xf bound_ctrl:1
	v_add_f32_dpp v247, v247, v247 quad_perm:[2,3,0,1] row_mask:0xf bank_mask:0xf bound_ctrl:1
	v_add_f32_dpp v168, v168, v168 row_half_mirror row_mask:0xf bank_mask:0xf bound_ctrl:1
	v_add_f32_dpp v174, v174, v174 row_half_mirror row_mask:0xf bank_mask:0xf bound_ctrl:1
	v_add_f32_dpp v241, v241, v241 row_half_mirror row_mask:0xf bank_mask:0xf bound_ctrl:1
	v_add_f32_dpp v247, v247, v247 row_half_mirror row_mask:0xf bank_mask:0xf bound_ctrl:1
	v_add_f32_dpp v168, v168, v168 row_mirror row_mask:0xf bank_mask:0xf bound_ctrl:1
	v_add_f32_dpp v174, v174, v174 row_mirror row_mask:0xf bank_mask:0xf bound_ctrl:1
	v_add_f32_dpp v241, v241, v241 row_mirror row_mask:0xf bank_mask:0xf bound_ctrl:1
	v_add_f32_dpp v247, v247, v247 row_mirror row_mask:0xf bank_mask:0xf bound_ctrl:1
	v_readlane_b32 s36, v168, 16
	v_readlane_b32 s40, v174, 16
	v_readlane_b32 s44, v241, 16
	v_readlane_b32 s48, v247, 16
	v_readlane_b32 s37, v168, 48
	v_readlane_b32 s41, v174, 48
	v_readlane_b32 s45, v241, 48
	v_readlane_b32 s49, v247, 48
	v_readlane_b32 s38, v168, 0
	v_readlane_b32 s42, v174, 0
	v_readlane_b32 s46, v241, 0
	v_readlane_b32 s50, v247, 0
	v_readlane_b32 s39, v168, 32
; __device__ __forceinline__ float bf2f(bf16 x) { return __uint_as_float(((unsigned)x) << 16); }
; __device__ __forceinline__ unsigned f2bf(float f) { return cvt_pk_bf16(f, 0.f) & 0xffffu; }
; __device__ __forceinline__ void rw_post(Frame& F) {
;     ...
;             for (int q = 0; q < 8; ++q) { const int row = rb0 + t0 + q;
;                 const float mean = wsum(y[q]) * (1.f / 64.f); const float dv = y[q] - mean; const float var = wsum(dv * dv) * (1.f / 64.f);
;                 const float yn = dv * (1.f / sqrtf(var + 64e-5f)) * g_ + b_;
;                 OB[(size_t)row * DH + col] = (bf16)f2bf((yn + rk[q] * vv[q]) * bf2f(gg[q])); }
	v_readlane_b32 s43, v174, 32
	v_readlane_b32 s47, v241, 32
	v_readlane_b32 s51, v247, 32
	v_mov_b32_e32 v168, s36
	v_mov_b32_e32 v174, s40
	v_mov_b32_e32 v241, s44
	v_mov_b32_e32 v247, s48
	v_mov_b32_e32 v169, s37
	v_mov_b32_e32 v175, s41
	v_mov_b32_e32 v242, s45
	v_mov_b32_e32 v248, s49
	v_add_f32_e32 v168, s38, v168
	v_add_f32_e32 v174, s42, v174
	v_add_f32_e32 v241, s46, v241
	v_add_f32_e32 v247, s50, v247
	v_add_f32_e32 v169, s39, v169
	v_add_f32_e32 v175, s43, v175
	v_add_f32_e32 v242, s47, v242
	v_add_f32_e32 v248, s51, v248
	v_add_f32_e32 v168, v168, v169
	v_add_f32_e32 v174, v174, v175
	v_add_f32_e32 v241, v241, v242
	v_add_f32_e32 v247, v247, v248
	v_fmamk_f32 v168, v168, 0x3c800000, v9
	v_fmamk_f32 v174, v174, 0x3c800000, v9
	v_fmamk_f32 v241, v241, 0x3c800000, v9
	v_fmamk_f32 v247, v247, 0x3c800000, v9
	v_readfirstlane_b32 s40, v174
	v_readfirstlane_b32 s44, v241
	v_readfirstlane_b32 s48, v247
	v_writelane_b32 v168, s40, 1
	v_writelane_b32 v168, s44, 2
	v_writelane_b32 v168, s48, 3
	v_mul_f32_e32 v169, 0x4f800000, v168
	v_cmp_gt_f32_e64 s[52:53], s68, v168
	v_mov_b32_e32 v170, v168
	s_nop 1
	v_cndmask_b32_e64 v168, v170, v169, s[52:53]
	v_sqrt_f32_e32 v169, v168
	s_nop 0
	v_add_u32_e32 v170, -1, v169
	v_fma_f32 v171, -v170, v169, v168
	v_cmp_ge_f32_e64 s[60:61], 0, v171
	v_add_u32_e32 v171, 1, v169
	s_nop 1
	v_cndmask_b32_e64 v170, v169, v170, s[60:61]
	v_fma_f32 v169, -v171, v169, v168
	v_cmp_lt_f32_e64 s[60:61], 0, v169
	s_nop 1
	v_cndmask_b32_e64 v169, v170, v171, s[60:61]
	v_mul_f32_e32 v170, 0x37800000, v169
	v_cndmask_b32_e64 v169, v169, v170, s[52:53]
	v_cmp_class_f32_e64 s[60:61], v168, v8
	s_nop 1
	v_cndmask_b32_e64 v168, v169, v168, s[60:61]
	v_div_scale_f32 v169, s[60:61], v168, v168, 1.0
	v_rcp_f32_e32 v170, v169
	s_nop 0
	v_fma_f32 v171, -v169, v170, 1.0
	v_fmac_f32_e32 v170, v171, v170
	v_div_scale_f32 v171, vcc, 1.0, v168, 1.0
	v_mul_f32_e32 v172, v171, v170
	v_fma_f32 v173, -v169, v172, v171
	v_fmac_f32_e32 v172, v173, v170
	v_fma_f32 v169, -v169, v172, v171
	v_div_fmas_f32 v169, v169, v170, v172
	v_div_fixup_f32 v168, v169, v168, 1.0
	s_nop 0
	v_readlane_b32 s37, v168, 0
	v_readlane_b32 s41, v168, 1
	v_readlane_b32 s45, v168, 2
	v_readlane_b32 s49, v168, 3
	v_mul_f32_e32 v80, s37, v80
	v_mul_f32_e32 v85, s41, v85
	v_mul_f32_e32 v90, s45, v90
	v_mul_f32_e32 v95, s49, v95
	v_lshlrev_b32_e32 v83, 16, v83
	v_lshlrev_b32_e32 v88, 16, v88
	v_lshlrev_b32_e32 v93, 16, v93
	v_lshlrev_b32_e32 v98, 16, v98
	v_fma_f32 v80, v6, v80, v7
	v_fma_f32 v85, v6, v85, v7
	v_fma_f32 v90, v6, v90, v7
	v_fma_f32 v95, v6, v95, v7
	v_fmac_f32_e32 v80, s69, v81
	v_fmac_f32_e32 v85, s70, v86
	v_fmac_f32_e32 v90, s71, v91
	v_fmac_f32_e32 v95, s72, v96
	v_mul_f32_e32 v80, v80, v83
	v_mul_f32_e32 v85, v85, v88
	v_mul_f32_e32 v90, v90, v93
	v_mul_f32_e32 v95, v95, v98
	v_cvt_pk_bf16_f32 v169, v80, v80
	v_cvt_pk_bf16_f32 v175, v85, v85
	v_cvt_pk_bf16_f32 v242, v90, v90
	v_cvt_pk_bf16_f32 v248, v95, v95
	global_store_short v2, v169, s[28:29]
	s_add_u32 s28, s28, 0x1000
	s_addc_u32 s29, s29, 0
	global_store_short v2, v175, s[28:29]
	s_add_u32 s28, s28, 0x1000
	s_addc_u32 s29, s29, 0
	global_store_short v2, v242, s[28:29]
	s_add_u32 s28, s28, 0x1000
	s_addc_u32 s29, s29, 0
	global_store_short v2, v248, s[28:29]
	s_add_u32 s28, s28, 0x1000
	s_addc_u32 s29, s29, 0
	s_waitcnt lgkmcnt(0)
	v_add_f32_e32 v100, v100, v44
	v_add_f32_e32 v105, v105, v45
	v_add_f32_e32 v110, v110, v46
	v_add_f32_e32 v115, v115, v47
	v_add_f32_dpp v168, v100, v100 quad_perm:[1,0,3,2] row_mask:0xf bank_mask:0xf bound_ctrl:1
	v_add_f32_dpp v174, v105, v105 quad_perm:[1,0,3,2] row_mask:0xf bank_mask:0xf bound_ctrl:1
	v_add_f32_dpp v241, v110, v110 quad_perm:[1,0,3,2] row_mask:0xf bank_mask:0xf bound_ctrl:1
	v_add_f32_dpp v247, v115, v115 quad_perm:[1,0,3,2] row_mask:0xf bank_mask:0xf bound_ctrl:1
	v_add_f32_dpp v168, v168, v168 quad_perm:[2,3,0,1] row_mask:0xf bank_mask:0xf bound_ctrl:1
	v_add_f32_dpp v174, v174, v174 quad_perm:[2,3,0,1] row_mask:0xf bank_mask:0xf bound_ctrl:1
	v_add_f32_dpp v241, v241, v241 quad_perm:[2,3,0,1] row_mask:0xf bank_mask:0xf bound_ctrl:1
	v_add_f32_dpp v247, v247, v247 quad_perm:[2,3,0,1] row_mask:0xf bank_mask:0xf bound_ctrl:1
	v_add_f32_dpp v168, v168, v168 row_half_mirror row_mask:0xf bank_mask:0xf bound_ctrl:1
	v_add_f32_dpp v174, v174, v174 row_half_mirror row_mask:0xf bank_mask:0xf bound_ctrl:1
	v_add_f32_dpp v241, v241, v241 row_half_mirror row_mask:0xf bank_mask:0xf bound_ctrl:1
	v_add_f32_dpp v247, v247, v247 row_half_mirror row_mask:0xf bank_mask:0xf bound_ctrl:1
	v_add_f32_dpp v168, v168, v168 row_mirror row_mask:0xf bank_mask:0xf bound_ctrl:1
	v_add_f32_dpp v174, v174, v174 row_mirror row_mask:0xf bank_mask:0xf bound_ctrl:1
	v_add_f32_dpp v241, v241, v241 row_mirror row_mask:0xf bank_mask:0xf bound_ctrl:1
	v_add_f32_dpp v247, v247, v247 row_mirror row_mask:0xf bank_mask:0xf bound_ctrl:1
	v_readlane_b32 s36, v168, 16
	v_readlane_b32 s40, v174, 16
	v_readlane_b32 s44, v241, 16
	v_readlane_b32 s48, v247, 16
	v_readlane_b32 s37, v168, 48
	v_readlane_b32 s41, v174, 48
	v_readlane_b32 s45, v241, 48
	v_readlane_b32 s49, v247, 48
	v_readlane_b32 s38, v168, 0
	v_readlane_b32 s42, v174, 0
	v_readlane_b32 s46, v241, 0
	v_readlane_b32 s50, v247, 0
	v_readlane_b32 s39, v168, 32
	v_readlane_b32 s43, v174, 32
	v_readlane_b32 s47, v241, 32
	v_readlane_b32 s51, v247, 32
	v_mov_b32_e32 v168, s36
	v_mov_b32_e32 v174, s40
	v_mov_b32_e32 v241, s44
	v_mov_b32_e32 v247, s48
	v_mov_b32_e32 v169, s37
	v_mov_b32_e32 v175, s41
	v_mov_b32_e32 v242, s45
	v_mov_b32_e32 v248, s49
	v_add_f32_e32 v168, s38, v168
	v_add_f32_e32 v174, s42, v174
	v_add_f32_e32 v241, s46, v241
; __device__ __forceinline__ float bf2f(bf16 x) { return __uint_as_float(((unsigned)x) << 16); }
; __device__ __forceinline__ unsigned f2bf(float f) { return cvt_pk_bf16(f, 0.f) & 0xffffu; }
; #define POST_LD(Y_, V_, G_, R_, C_, t) do { _Pragma("unroll") for (int q = 0; q < 8; ++q) { const size_t o_ = (size_t)((t) + q) * DH; Y_[q] = yp[o_]; V_[q] = vp[o_]; G_[q] = gp[o_]; R_[q] = rp[((t) + q) * 32]; C_[q] = cp[o_]; } } while (0)
; __device__ __forceinline__ void rw_post(Frame& F) {
;     ...
;         POST_LD(y, vv, gg, rk, cc, 0);
;         for (int t0 = 0; t0 < 64; t0 += 8) {
;             float ny[8], nv[8], nr[8], nc[8]; bf16 ng[8];
;             const int tn = t0 + 8 < 64 ? t0 + 8 : t0;
;             POST_LD(ny, nv, ng, nr, nc, tn);
;     ...
;             for (int q = 0; q < 8; ++q) { const int row = rb0 + t0 + q;
;                 const float mean = wsum(y[q]) * (1.f / 64.f); const float dv = y[q] - mean; const float var = wsum(dv * dv) * (1.f / 64.f);
;                 const float yn = dv * (1.f / sqrtf(var + 64e-5f)) * g_ + b_;
;                 OB[(size_t)row * DH + col] = (bf16)f2bf((yn + rk[q] * vv[q]) * bf2f(gg[q])); }
	v_add_f32_e32 v247, s50, v247
	v_add_f32_e32 v169, s39, v169
	v_add_f32_e32 v175, s43, v175
	v_add_f32_e32 v242, s47, v242
	v_add_f32_e32 v248, s51, v248
	v_add_f32_e32 v168, v168, v169
	v_add_f32_e32 v174, v174, v175
	v_add_f32_e32 v241, v241, v242
	v_add_f32_e32 v247, v247, v248
	v_fmamk_f32 v100, v168, 0xbc800000, v100
	v_fmamk_f32 v105, v174, 0xbc800000, v105
	v_fmamk_f32 v110, v241, 0xbc800000, v110
	v_fmamk_f32 v115, v247, 0xbc800000, v115
	v_mul_f32_e32 v168, v100, v100
	v_mul_f32_e32 v174, v105, v105
	v_mul_f32_e32 v241, v110, v110
	v_mul_f32_e32 v247, v115, v115
	v_mov_b32_dpp v168, v168 quad_perm:[1,0,3,2] row_mask:0xf bank_mask:0xf bound_ctrl:1
	v_mov_b32_dpp v174, v174 quad_perm:[1,0,3,2] row_mask:0xf bank_mask:0xf bound_ctrl:1
	v_mov_b32_dpp v241, v241 quad_perm:[1,0,3,2] row_mask:0xf bank_mask:0xf bound_ctrl:1
	v_mov_b32_dpp v247, v247 quad_perm:[1,0,3,2] row_mask:0xf bank_mask:0xf bound_ctrl:1
	v_fmac_f32_e32 v168, v100, v100
	v_fmac_f32_e32 v174, v105, v105
	v_fmac_f32_e32 v241, v110, v110
	v_fmac_f32_e32 v247, v115, v115
	v_add_f32_dpp v168, v168, v168 quad_perm:[2,3,0,1] row_mask:0xf bank_mask:0xf bound_ctrl:1
	v_add_f32_dpp v174, v174, v174 quad_perm:[2,3,0,1] row_mask:0xf bank_mask:0xf bound_ctrl:1
	v_add_f32_dpp v241, v241, v241 quad_perm:[2,3,0,1] row_mask:0xf bank_mask:0xf bound_ctrl:1
	v_add_f32_dpp v247, v247, v247 quad_perm:[2,3,0,1] row_mask:0xf bank_mask:0xf bound_ctrl:1
	v_add_f32_dpp v168, v168, v168 row_half_mirror row_mask:0xf bank_mask:0xf bound_ctrl:1
	v_add_f32_dpp v174, v174, v174 row_half_mirror row_mask:0xf bank_mask:0xf bound_ctrl:1
	v_add_f32_dpp v241, v241, v241 row_half_mirror row_mask:0xf bank_mask:0xf bound_ctrl:1
	v_add_f32_dpp v247, v247, v247 row_half_mirror row_mask:0xf bank_mask:0xf bound_ctrl:1
	v_add_f32_dpp v168, v168, v168 row_mirror row_mask:0xf bank_mask:0xf bound_ctrl:1
	v_add_f32_dpp v174, v174, v174 row_mirror row_mask:0xf bank_mask:0xf bound_ctrl:1
	v_add_f32_dpp v241, v241, v241 row_mirror row_mask:0xf bank_mask:0xf bound_ctrl:1
	v_add_f32_dpp v247, v247, v247 row_mirror row_mask:0xf bank_mask:0xf bound_ctrl:1
	v_readlane_b32 s36, v168, 16
	v_readlane_b32 s40, v174, 16
	v_readlane_b32 s44, v241, 16
	v_readlane_b32 s48, v247, 16
	v_readlane_b32 s37, v168, 48
	v_readlane_b32 s41, v174, 48
	v_readlane_b32 s45, v241, 48
	v_readlane_b32 s49, v247, 48
	v_readlane_b32 s38, v168, 0
	v_readlane_b32 s42, v174, 0
	v_readlane_b32 s46, v241, 0
	v_readlane_b32 s50, v247, 0
	v_readlane_b32 s39, v168, 32
	v_readlane_b32 s43, v174, 32
	v_readlane_b32 s47, v241, 32
	v_readlane_b32 s51, v247, 32
	v_mov_b32_e32 v168, s36
	v_mov_b32_e32 v174, s40
	v_mov_b32_e32 v241, s44
	v_mov_b32_e32 v247, s48
	v_mov_b32_e32 v169, s37
	v_mov_b32_e32 v175, s41
	v_mov_b32_e32 v242, s45
	v_mov_b32_e32 v248, s49
	v_add_f32_e32 v168, s38, v168
	v_add_f32_e32 v174, s42, v174
	v_add_f32_e32 v241, s46, v241
	v_add_f32_e32 v247, s50, v247
	v_add_f32_e32 v169, s39, v169
	v_add_f32_e32 v175, s43, v175
	v_add_f32_e32 v242, s47, v242
	v_add_f32_e32 v248, s51, v248
	v_add_f32_e32 v168, v168, v169
	v_add_f32_e32 v174, v174, v175
	v_add_f32_e32 v241, v241, v242
	v_add_f32_e32 v247, v247, v248
	v_fmamk_f32 v168, v168, 0x3c800000, v9
	v_fmamk_f32 v174, v174, 0x3c800000, v9
	v_fmamk_f32 v241, v241, 0x3c800000, v9
	v_fmamk_f32 v247, v247, 0x3c800000, v9
	v_readfirstlane_b32 s40, v174
	v_readfirstlane_b32 s44, v241
	v_readfirstlane_b32 s48, v247
	v_writelane_b32 v168, s40, 1
	v_writelane_b32 v168, s44, 2
	v_writelane_b32 v168, s48, 3
	v_mul_f32_e32 v169, 0x4f800000, v168
	v_cmp_gt_f32_e64 s[52:53], s68, v168
	v_mov_b32_e32 v170, v168
	s_nop 1
	v_cndmask_b32_e64 v168, v170, v169, s[52:53]
	v_sqrt_f32_e32 v169, v168
	s_nop 0
	v_add_u32_e32 v170, -1, v169
	v_fma_f32 v171, -v170, v169, v168
	v_cmp_ge_f32_e64 s[60:61], 0, v171
	v_add_u32_e32 v171, 1, v169
	s_nop 1
	v_cndmask_b32_e64 v170, v169, v170, s[60:61]
	v_fma_f32 v169, -v171, v169, v168
	v_cmp_lt_f32_e64 s[60:61], 0, v169
	s_nop 1
	v_cndmask_b32_e64 v169, v170, v171, s[60:61]
	v_mul_f32_e32 v170, 0x37800000, v169
	v_cndmask_b32_e64 v169, v169, v170, s[52:53]
	v_cmp_class_f32_e64 s[60:61], v168, v8
	s_nop 1
	v_cndmask_b32_e64 v168, v169, v168, s[60:61]
	v_div_scale_f32 v169, s[60:61], v168, v168, 1.0
	v_rcp_f32_e32 v170, v169
	s_nop 0
	v_fma_f32 v171, -v169, v170, 1.0
	v_fmac_f32_e32 v170, v171, v170
	v_div_scale_f32 v171, vcc, 1.0, v168, 1.0
	v_mul_f32_e32 v172, v171, v170
	v_fma_f32 v173, -v169, v172, v171
	v_fmac_f32_e32 v172, v173, v170
	v_fma_f32 v169, -v169, v172, v171
	v_div_fmas_f32 v169, v169, v170, v172
	v_div_fixup_f32 v168, v169, v168, 1.0
	s_nop 0
	v_readlane_b32 s37, v168, 0
	v_readlane_b32 s41, v168, 1
	v_readlane_b32 s45, v168, 2
	v_readlane_b32 s49, v168, 3
	v_mul_f32_e32 v100, s37, v100
	v_mul_f32_e32 v105, s41, v105
	v_mul_f32_e32 v110, s45, v110
	v_mul_f32_e32 v115, s49, v115
	v_lshlrev_b32_e32 v103, 16, v103
	v_lshlrev_b32_e32 v108, 16, v108
	v_lshlrev_b32_e32 v113, 16, v113
	v_lshlrev_b32_e32 v118, 16, v118
	v_fma_f32 v100, v6, v100, v7
	v_fma_f32 v105, v6, v105, v7
	v_fma_f32 v110, v6, v110, v7
	v_fma_f32 v115, v6, v115, v7
	v_fmac_f32_e32 v100, s73, v101
	v_fmac_f32_e32 v105, s26, v106
	v_fmac_f32_e32 v110, s27, v111
	v_fmac_f32_e32 v115, s32, v116
	v_mul_f32_e32 v100, v100, v103
	v_mul_f32_e32 v105, v105, v108
	v_mul_f32_e32 v110, v110, v113
	v_mul_f32_e32 v115, v115, v118
	v_cvt_pk_bf16_f32 v169, v100, v100
	v_cvt_pk_bf16_f32 v175, v105, v105
	v_cvt_pk_bf16_f32 v242, v110, v110
	v_cvt_pk_bf16_f32 v248, v115, v115
	global_store_short v2, v169, s[28:29]
	s_add_u32 s28, s28, 0x1000
	s_addc_u32 s29, s29, 0
	global_store_short v2, v175, s[28:29]
	s_add_u32 s28, s28, 0x1000
	s_addc_u32 s29, s29, 0
	global_store_short v2, v242, s[28:29]
	s_add_u32 s28, s28, 0x1000
	s_addc_u32 s29, s29, 0
	global_store_short v2, v248, s[28:29]
	s_add_u32 s28, s28, 0x1000
	s_addc_u32 s29, s29, 0
	s_waitcnt vmcnt(8)
	ds_write_b128 v12, v[120:123] offset:0
	ds_write_b128 v12, v[124:127] offset:1024
	ds_write_b128 v12, v[128:131] offset:16384
	ds_write_b128 v12, v[132:135] offset:17408
	ds_write_b128 v14, v[136:139]
	v_readlane_b32 s69, v159, 0
	v_readlane_b32 s70, v159, 1
	v_readlane_b32 s71, v159, 2
	v_readlane_b32 s72, v159, 3
	v_readlane_b32 s73, v159, 4
	v_readlane_b32 s26, v159, 5
	v_readlane_b32 s27, v159, 6
	v_readlane_b32 s32, v159, 7
	global_load_dwordx4 v[120:123], v11, s[6:7]
	global_load_dwordx4 v[124:127], v11, s[6:7] offset:1024
	global_load_dwordx4 v[128:131], v11, s[8:9]
	global_load_dwordx4 v[132:135], v11, s[8:9] offset:1024
	global_load_dwordx4 v[136:139], v11, s[10:11]
	global_load_dword v159, v158, s[12:13]
	s_add_u32 s6, s6, 0x10000
	s_addc_u32 s7, s7, 0
	s_add_u32 s8, s8, 0x10000
	s_addc_u32 s9, s9, 0
	s_add_u32 s10, s10, 0x8000
	s_addc_u32 s11, s11, 0
	s_add_u32 s12, s12, 0x400
	s_addc_u32 s13, s13, 0
	s_waitcnt lgkmcnt(0)
	s_barrier
; __device__ __forceinline__ float bf2f(bf16 x) { return __uint_as_float(((unsigned)x) << 16); }
; __device__ __forceinline__ unsigned f2bf(float f) { return cvt_pk_bf16(f, 0.f) & 0xffffu; }
; __device__ __forceinline__ void rw_post(Frame& F) {
;     ...
;             for (int q = 0; q < 8; ++q) { const int row = rb0 + t0 + q;
;                 const float mean = wsum(y[q]) * (1.f / 64.f); const float dv = y[q] - mean; const float var = wsum(dv * dv) * (1.f / 64.f);
;                 const float yn = dv * (1.f / sqrtf(var + 64e-5f)) * g_ + b_;
;                 OB[(size_t)row * DH + col] = (bf16)f2bf((yn + rk[q] * vv[q]) * bf2f(gg[q])); }
	ds_read_b32 v80, v154 offset:0
	ds_read_b32 v81, v154 offset:16384
	ds_read_u16 v83, v156 offset:0
	ds_read_b32 v85, v154 offset:2048
	ds_read_b32 v86, v154 offset:18432
	ds_read_u16 v88, v156 offset:1024
	ds_read_b32 v90, v154 offset:4096
	ds_read_b32 v91, v154 offset:20480
	ds_read_u16 v93, v156 offset:2048
	ds_read_b32 v95, v154 offset:6144
	ds_read_b32 v96, v154 offset:22528
	ds_read_u16 v98, v156 offset:3072
	ds_read_b32 v100, v154 offset:8192
	ds_read_b32 v101, v154 offset:24576
	ds_read_u16 v103, v156 offset:4096
	ds_read_b32 v105, v154 offset:10240
	ds_read_b32 v106, v154 offset:26624
	ds_read_u16 v108, v156 offset:5120
	ds_read_b32 v110, v154 offset:12288
	ds_read_b32 v111, v154 offset:28672
	ds_read_u16 v113, v156 offset:6144
	ds_read_b32 v115, v154 offset:14336
	ds_read_b32 v116, v154 offset:30720
	ds_read_u16 v118, v156 offset:7168
	s_waitcnt lgkmcnt(12)
	v_add_f32_e32 v80, v80, v48
	v_add_f32_e32 v85, v85, v49
	v_add_f32_e32 v90, v90, v50
	v_add_f32_e32 v95, v95, v51
	v_add_f32_dpp v168, v80, v80 quad_perm:[1,0,3,2] row_mask:0xf bank_mask:0xf bound_ctrl:1
	v_add_f32_dpp v174, v85, v85 quad_perm:[1,0,3,2] row_mask:0xf bank_mask:0xf bound_ctrl:1
	v_add_f32_dpp v241, v90, v90 quad_perm:[1,0,3,2] row_mask:0xf bank_mask:0xf bound_ctrl:1
	v_add_f32_dpp v247, v95, v95 quad_perm:[1,0,3,2] row_mask:0xf bank_mask:0xf bound_ctrl:1
	v_add_f32_dpp v168, v168, v168 quad_perm:[2,3,0,1] row_mask:0xf bank_mask:0xf bound_ctrl:1
	v_add_f32_dpp v174, v174, v174 quad_perm:[2,3,0,1] row_mask:0xf bank_mask:0xf bound_ctrl:1
	v_add_f32_dpp v241, v241, v241 quad_perm:[2,3,0,1] row_mask:0xf bank_mask:0xf bound_ctrl:1
	v_add_f32_dpp v247, v247, v247 quad_perm:[2,3,0,1] row_mask:0xf bank_mask:0xf bound_ctrl:1
	v_add_f32_dpp v168, v168, v168 row_half_mirror row_mask:0xf bank_mask:0xf bound_ctrl:1
	v_add_f32_dpp v174, v174, v174 row_half_mirror row_mask:0xf bank_mask:0xf bound_ctrl:1
	v_add_f32_dpp v241, v241, v241 row_half_mirror row_mask:0xf bank_mask:0xf bound_ctrl:1
	v_add_f32_dpp v247, v247, v247 row_half_mirror row_mask:0xf bank_mask:0xf bound_ctrl:1
	v_add_f32_dpp v168, v168, v168 row_mirror row_mask:0xf bank_mask:0xf bound_ctrl:1
	v_add_f32_dpp v174, v174, v174 row_mirror row_mask:0xf bank_mask:0xf bound_ctrl:1
	v_add_f32_dpp v241, v241, v241 row_mirror row_mask:0xf bank_mask:0xf bound_ctrl:1
	v_add_f32_dpp v247, v247, v247 row_mirror row_mask:0xf bank_mask:0xf bound_ctrl:1
	v_readlane_b32 s36, v168, 16
	v_readlane_b32 s40, v174, 16
	v_readlane_b32 s44, v241, 16
	v_readlane_b32 s48, v247, 16
	v_readlane_b32 s37, v168, 48
	v_readlane_b32 s41, v174, 48
	v_readlane_b32 s45, v241, 48
	v_readlane_b32 s49, v247, 48
	v_readlane_b32 s38, v168, 0
	v_readlane_b32 s42, v174, 0
	v_readlane_b32 s46, v241, 0
	v_readlane_b32 s50, v247, 0
	v_readlane_b32 s39, v168, 32
	v_readlane_b32 s43, v174, 32
	v_readlane_b32 s47, v241, 32
	v_readlane_b32 s51, v247, 32
	v_mov_b32_e32 v168, s36
	v_mov_b32_e32 v174, s40
	v_mov_b32_e32 v241, s44
	v_mov_b32_e32 v247, s48
	v_mov_b32_e32 v169, s37
	v_mov_b32_e32 v175, s41
	v_mov_b32_e32 v242, s45
	v_mov_b32_e32 v248, s49
	v_add_f32_e32 v168, s38, v168
	v_add_f32_e32 v174, s42, v174
	v_add_f32_e32 v241, s46, v241
	v_add_f32_e32 v247, s50, v247
	v_add_f32_e32 v169, s39, v169
	v_add_f32_e32 v175, s43, v175
	v_add_f32_e32 v242, s47, v242
	v_add_f32_e32 v248, s51, v248
	v_add_f32_e32 v168, v168, v169
	v_add_f32_e32 v174, v174, v175
	v_add_f32_e32 v241, v241, v242
	v_add_f32_e32 v247, v247, v248
	v_fmamk_f32 v80, v168, 0xbc800000, v80
	v_fmamk_f32 v85, v174, 0xbc800000, v85
	v_fmamk_f32 v90, v241, 0xbc800000, v90
	v_fmamk_f32 v95, v247, 0xbc800000, v95
	v_mul_f32_e32 v168, v80, v80
	v_mul_f32_e32 v174, v85, v85
	v_mul_f32_e32 v241, v90, v90
	v_mul_f32_e32 v247, v95, v95
	v_mov_b32_dpp v168, v168 quad_perm:[1,0,3,2] row_mask:0xf bank_mask:0xf bound_ctrl:1
	v_mov_b32_dpp v174, v174 quad_perm:[1,0,3,2] row_mask:0xf bank_mask:0xf bound_ctrl:1
	v_mov_b32_dpp v241, v241 quad_perm:[1,0,3,2] row_mask:0xf bank_mask:0xf bound_ctrl:1
	v_mov_b32_dpp v247, v247 quad_perm:[1,0,3,2] row_mask:0xf bank_mask:0xf bound_ctrl:1
	v_fmac_f32_e32 v168, v80, v80
	v_fmac_f32_e32 v174, v85, v85
	v_fmac_f32_e32 v241, v90, v90
	v_fmac_f32_e32 v247, v95, v95
	v_add_f32_dpp v168, v168, v168 quad_perm:[2,3,0,1] row_mask:0xf bank_mask:0xf bound_ctrl:1
	v_add_f32_dpp v174, v174, v174 quad_perm:[2,3,0,1] row_mask:0xf bank_mask:0xf bound_ctrl:1
	v_add_f32_dpp v241, v241, v241 quad_perm:[2,3,0,1] row_mask:0xf bank_mask:0xf bound_ctrl:1
	v_add_f32_dpp v247, v247, v247 quad_perm:[2,3,0,1] row_mask:0xf bank_mask:0xf bound_ctrl:1
	v_add_f32_dpp v168, v168, v168 row_half_mirror row_mask:0xf bank_mask:0xf bound_ctrl:1
	v_add_f32_dpp v174, v174, v174 row_half_mirror row_mask:0xf bank_mask:0xf bound_ctrl:1
	v_add_f32_dpp v241, v241, v241 row_half_mirror row_mask:0xf bank_mask:0xf bound_ctrl:1
	v_add_f32_dpp v247, v247, v247 row_half_mirror row_mask:0xf bank_mask:0xf bound_ctrl:1
	v_add_f32_dpp v168, v168, v168 row_mirror row_mask:0xf bank_mask:0xf bound_ctrl:1
	v_add_f32_dpp v174, v174, v174 row_mirror row_mask:0xf bank_mask:0xf bound_ctrl:1
	v_add_f32_dpp v241, v241, v241 row_mirror row_mask:0xf bank_mask:0xf bound_ctrl:1
	v_add_f32_dpp v247, v247, v247 row_mirror row_mask:0xf bank_mask:0xf bound_ctrl:1
	v_readlane_b32 s36, v168, 16
	v_readlane_b32 s40, v174, 16
	v_readlane_b32 s44, v241, 16
	v_readlane_b32 s48, v247, 16
	v_readlane_b32 s37, v168, 48
	v_readlane_b32 s41, v174, 48
	v_readlane_b32 s45, v241, 48
	v_readlane_b32 s49, v247, 48
	v_readlane_b32 s38, v168, 0
	v_readlane_b32 s42, v174, 0
	v_readlane_b32 s46, v241, 0
	v_readlane_b32 s50, v247, 0
	v_readlane_b32 s39, v168, 32
; __device__ __forceinline__ float bf2f(bf16 x) { return __uint_as_float(((unsigned)x) << 16); }
; __device__ __forceinline__ unsigned f2bf(float f) { return cvt_pk_bf16(f, 0.f) & 0xffffu; }
; __device__ __forceinline__ void rw_post(Frame& F) {
;     ...
;             for (int q = 0; q < 8; ++q) { const int row = rb0 + t0 + q;
;                 const float mean = wsum(y[q]) * (1.f / 64.f); const float dv = y[q] - mean; const float var = wsum(dv * dv) * (1.f / 64.f);
;                 const float yn = dv * (1.f / sqrtf(var + 64e-5f)) * g_ + b_;
;                 OB[(size_t)row * DH + col] = (bf16)f2bf((yn + rk[q] * vv[q]) * bf2f(gg[q])); }
	v_readlane_b32 s43, v174, 32
	v_readlane_b32 s47, v241, 32
	v_readlane_b32 s51, v247, 32
	v_mov_b32_e32 v168, s36
	v_mov_b32_e32 v174, s40
	v_mov_b32_e32 v241, s44
	v_mov_b32_e32 v247, s48
	v_mov_b32_e32 v169, s37
	v_mov_b32_e32 v175, s41
	v_mov_b32_e32 v242, s45
	v_mov_b32_e32 v248, s49
	v_add_f32_e32 v168, s38, v168
	v_add_f32_e32 v174, s42, v174
	v_add_f32_e32 v241, s46, v241
	v_add_f32_e32 v247, s50, v247
	v_add_f32_e32 v169, s39, v169
	v_add_f32_e32 v175, s43, v175
	v_add_f32_e32 v242, s47, v242
	v_add_f32_e32 v248, s51, v248
	v_add_f32_e32 v168, v168, v169
	v_add_f32_e32 v174, v174, v175
	v_add_f32_e32 v241, v241, v242
	v_add_f32_e32 v247, v247, v248
	v_fmamk_f32 v168, v168, 0x3c800000, v9
	v_fmamk_f32 v174, v174, 0x3c800000, v9
	v_fmamk_f32 v241, v241, 0x3c800000, v9
	v_fmamk_f32 v247, v247, 0x3c800000, v9
	v_readfirstlane_b32 s40, v174
	v_readfirstlane_b32 s44, v241
	v_readfirstlane_b32 s48, v247
	v_writelane_b32 v168, s40, 1
	v_writelane_b32 v168, s44, 2
	v_writelane_b32 v168, s48, 3
	v_mul_f32_e32 v169, 0x4f800000, v168
	v_cmp_gt_f32_e64 s[52:53], s68, v168
	v_mov_b32_e32 v170, v168
	s_nop 1
	v_cndmask_b32_e64 v168, v170, v169, s[52:53]
	v_sqrt_f32_e32 v169, v168
	s_nop 0
	v_add_u32_e32 v170, -1, v169
	v_fma_f32 v171, -v170, v169, v168
	v_cmp_ge_f32_e64 s[60:61], 0, v171
	v_add_u32_e32 v171, 1, v169
	s_nop 1
	v_cndmask_b32_e64 v170, v169, v170, s[60:61]
	v_fma_f32 v169, -v171, v169, v168
	v_cmp_lt_f32_e64 s[60:61], 0, v169
	s_nop 1
	v_cndmask_b32_e64 v169, v170, v171, s[60:61]
	v_mul_f32_e32 v170, 0x37800000, v169
	v_cndmask_b32_e64 v169, v169, v170, s[52:53]
	v_cmp_class_f32_e64 s[60:61], v168, v8
	s_nop 1
	v_cndmask_b32_e64 v168, v169, v168, s[60:61]
	v_div_scale_f32 v169, s[60:61], v168, v168, 1.0
	v_rcp_f32_e32 v170, v169
	s_nop 0
	v_fma_f32 v171, -v169, v170, 1.0
	v_fmac_f32_e32 v170, v171, v170
	v_div_scale_f32 v171, vcc, 1.0, v168, 1.0
	v_mul_f32_e32 v172, v171, v170
	v_fma_f32 v173, -v169, v172, v171
	v_fmac_f32_e32 v172, v173, v170
	v_fma_f32 v169, -v169, v172, v171
	v_div_fmas_f32 v169, v169, v170, v172
	v_div_fixup_f32 v168, v169, v168, 1.0
	s_nop 0
	v_readlane_b32 s37, v168, 0
	v_readlane_b32 s41, v168, 1
	v_readlane_b32 s45, v168, 2
	v_readlane_b32 s49, v168, 3
	v_mul_f32_e32 v80, s37, v80
	v_mul_f32_e32 v85, s41, v85
	v_mul_f32_e32 v90, s45, v90
	v_mul_f32_e32 v95, s49, v95
	v_lshlrev_b32_e32 v83, 16, v83
	v_lshlrev_b32_e32 v88, 16, v88
	v_lshlrev_b32_e32 v93, 16, v93
	v_lshlrev_b32_e32 v98, 16, v98
	v_fma_f32 v80, v6, v80, v7
	v_fma_f32 v85, v6, v85, v7
	v_fma_f32 v90, v6, v90, v7
	v_fma_f32 v95, v6, v95, v7
	v_fmac_f32_e32 v80, s69, v81
	v_fmac_f32_e32 v85, s70, v86
	v_fmac_f32_e32 v90, s71, v91
	v_fmac_f32_e32 v95, s72, v96
	v_mul_f32_e32 v80, v80, v83
	v_mul_f32_e32 v85, v85, v88
	v_mul_f32_e32 v90, v90, v93
	v_mul_f32_e32 v95, v95, v98
	v_cvt_pk_bf16_f32 v169, v80, v80
	v_cvt_pk_bf16_f32 v175, v85, v85
	v_cvt_pk_bf16_f32 v242, v90, v90
	v_cvt_pk_bf16_f32 v248, v95, v95
	global_store_short v2, v169, s[28:29]
	s_add_u32 s28, s28, 0x1000
	s_addc_u32 s29, s29, 0
	global_store_short v2, v175, s[28:29]
	s_add_u32 s28, s28, 0x1000
	s_addc_u32 s29, s29, 0
	global_store_short v2, v242, s[28:29]
	s_add_u32 s28, s28, 0x1000
	s_addc_u32 s29, s29, 0
	global_store_short v2, v248, s[28:29]
	s_add_u32 s28, s28, 0x1000
	s_addc_u32 s29, s29, 0
	s_waitcnt lgkmcnt(0)
	v_add_f32_e32 v100, v100, v64
	v_add_f32_e32 v105, v105, v65
	v_add_f32_e32 v110, v110, v66
	v_add_f32_e32 v115, v115, v67
	v_add_f32_dpp v168, v100, v100 quad_perm:[1,0,3,2] row_mask:0xf bank_mask:0xf bound_ctrl:1
	v_add_f32_dpp v174, v105, v105 quad_perm:[1,0,3,2] row_mask:0xf bank_mask:0xf bound_ctrl:1
	v_add_f32_dpp v241, v110, v110 quad_perm:[1,0,3,2] row_mask:0xf bank_mask:0xf bound_ctrl:1
	v_add_f32_dpp v247, v115, v115 quad_perm:[1,0,3,2] row_mask:0xf bank_mask:0xf bound_ctrl:1
	v_add_f32_dpp v168, v168, v168 quad_perm:[2,3,0,1] row_mask:0xf bank_mask:0xf bound_ctrl:1
	v_add_f32_dpp v174, v174, v174 quad_perm:[2,3,0,1] row_mask:0xf bank_mask:0xf bound_ctrl:1
	v_add_f32_dpp v241, v241, v241 quad_perm:[2,3,0,1] row_mask:0xf bank_mask:0xf bound_ctrl:1
	v_add_f32_dpp v247, v247, v247 quad_perm:[2,3,0,1] row_mask:0xf bank_mask:0xf bound_ctrl:1
	v_add_f32_dpp v168, v168, v168 row_half_mirror row_mask:0xf bank_mask:0xf bound_ctrl:1
	v_add_f32_dpp v174, v174, v174 row_half_mirror row_mask:0xf bank_mask:0xf bound_ctrl:1
	v_add_f32_dpp v241, v241, v241 row_half_mirror row_mask:0xf bank_mask:0xf bound_ctrl:1
	v_add_f32_dpp v247, v247, v247 row_half_mirror row_mask:0xf bank_mask:0xf bound_ctrl:1
	v_add_f32_dpp v168, v168, v168 row_mirror row_mask:0xf bank_mask:0xf bound_ctrl:1
	v_add_f32_dpp v174, v174, v174 row_mirror row_mask:0xf bank_mask:0xf bound_ctrl:1
	v_add_f32_dpp v241, v241, v241 row_mirror row_mask:0xf bank_mask:0xf bound_ctrl:1
	v_add_f32_dpp v247, v247, v247 row_mirror row_mask:0xf bank_mask:0xf bound_ctrl:1
	v_readlane_b32 s36, v168, 16
	v_readlane_b32 s40, v174, 16
	v_readlane_b32 s44, v241, 16
	v_readlane_b32 s48, v247, 16
	v_readlane_b32 s37, v168, 48
	v_readlane_b32 s41, v174, 48
	v_readlane_b32 s45, v241, 48
	v_readlane_b32 s49, v247, 48
	v_readlane_b32 s38, v168, 0
	v_readlane_b32 s42, v174, 0
	v_readlane_b32 s46, v241, 0
	v_readlane_b32 s50, v247, 0
	v_readlane_b32 s39, v168, 32
	v_readlane_b32 s43, v174, 32
	v_readlane_b32 s47, v241, 32
	v_readlane_b32 s51, v247, 32
	v_mov_b32_e32 v168, s36
	v_mov_b32_e32 v174, s40
	v_mov_b32_e32 v241, s44
	v_mov_b32_e32 v247, s48
	v_mov_b32_e32 v169, s37
	v_mov_b32_e32 v175, s41
	v_mov_b32_e32 v242, s45
	v_mov_b32_e32 v248, s49
	v_add_f32_e32 v168, s38, v168
	v_add_f32_e32 v174, s42, v174
	v_add_f32_e32 v241, s46, v241
; __device__ __forceinline__ float bf2f(bf16 x) { return __uint_as_float(((unsigned)x) << 16); }
; __device__ __forceinline__ unsigned f2bf(float f) { return cvt_pk_bf16(f, 0.f) & 0xffffu; }
; #define POST_LD(Y_, V_, G_, R_, C_, t) do { _Pragma("unroll") for (int q = 0; q < 8; ++q) { const size_t o_ = (size_t)((t) + q) * DH; Y_[q] = yp[o_]; V_[q] = vp[o_]; G_[q] = gp[o_]; R_[q] = rp[((t) + q) * 32]; C_[q] = cp[o_]; } } while (0)
; __device__ __forceinline__ void rw_post(Frame& F) {
;     ...
;         POST_LD(y, vv, gg, rk, cc, 0);
;         for (int t0 = 0; t0 < 64; t0 += 8) {
;             float ny[8], nv[8], nr[8], nc[8]; bf16 ng[8];
;             const int tn = t0 + 8 < 64 ? t0 + 8 : t0;
;             POST_LD(ny, nv, ng, nr, nc, tn);
;     ...
;             for (int q = 0; q < 8; ++q) { const int row = rb0 + t0 + q;
;                 const float mean = wsum(y[q]) * (1.f / 64.f); const float dv = y[q] - mean; const float var = wsum(dv * dv) * (1.f / 64.f);
;                 const float yn = dv * (1.f / sqrtf(var + 64e-5f)) * g_ + b_;
;                 OB[(size_t)row * DH + col] = (bf16)f2bf((yn + rk[q] * vv[q]) * bf2f(gg[q])); }
	v_add_f32_e32 v247, s50, v247
	v_add_f32_e32 v169, s39, v169
	v_add_f32_e32 v175, s43, v175
	v_add_f32_e32 v242, s47, v242
	v_add_f32_e32 v248, s51, v248
	v_add_f32_e32 v168, v168, v169
	v_add_f32_e32 v174, v174, v175
	v_add_f32_e32 v241, v241, v242
	v_add_f32_e32 v247, v247, v248
	v_fmamk_f32 v100, v168, 0xbc800000, v100
	v_fmamk_f32 v105, v174, 0xbc800000, v105
	v_fmamk_f32 v110, v241, 0xbc800000, v110
	v_fmamk_f32 v115, v247, 0xbc800000, v115
	v_mul_f32_e32 v168, v100, v100
	v_mul_f32_e32 v174, v105, v105
	v_mul_f32_e32 v241, v110, v110
	v_mul_f32_e32 v247, v115, v115
	v_mov_b32_dpp v168, v168 quad_perm:[1,0,3,2] row_mask:0xf bank_mask:0xf bound_ctrl:1
	v_mov_b32_dpp v174, v174 quad_perm:[1,0,3,2] row_mask:0xf bank_mask:0xf bound_ctrl:1
	v_mov_b32_dpp v241, v241 quad_perm:[1,0,3,2] row_mask:0xf bank_mask:0xf bound_ctrl:1
	v_mov_b32_dpp v247, v247 quad_perm:[1,0,3,2] row_mask:0xf bank_mask:0xf bound_ctrl:1
	v_fmac_f32_e32 v168, v100, v100
	v_fmac_f32_e32 v174, v105, v105
	v_fmac_f32_e32 v241, v110, v110
	v_fmac_f32_e32 v247, v115, v115
	v_add_f32_dpp v168, v168, v168 quad_perm:[2,3,0,1] row_mask:0xf bank_mask:0xf bound_ctrl:1
	v_add_f32_dpp v174, v174, v174 quad_perm:[2,3,0,1] row_mask:0xf bank_mask:0xf bound_ctrl:1
	v_add_f32_dpp v241, v241, v241 quad_perm:[2,3,0,1] row_mask:0xf bank_mask:0xf bound_ctrl:1
	v_add_f32_dpp v247, v247, v247 quad_perm:[2,3,0,1] row_mask:0xf bank_mask:0xf bound_ctrl:1
	v_add_f32_dpp v168, v168, v168 row_half_mirror row_mask:0xf bank_mask:0xf bound_ctrl:1
	v_add_f32_dpp v174, v174, v174 row_half_mirror row_mask:0xf bank_mask:0xf bound_ctrl:1
	v_add_f32_dpp v241, v241, v241 row_half_mirror row_mask:0xf bank_mask:0xf bound_ctrl:1
	v_add_f32_dpp v247, v247, v247 row_half_mirror row_mask:0xf bank_mask:0xf bound_ctrl:1
	v_add_f32_dpp v168, v168, v168 row_mirror row_mask:0xf bank_mask:0xf bound_ctrl:1
	v_add_f32_dpp v174, v174, v174 row_mirror row_mask:0xf bank_mask:0xf bound_ctrl:1
	v_add_f32_dpp v241, v241, v241 row_mirror row_mask:0xf bank_mask:0xf bound_ctrl:1
	v_add_f32_dpp v247, v247, v247 row_mirror row_mask:0xf bank_mask:0xf bound_ctrl:1
	v_readlane_b32 s36, v168, 16
	v_readlane_b32 s40, v174, 16
	v_readlane_b32 s44, v241, 16
	v_readlane_b32 s48, v247, 16
	v_readlane_b32 s37, v168, 48
	v_readlane_b32 s41, v174, 48
	v_readlane_b32 s45, v241, 48
	v_readlane_b32 s49, v247, 48
	v_readlane_b32 s38, v168, 0
	v_readlane_b32 s42, v174, 0
	v_readlane_b32 s46, v241, 0
	v_readlane_b32 s50, v247, 0
	v_readlane_b32 s39, v168, 32
	v_readlane_b32 s43, v174, 32
	v_readlane_b32 s47, v241, 32
	v_readlane_b32 s51, v247, 32
	v_mov_b32_e32 v168, s36
	v_mov_b32_e32 v174, s40
	v_mov_b32_e32 v241, s44
	v_mov_b32_e32 v247, s48
	v_mov_b32_e32 v169, s37
	v_mov_b32_e32 v175, s41
	v_mov_b32_e32 v242, s45
	v_mov_b32_e32 v248, s49
	v_add_f32_e32 v168, s38, v168
	v_add_f32_e32 v174, s42, v174
	v_add_f32_e32 v241, s46, v241
	v_add_f32_e32 v247, s50, v247
	v_add_f32_e32 v169, s39, v169
	v_add_f32_e32 v175, s43, v175
	v_add_f32_e32 v242, s47, v242
	v_add_f32_e32 v248, s51, v248
	v_add_f32_e32 v168, v168, v169
	v_add_f32_e32 v174, v174, v175
	v_add_f32_e32 v241, v241, v242
	v_add_f32_e32 v247, v247, v248
	v_fmamk_f32 v168, v168, 0x3c800000, v9
	v_fmamk_f32 v174, v174, 0x3c800000, v9
	v_fmamk_f32 v241, v241, 0x3c800000, v9
	v_fmamk_f32 v247, v247, 0x3c800000, v9
	v_readfirstlane_b32 s40, v174
	v_readfirstlane_b32 s44, v241
	v_readfirstlane_b32 s48, v247
	v_writelane_b32 v168, s40, 1
	v_writelane_b32 v168, s44, 2
	v_writelane_b32 v168, s48, 3
	v_mul_f32_e32 v169, 0x4f800000, v168
	v_cmp_gt_f32_e64 s[52:53], s68, v168
	v_mov_b32_e32 v170, v168
	s_nop 1
	v_cndmask_b32_e64 v168, v170, v169, s[52:53]
	v_sqrt_f32_e32 v169, v168
	s_nop 0
	v_add_u32_e32 v170, -1, v169
	v_fma_f32 v171, -v170, v169, v168
	v_cmp_ge_f32_e64 s[60:61], 0, v171
	v_add_u32_e32 v171, 1, v169
	s_nop 1
	v_cndmask_b32_e64 v170, v169, v170, s[60:61]
	v_fma_f32 v169, -v171, v169, v168
	v_cmp_lt_f32_e64 s[60:61], 0, v169
	s_nop 1
	v_cndmask_b32_e64 v169, v170, v171, s[60:61]
	v_mul_f32_e32 v170, 0x37800000, v169
	v_cndmask_b32_e64 v169, v169, v170, s[52:53]
	v_cmp_class_f32_e64 s[60:61], v168, v8
	s_nop 1
	v_cndmask_b32_e64 v168, v169, v168, s[60:61]
	v_div_scale_f32 v169, s[60:61], v168, v168, 1.0
	v_rcp_f32_e32 v170, v169
	s_nop 0
	v_fma_f32 v171, -v169, v170, 1.0
	v_fmac_f32_e32 v170, v171, v170
	v_div_scale_f32 v171, vcc, 1.0, v168, 1.0
	v_mul_f32_e32 v172, v171, v170
	v_fma_f32 v173, -v169, v172, v171
	v_fmac_f32_e32 v172, v173, v170
	v_fma_f32 v169, -v169, v172, v171
	v_div_fmas_f32 v169, v169, v170, v172
	v_div_fixup_f32 v168, v169, v168, 1.0
	s_nop 0
	v_readlane_b32 s37, v168, 0
	v_readlane_b32 s41, v168, 1
	v_readlane_b32 s45, v168, 2
	v_readlane_b32 s49, v168, 3
	v_mul_f32_e32 v100, s37, v100
	v_mul_f32_e32 v105, s41, v105
	v_mul_f32_e32 v110, s45, v110
	v_mul_f32_e32 v115, s49, v115
	v_lshlrev_b32_e32 v103, 16, v103
	v_lshlrev_b32_e32 v108, 16, v108
	v_lshlrev_b32_e32 v113, 16, v113
	v_lshlrev_b32_e32 v118, 16, v118
	v_fma_f32 v100, v6, v100, v7
	v_fma_f32 v105, v6, v105, v7
	v_fma_f32 v110, v6, v110, v7
	v_fma_f32 v115, v6, v115, v7
	v_fmac_f32_e32 v100, s73, v101
	v_fmac_f32_e32 v105, s26, v106
	v_fmac_f32_e32 v110, s27, v111
	v_fmac_f32_e32 v115, s32, v116
	v_mul_f32_e32 v100, v100, v103
	v_mul_f32_e32 v105, v105, v108
	v_mul_f32_e32 v110, v110, v113
	v_mul_f32_e32 v115, v115, v118
	v_cvt_pk_bf16_f32 v169, v100, v100
	v_cvt_pk_bf16_f32 v175, v105, v105
	v_cvt_pk_bf16_f32 v242, v110, v110
	v_cvt_pk_bf16_f32 v248, v115, v115
	global_store_short v2, v169, s[28:29]
	s_add_u32 s28, s28, 0x1000
	s_addc_u32 s29, s29, 0
	global_store_short v2, v175, s[28:29]
	s_add_u32 s28, s28, 0x1000
	s_addc_u32 s29, s29, 0
	global_store_short v2, v242, s[28:29]
	s_add_u32 s28, s28, 0x1000
	s_addc_u32 s29, s29, 0
	global_store_short v2, v248, s[28:29]
	s_add_u32 s28, s28, 0x1000
	s_addc_u32 s29, s29, 0
	s_waitcnt vmcnt(8)
	ds_write_b128 v13, v[120:123] offset:0
	ds_write_b128 v13, v[124:127] offset:1024
	ds_write_b128 v13, v[128:131] offset:16384
	ds_write_b128 v13, v[132:135] offset:17408
	ds_write_b128 v15, v[136:139]
	v_readlane_b32 s69, v159, 0
	v_readlane_b32 s70, v159, 1
	v_readlane_b32 s71, v159, 2
	v_readlane_b32 s72, v159, 3
	v_readlane_b32 s73, v159, 4
	v_readlane_b32 s26, v159, 5
	v_readlane_b32 s27, v159, 6
	v_readlane_b32 s32, v159, 7
	global_load_dwordx4 v[120:123], v11, s[6:7]
	global_load_dwordx4 v[124:127], v11, s[6:7] offset:1024
	global_load_dwordx4 v[128:131], v11, s[8:9]
	global_load_dwordx4 v[132:135], v11, s[8:9] offset:1024
	global_load_dwordx4 v[136:139], v11, s[10:11]
	global_load_dword v159, v158, s[12:13]
	s_add_u32 s6, s6, 0x10000
	s_addc_u32 s7, s7, 0
	s_add_u32 s8, s8, 0x10000
	s_addc_u32 s9, s9, 0
	s_add_u32 s10, s10, 0x8000
	s_addc_u32 s11, s11, 0
	s_add_u32 s12, s12, 0x400
	s_addc_u32 s13, s13, 0
	s_waitcnt lgkmcnt(0)
	s_barrier
; __device__ __forceinline__ float bf2f(bf16 x) { return __uint_as_float(((unsigned)x) << 16); }
; __device__ __forceinline__ unsigned f2bf(float f) { return cvt_pk_bf16(f, 0.f) & 0xffffu; }
; __device__ __forceinline__ void rw_post(Frame& F) {
;     ...
;             for (int q = 0; q < 8; ++q) { const int row = rb0 + t0 + q;
;                 const float mean = wsum(y[q]) * (1.f / 64.f); const float dv = y[q] - mean; const float var = wsum(dv * dv) * (1.f / 64.f);
;                 const float yn = dv * (1.f / sqrtf(var + 64e-5f)) * g_ + b_;
;                 OB[(size_t)row * DH + col] = (bf16)f2bf((yn + rk[q] * vv[q]) * bf2f(gg[q])); }
	ds_read_b32 v80, v155 offset:0
	ds_read_b32 v81, v155 offset:16384
	ds_read_u16 v83, v157 offset:0
	ds_read_b32 v85, v155 offset:2048
	ds_read_b32 v86, v155 offset:18432
	ds_read_u16 v88, v157 offset:1024
	ds_read_b32 v90, v155 offset:4096
	ds_read_b32 v91, v155 offset:20480
	ds_read_u16 v93, v157 offset:2048
	ds_read_b32 v95, v155 offset:6144
	ds_read_b32 v96, v155 offset:22528
	ds_read_u16 v98, v157 offset:3072
	ds_read_b32 v100, v155 offset:8192
	ds_read_b32 v101, v155 offset:24576
	ds_read_u16 v103, v157 offset:4096
	ds_read_b32 v105, v155 offset:10240
	ds_read_b32 v106, v155 offset:26624
	ds_read_u16 v108, v157 offset:5120
	ds_read_b32 v110, v155 offset:12288
	ds_read_b32 v111, v155 offset:28672
	ds_read_u16 v113, v157 offset:6144
	ds_read_b32 v115, v155 offset:14336
	ds_read_b32 v116, v155 offset:30720
	ds_read_u16 v118, v157 offset:7168
	s_waitcnt lgkmcnt(12)
	v_add_f32_e32 v80, v80, v52
	v_add_f32_e32 v85, v85, v53
	v_add_f32_e32 v90, v90, v54
	v_add_f32_e32 v95, v95, v55
	v_add_f32_dpp v168, v80, v80 quad_perm:[1,0,3,2] row_mask:0xf bank_mask:0xf bound_ctrl:1
	v_add_f32_dpp v174, v85, v85 quad_perm:[1,0,3,2] row_mask:0xf bank_mask:0xf bound_ctrl:1
	v_add_f32_dpp v241, v90, v90 quad_perm:[1,0,3,2] row_mask:0xf bank_mask:0xf bound_ctrl:1
	v_add_f32_dpp v247, v95, v95 quad_perm:[1,0,3,2] row_mask:0xf bank_mask:0xf bound_ctrl:1
	v_add_f32_dpp v168, v168, v168 quad_perm:[2,3,0,1] row_mask:0xf bank_mask:0xf bound_ctrl:1
	v_add_f32_dpp v174, v174, v174 quad_perm:[2,3,0,1] row_mask:0xf bank_mask:0xf bound_ctrl:1
	v_add_f32_dpp v241, v241, v241 quad_perm:[2,3,0,1] row_mask:0xf bank_mask:0xf bound_ctrl:1
	v_add_f32_dpp v247, v247, v247 quad_perm:[2,3,0,1] row_mask:0xf bank_mask:0xf bound_ctrl:1
	v_add_f32_dpp v168, v168, v168 row_half_mirror row_mask:0xf bank_mask:0xf bound_ctrl:1
	v_add_f32_dpp v174, v174, v174 row_half_mirror row_mask:0xf bank_mask:0xf bound_ctrl:1
	v_add_f32_dpp v241, v241, v241 row_half_mirror row_mask:0xf bank_mask:0xf bound_ctrl:1
	v_add_f32_dpp v247, v247, v247 row_half_mirror row_mask:0xf bank_mask:0xf bound_ctrl:1
	v_add_f32_dpp v168, v168, v168 row_mirror row_mask:0xf bank_mask:0xf bound_ctrl:1
	v_add_f32_dpp v174, v174, v174 row_mirror row_mask:0xf bank_mask:0xf bound_ctrl:1
	v_add_f32_dpp v241, v241, v241 row_mirror row_mask:0xf bank_mask:0xf bound_ctrl:1
	v_add_f32_dpp v247, v247, v247 row_mirror row_mask:0xf bank_mask:0xf bound_ctrl:1
	v_readlane_b32 s36, v168, 16
	v_readlane_b32 s40, v174, 16
	v_readlane_b32 s44, v241, 16
	v_readlane_b32 s48, v247, 16
	v_readlane_b32 s37, v168, 48
	v_readlane_b32 s41, v174, 48
	v_readlane_b32 s45, v241, 48
	v_readlane_b32 s49, v247, 48
	v_readlane_b32 s38, v168, 0
	v_readlane_b32 s42, v174, 0
	v_readlane_b32 s46, v241, 0
	v_readlane_b32 s50, v247, 0
	v_readlane_b32 s39, v168, 32
	v_readlane_b32 s43, v174, 32
	v_readlane_b32 s47, v241, 32
	v_readlane_b32 s51, v247, 32
	v_mov_b32_e32 v168, s36
	v_mov_b32_e32 v174, s40
	v_mov_b32_e32 v241, s44
	v_mov_b32_e32 v247, s48
	v_mov_b32_e32 v169, s37
	v_mov_b32_e32 v175, s41
	v_mov_b32_e32 v242, s45
	v_mov_b32_e32 v248, s49
	v_add_f32_e32 v168, s38, v168
	v_add_f32_e32 v174, s42, v174
	v_add_f32_e32 v241, s46, v241
	v_add_f32_e32 v247, s50, v247
	v_add_f32_e32 v169, s39, v169
	v_add_f32_e32 v175, s43, v175
	v_add_f32_e32 v242, s47, v242
	v_add_f32_e32 v248, s51, v248
	v_add_f32_e32 v168, v168, v169
	v_add_f32_e32 v174, v174, v175
	v_add_f32_e32 v241, v241, v242
	v_add_f32_e32 v247, v247, v248
	v_fmamk_f32 v80, v168, 0xbc800000, v80
	v_fmamk_f32 v85, v174, 0xbc800000, v85
	v_fmamk_f32 v90, v241, 0xbc800000, v90
	v_fmamk_f32 v95, v247, 0xbc800000, v95
	v_mul_f32_e32 v168, v80, v80
	v_mul_f32_e32 v174, v85, v85
	v_mul_f32_e32 v241, v90, v90
	v_mul_f32_e32 v247, v95, v95
	v_mov_b32_dpp v168, v168 quad_perm:[1,0,3,2] row_mask:0xf bank_mask:0xf bound_ctrl:1
	v_mov_b32_dpp v174, v174 quad_perm:[1,0,3,2] row_mask:0xf bank_mask:0xf bound_ctrl:1
	v_mov_b32_dpp v241, v241 quad_perm:[1,0,3,2] row_mask:0xf bank_mask:0xf bound_ctrl:1
	v_mov_b32_dpp v247, v247 quad_perm:[1,0,3,2] row_mask:0xf bank_mask:0xf bound_ctrl:1
	v_fmac_f32_e32 v168, v80, v80
	v_fmac_f32_e32 v174, v85, v85
	v_fmac_f32_e32 v241, v90, v90
	v_fmac_f32_e32 v247, v95, v95
	v_add_f32_dpp v168, v168, v168 quad_perm:[2,3,0,1] row_mask:0xf bank_mask:0xf bound_ctrl:1
	v_add_f32_dpp v174, v174, v174 quad_perm:[2,3,0,1] row_mask:0xf bank_mask:0xf bound_ctrl:1
	v_add_f32_dpp v241, v241, v241 quad_perm:[2,3,0,1] row_mask:0xf bank_mask:0xf bound_ctrl:1
	v_add_f32_dpp v247, v247, v247 quad_perm:[2,3,0,1] row_mask:0xf bank_mask:0xf bound_ctrl:1
	v_add_f32_dpp v168, v168, v168 row_half_mirror row_mask:0xf bank_mask:0xf bound_ctrl:1
	v_add_f32_dpp v174, v174, v174 row_half_mirror row_mask:0xf bank_mask:0xf bound_ctrl:1
	v_add_f32_dpp v241, v241, v241 row_half_mirror row_mask:0xf bank_mask:0xf bound_ctrl:1
	v_add_f32_dpp v247, v247, v247 row_half_mirror row_mask:0xf bank_mask:0xf bound_ctrl:1
	v_add_f32_dpp v168, v168, v168 row_mirror row_mask:0xf bank_mask:0xf bound_ctrl:1
	v_add_f32_dpp v174, v174, v174 row_mirror row_mask:0xf bank_mask:0xf bound_ctrl:1
	v_add_f32_dpp v241, v241, v241 row_mirror row_mask:0xf bank_mask:0xf bound_ctrl:1
	v_add_f32_dpp v247, v247, v247 row_mirror row_mask:0xf bank_mask:0xf bound_ctrl:1
	v_readlane_b32 s36, v168, 16
	v_readlane_b32 s40, v174, 16
	v_readlane_b32 s44, v241, 16
	v_readlane_b32 s48, v247, 16
	v_readlane_b32 s37, v168, 48
	v_readlane_b32 s41, v174, 48
	v_readlane_b32 s45, v241, 48
	v_readlane_b32 s49, v247, 48
	v_readlane_b32 s38, v168, 0
	v_readlane_b32 s42, v174, 0
	v_readlane_b32 s46, v241, 0
	v_readlane_b32 s50, v247, 0
	v_readlane_b32 s39, v168, 32
; __device__ __forceinline__ float bf2f(bf16 x) { return __uint_as_float(((unsigned)x) << 16); }
; __device__ __forceinline__ unsigned f2bf(float f) { return cvt_pk_bf16(f, 0.f) & 0xffffu; }
; __device__ __forceinline__ void rw_post(Frame& F) {
;     ...
;             for (int q = 0; q < 8; ++q) { const int row = rb0 + t0 + q;
;                 const float mean = wsum(y[q]) * (1.f / 64.f); const float dv = y[q] - mean; const float var = wsum(dv * dv) * (1.f / 64.f);
;                 const float yn = dv * (1.f / sqrtf(var + 64e-5f)) * g_ + b_;
;                 OB[(size_t)row * DH + col] = (bf16)f2bf((yn + rk[q] * vv[q]) * bf2f(gg[q])); }
	v_readlane_b32 s43, v174, 32
	v_readlane_b32 s47, v241, 32
	v_readlane_b32 s51, v247, 32
	v_mov_b32_e32 v168, s36
	v_mov_b32_e32 v174, s40
	v_mov_b32_e32 v241, s44
	v_mov_b32_e32 v247, s48
	v_mov_b32_e32 v169, s37
	v_mov_b32_e32 v175, s41
	v_mov_b32_e32 v242, s45
	v_mov_b32_e32 v248, s49
	v_add_f32_e32 v168, s38, v168
	v_add_f32_e32 v174, s42, v174
	v_add_f32_e32 v241, s46, v241
	v_add_f32_e32 v247, s50, v247
	v_add_f32_e32 v169, s39, v169
	v_add_f32_e32 v175, s43, v175
	v_add_f32_e32 v242, s47, v242
	v_add_f32_e32 v248, s51, v248
	v_add_f32_e32 v168, v168, v169
	v_add_f32_e32 v174, v174, v175
	v_add_f32_e32 v241, v241, v242
	v_add_f32_e32 v247, v247, v248
	v_fmamk_f32 v168, v168, 0x3c800000, v9
	v_fmamk_f32 v174, v174, 0x3c800000, v9
	v_fmamk_f32 v241, v241, 0x3c800000, v9
	v_fmamk_f32 v247, v247, 0x3c800000, v9
	v_readfirstlane_b32 s40, v174
	v_readfirstlane_b32 s44, v241
	v_readfirstlane_b32 s48, v247
	v_writelane_b32 v168, s40, 1
	v_writelane_b32 v168, s44, 2
	v_writelane_b32 v168, s48, 3
	v_mul_f32_e32 v169, 0x4f800000, v168
	v_cmp_gt_f32_e64 s[52:53], s68, v168
	v_mov_b32_e32 v170, v168
	s_nop 1
	v_cndmask_b32_e64 v168, v170, v169, s[52:53]
	v_sqrt_f32_e32 v169, v168
	s_nop 0
	v_add_u32_e32 v170, -1, v169
	v_fma_f32 v171, -v170, v169, v168
	v_cmp_ge_f32_e64 s[60:61], 0, v171
	v_add_u32_e32 v171, 1, v169
	s_nop 1
	v_cndmask_b32_e64 v170, v169, v170, s[60:61]
	v_fma_f32 v169, -v171, v169, v168
	v_cmp_lt_f32_e64 s[60:61], 0, v169
	s_nop 1
	v_cndmask_b32_e64 v169, v170, v171, s[60:61]
	v_mul_f32_e32 v170, 0x37800000, v169
	v_cndmask_b32_e64 v169, v169, v170, s[52:53]
	v_cmp_class_f32_e64 s[60:61], v168, v8
	s_nop 1
	v_cndmask_b32_e64 v168, v169, v168, s[60:61]
	v_div_scale_f32 v169, s[60:61], v168, v168, 1.0
	v_rcp_f32_e32 v170, v169
	s_nop 0
	v_fma_f32 v171, -v169, v170, 1.0
	v_fmac_f32_e32 v170, v171, v170
	v_div_scale_f32 v171, vcc, 1.0, v168, 1.0
	v_mul_f32_e32 v172, v171, v170
	v_fma_f32 v173, -v169, v172, v171
	v_fmac_f32_e32 v172, v173, v170
	v_fma_f32 v169, -v169, v172, v171
	v_div_fmas_f32 v169, v169, v170, v172
	v_div_fixup_f32 v168, v169, v168, 1.0
	s_nop 0
	v_readlane_b32 s37, v168, 0
	v_readlane_b32 s41, v168, 1
	v_readlane_b32 s45, v168, 2
	v_readlane_b32 s49, v168, 3
	v_mul_f32_e32 v80, s37, v80
	v_mul_f32_e32 v85, s41, v85
	v_mul_f32_e32 v90, s45, v90
	v_mul_f32_e32 v95, s49, v95
	v_lshlrev_b32_e32 v83, 16, v83
	v_lshlrev_b32_e32 v88, 16, v88
	v_lshlrev_b32_e32 v93, 16, v93
	v_lshlrev_b32_e32 v98, 16, v98
	v_fma_f32 v80, v6, v80, v7
	v_fma_f32 v85, v6, v85, v7
	v_fma_f32 v90, v6, v90, v7
	v_fma_f32 v95, v6, v95, v7
	v_fmac_f32_e32 v80, s69, v81
	v_fmac_f32_e32 v85, s70, v86
	v_fmac_f32_e32 v90, s71, v91
	v_fmac_f32_e32 v95, s72, v96
	v_mul_f32_e32 v80, v80, v83
	v_mul_f32_e32 v85, v85, v88
	v_mul_f32_e32 v90, v90, v93
	v_mul_f32_e32 v95, v95, v98
	v_cvt_pk_bf16_f32 v169, v80, v80
	v_cvt_pk_bf16_f32 v175, v85, v85
	v_cvt_pk_bf16_f32 v242, v90, v90
	v_cvt_pk_bf16_f32 v248, v95, v95
	global_store_short v2, v169, s[28:29]
	s_add_u32 s28, s28, 0x1000
	s_addc_u32 s29, s29, 0
	global_store_short v2, v175, s[28:29]
	s_add_u32 s28, s28, 0x1000
	s_addc_u32 s29, s29, 0
	global_store_short v2, v242, s[28:29]
	s_add_u32 s28, s28, 0x1000
	s_addc_u32 s29, s29, 0
	global_store_short v2, v248, s[28:29]
	s_add_u32 s28, s28, 0x1000
	s_addc_u32 s29, s29, 0
	s_waitcnt lgkmcnt(0)
	v_add_f32_e32 v100, v100, v68
	v_add_f32_e32 v105, v105, v69
	v_add_f32_e32 v110, v110, v70
	v_add_f32_e32 v115, v115, v71
	v_add_f32_dpp v168, v100, v100 quad_perm:[1,0,3,2] row_mask:0xf bank_mask:0xf bound_ctrl:1
	v_add_f32_dpp v174, v105, v105 quad_perm:[1,0,3,2] row_mask:0xf bank_mask:0xf bound_ctrl:1
	v_add_f32_dpp v241, v110, v110 quad_perm:[1,0,3,2] row_mask:0xf bank_mask:0xf bound_ctrl:1
	v_add_f32_dpp v247, v115, v115 quad_perm:[1,0,3,2] row_mask:0xf bank_mask:0xf bound_ctrl:1
	v_add_f32_dpp v168, v168, v168 quad_perm:[2,3,0,1] row_mask:0xf bank_mask:0xf bound_ctrl:1
	v_add_f32_dpp v174, v174, v174 quad_perm:[2,3,0,1] row_mask:0xf bank_mask:0xf bound_ctrl:1
	v_add_f32_dpp v241, v241, v241 quad_perm:[2,3,0,1] row_mask:0xf bank_mask:0xf bound_ctrl:1
	v_add_f32_dpp v247, v247, v247 quad_perm:[2,3,0,1] row_mask:0xf bank_mask:0xf bound_ctrl:1
	v_add_f32_dpp v168, v168, v168 row_half_mirror row_mask:0xf bank_mask:0xf bound_ctrl:1
	v_add_f32_dpp v174, v174, v174 row_half_mirror row_mask:0xf bank_mask:0xf bound_ctrl:1
	v_add_f32_dpp v241, v241, v241 row_half_mirror row_mask:0xf bank_mask:0xf bound_ctrl:1
	v_add_f32_dpp v247, v247, v247 row_half_mirror row_mask:0xf bank_mask:0xf bound_ctrl:1
	v_add_f32_dpp v168, v168, v168 row_mirror row_mask:0xf bank_mask:0xf bound_ctrl:1
	v_add_f32_dpp v174, v174, v174 row_mirror row_mask:0xf bank_mask:0xf bound_ctrl:1
	v_add_f32_dpp v241, v241, v241 row_mirror row_mask:0xf bank_mask:0xf bound_ctrl:1
	v_add_f32_dpp v247, v247, v247 row_mirror row_mask:0xf bank_mask:0xf bound_ctrl:1
	v_readlane_b32 s36, v168, 16
	v_readlane_b32 s40, v174, 16
	v_readlane_b32 s44, v241, 16
	v_readlane_b32 s48, v247, 16
	v_readlane_b32 s37, v168, 48
	v_readlane_b32 s41, v174, 48
	v_readlane_b32 s45, v241, 48
	v_readlane_b32 s49, v247, 48
	v_readlane_b32 s38, v168, 0
	v_readlane_b32 s42, v174, 0
	v_readlane_b32 s46, v241, 0
	v_readlane_b32 s50, v247, 0
	v_readlane_b32 s39, v168, 32
	v_readlane_b32 s43, v174, 32
	v_readlane_b32 s47, v241, 32
	v_readlane_b32 s51, v247, 32
	v_mov_b32_e32 v168, s36
	v_mov_b32_e32 v174, s40
	v_mov_b32_e32 v241, s44
	v_mov_b32_e32 v247, s48
	v_mov_b32_e32 v169, s37
	v_mov_b32_e32 v175, s41
	v_mov_b32_e32 v242, s45
	v_mov_b32_e32 v248, s49
	v_add_f32_e32 v168, s38, v168
	v_add_f32_e32 v174, s42, v174
	v_add_f32_e32 v241, s46, v241
; __device__ __forceinline__ float bf2f(bf16 x) { return __uint_as_float(((unsigned)x) << 16); }
; __device__ __forceinline__ unsigned f2bf(float f) { return cvt_pk_bf16(f, 0.f) & 0xffffu; }
; #define POST_LD(Y_, V_, G_, R_, C_, t) do { _Pragma("unroll") for (int q = 0; q < 8; ++q) { const size_t o_ = (size_t)((t) + q) * DH; Y_[q] = yp[o_]; V_[q] = vp[o_]; G_[q] = gp[o_]; R_[q] = rp[((t) + q) * 32]; C_[q] = cp[o_]; } } while (0)
; __device__ __forceinline__ void rw_post(Frame& F) {
;     ...
;         POST_LD(y, vv, gg, rk, cc, 0);
;         for (int t0 = 0; t0 < 64; t0 += 8) {
;             float ny[8], nv[8], nr[8], nc[8]; bf16 ng[8];
;             const int tn = t0 + 8 < 64 ? t0 + 8 : t0;
;             POST_LD(ny, nv, ng, nr, nc, tn);
;     ...
;             for (int q = 0; q < 8; ++q) { const int row = rb0 + t0 + q;
;                 const float mean = wsum(y[q]) * (1.f / 64.f); const float dv = y[q] - mean; const float var = wsum(dv * dv) * (1.f / 64.f);
;                 const float yn = dv * (1.f / sqrtf(var + 64e-5f)) * g_ + b_;
;                 OB[(size_t)row * DH + col] = (bf16)f2bf((yn + rk[q] * vv[q]) * bf2f(gg[q])); }
	v_add_f32_e32 v247, s50, v247
	v_add_f32_e32 v169, s39, v169
	v_add_f32_e32 v175, s43, v175
	v_add_f32_e32 v242, s47, v242
	v_add_f32_e32 v248, s51, v248
	v_add_f32_e32 v168, v168, v169
	v_add_f32_e32 v174, v174, v175
	v_add_f32_e32 v241, v241, v242
	v_add_f32_e32 v247, v247, v248
	v_fmamk_f32 v100, v168, 0xbc800000, v100
	v_fmamk_f32 v105, v174, 0xbc800000, v105
	v_fmamk_f32 v110, v241, 0xbc800000, v110
	v_fmamk_f32 v115, v247, 0xbc800000, v115
	v_mul_f32_e32 v168, v100, v100
	v_mul_f32_e32 v174, v105, v105
	v_mul_f32_e32 v241, v110, v110
	v_mul_f32_e32 v247, v115, v115
	v_mov_b32_dpp v168, v168 quad_perm:[1,0,3,2] row_mask:0xf bank_mask:0xf bound_ctrl:1
	v_mov_b32_dpp v174, v174 quad_perm:[1,0,3,2] row_mask:0xf bank_mask:0xf bound_ctrl:1
	v_mov_b32_dpp v241, v241 quad_perm:[1,0,3,2] row_mask:0xf bank_mask:0xf bound_ctrl:1
	v_mov_b32_dpp v247, v247 quad_perm:[1,0,3,2] row_mask:0xf bank_mask:0xf bound_ctrl:1
	v_fmac_f32_e32 v168, v100, v100
	v_fmac_f32_e32 v174, v105, v105
	v_fmac_f32_e32 v241, v110, v110
	v_fmac_f32_e32 v247, v115, v115
	v_add_f32_dpp v168, v168, v168 quad_perm:[2,3,0,1] row_mask:0xf bank_mask:0xf bound_ctrl:1
	v_add_f32_dpp v174, v174, v174 quad_perm:[2,3,0,1] row_mask:0xf bank_mask:0xf bound_ctrl:1
	v_add_f32_dpp v241, v241, v241 quad_perm:[2,3,0,1] row_mask:0xf bank_mask:0xf bound_ctrl:1
	v_add_f32_dpp v247, v247, v247 quad_perm:[2,3,0,1] row_mask:0xf bank_mask:0xf bound_ctrl:1
	v_add_f32_dpp v168, v168, v168 row_half_mirror row_mask:0xf bank_mask:0xf bound_ctrl:1
	v_add_f32_dpp v174, v174, v174 row_half_mirror row_mask:0xf bank_mask:0xf bound_ctrl:1
	v_add_f32_dpp v241, v241, v241 row_half_mirror row_mask:0xf bank_mask:0xf bound_ctrl:1
	v_add_f32_dpp v247, v247, v247 row_half_mirror row_mask:0xf bank_mask:0xf bound_ctrl:1
	v_add_f32_dpp v168, v168, v168 row_mirror row_mask:0xf bank_mask:0xf bound_ctrl:1
	v_add_f32_dpp v174, v174, v174 row_mirror row_mask:0xf bank_mask:0xf bound_ctrl:1
	v_add_f32_dpp v241, v241, v241 row_mirror row_mask:0xf bank_mask:0xf bound_ctrl:1
	v_add_f32_dpp v247, v247, v247 row_mirror row_mask:0xf bank_mask:0xf bound_ctrl:1
	v_readlane_b32 s36, v168, 16
	v_readlane_b32 s40, v174, 16
	v_readlane_b32 s44, v241, 16
	v_readlane_b32 s48, v247, 16
	v_readlane_b32 s37, v168, 48
	v_readlane_b32 s41, v174, 48
	v_readlane_b32 s45, v241, 48
	v_readlane_b32 s49, v247, 48
	v_readlane_b32 s38, v168, 0
	v_readlane_b32 s42, v174, 0
	v_readlane_b32 s46, v241, 0
	v_readlane_b32 s50, v247, 0
	v_readlane_b32 s39, v168, 32
	v_readlane_b32 s43, v174, 32
	v_readlane_b32 s47, v241, 32
	v_readlane_b32 s51, v247, 32
	v_mov_b32_e32 v168, s36
	v_mov_b32_e32 v174, s40
	v_mov_b32_e32 v241, s44
	v_mov_b32_e32 v247, s48
	v_mov_b32_e32 v169, s37
	v_mov_b32_e32 v175, s41
	v_mov_b32_e32 v242, s45
	v_mov_b32_e32 v248, s49
	v_add_f32_e32 v168, s38, v168
	v_add_f32_e32 v174, s42, v174
	v_add_f32_e32 v241, s46, v241
	v_add_f32_e32 v247, s50, v247
	v_add_f32_e32 v169, s39, v169
	v_add_f32_e32 v175, s43, v175
	v_add_f32_e32 v242, s47, v242
	v_add_f32_e32 v248, s51, v248
	v_add_f32_e32 v168, v168, v169
	v_add_f32_e32 v174, v174, v175
	v_add_f32_e32 v241, v241, v242
	v_add_f32_e32 v247, v247, v248
	v_fmamk_f32 v168, v168, 0x3c800000, v9
	v_fmamk_f32 v174, v174, 0x3c800000, v9
	v_fmamk_f32 v241, v241, 0x3c800000, v9
	v_fmamk_f32 v247, v247, 0x3c800000, v9
	v_readfirstlane_b32 s40, v174
	v_readfirstlane_b32 s44, v241
	v_readfirstlane_b32 s48, v247
	v_writelane_b32 v168, s40, 1
	v_writelane_b32 v168, s44, 2
	v_writelane_b32 v168, s48, 3
	v_mul_f32_e32 v169, 0x4f800000, v168
	v_cmp_gt_f32_e64 s[52:53], s68, v168
	v_mov_b32_e32 v170, v168
	s_nop 1
	v_cndmask_b32_e64 v168, v170, v169, s[52:53]
	v_sqrt_f32_e32 v169, v168
	s_nop 0
	v_add_u32_e32 v170, -1, v169
	v_fma_f32 v171, -v170, v169, v168
	v_cmp_ge_f32_e64 s[60:61], 0, v171
	v_add_u32_e32 v171, 1, v169
	s_nop 1
	v_cndmask_b32_e64 v170, v169, v170, s[60:61]
	v_fma_f32 v169, -v171, v169, v168
	v_cmp_lt_f32_e64 s[60:61], 0, v169
	s_nop 1
	v_cndmask_b32_e64 v169, v170, v171, s[60:61]
	v_mul_f32_e32 v170, 0x37800000, v169
	v_cndmask_b32_e64 v169, v169, v170, s[52:53]
	v_cmp_class_f32_e64 s[60:61], v168, v8
	s_nop 1
	v_cndmask_b32_e64 v168, v169, v168, s[60:61]
	v_div_scale_f32 v169, s[60:61], v168, v168, 1.0
	v_rcp_f32_e32 v170, v169
	s_nop 0
	v_fma_f32 v171, -v169, v170, 1.0
	v_fmac_f32_e32 v170, v171, v170
	v_div_scale_f32 v171, vcc, 1.0, v168, 1.0
	v_mul_f32_e32 v172, v171, v170
	v_fma_f32 v173, -v169, v172, v171
	v_fmac_f32_e32 v172, v173, v170
	v_fma_f32 v169, -v169, v172, v171
	v_div_fmas_f32 v169, v169, v170, v172
	v_div_fixup_f32 v168, v169, v168, 1.0
	s_nop 0
	v_readlane_b32 s37, v168, 0
	v_readlane_b32 s41, v168, 1
	v_readlane_b32 s45, v168, 2
	v_readlane_b32 s49, v168, 3
	v_mul_f32_e32 v100, s37, v100
	v_mul_f32_e32 v105, s41, v105
	v_mul_f32_e32 v110, s45, v110
	v_mul_f32_e32 v115, s49, v115
	v_lshlrev_b32_e32 v103, 16, v103
	v_lshlrev_b32_e32 v108, 16, v108
	v_lshlrev_b32_e32 v113, 16, v113
	v_lshlrev_b32_e32 v118, 16, v118
	v_fma_f32 v100, v6, v100, v7
	v_fma_f32 v105, v6, v105, v7
	v_fma_f32 v110, v6, v110, v7
	v_fma_f32 v115, v6, v115, v7
	v_fmac_f32_e32 v100, s73, v101
	v_fmac_f32_e32 v105, s26, v106
	v_fmac_f32_e32 v110, s27, v111
	v_fmac_f32_e32 v115, s32, v116
	v_mul_f32_e32 v100, v100, v103
	v_mul_f32_e32 v105, v105, v108
	v_mul_f32_e32 v110, v110, v113
	v_mul_f32_e32 v115, v115, v118
	v_cvt_pk_bf16_f32 v169, v100, v100
	v_cvt_pk_bf16_f32 v175, v105, v105
	v_cvt_pk_bf16_f32 v242, v110, v110
	v_cvt_pk_bf16_f32 v248, v115, v115
	global_store_short v2, v169, s[28:29]
	s_add_u32 s28, s28, 0x1000
	s_addc_u32 s29, s29, 0
	global_store_short v2, v175, s[28:29]
	s_add_u32 s28, s28, 0x1000
	s_addc_u32 s29, s29, 0
	global_store_short v2, v242, s[28:29]
	s_add_u32 s28, s28, 0x1000
	s_addc_u32 s29, s29, 0
	global_store_short v2, v248, s[28:29]
	s_add_u32 s28, s28, 0x1000
	s_addc_u32 s29, s29, 0
	s_waitcnt vmcnt(8)
	ds_write_b128 v12, v[120:123] offset:0
	ds_write_b128 v12, v[124:127] offset:1024
	ds_write_b128 v12, v[128:131] offset:16384
	ds_write_b128 v12, v[132:135] offset:17408
	ds_write_b128 v14, v[136:139]
	v_readlane_b32 s69, v159, 0
	v_readlane_b32 s70, v159, 1
	v_readlane_b32 s71, v159, 2
	v_readlane_b32 s72, v159, 3
	v_readlane_b32 s73, v159, 4
	v_readlane_b32 s26, v159, 5
	v_readlane_b32 s27, v159, 6
	v_readlane_b32 s32, v159, 7
	global_load_dwordx4 v[120:123], v11, s[6:7]
	global_load_dwordx4 v[124:127], v11, s[6:7] offset:1024
	global_load_dwordx4 v[128:131], v11, s[8:9]
	global_load_dwordx4 v[132:135], v11, s[8:9] offset:1024
	global_load_dwordx4 v[136:139], v11, s[10:11]
	global_load_dword v159, v158, s[12:13]
	s_add_u32 s6, s6, 0x10000
	s_addc_u32 s7, s7, 0
	s_add_u32 s8, s8, 0x10000
	s_addc_u32 s9, s9, 0
	s_add_u32 s10, s10, 0x8000
	s_addc_u32 s11, s11, 0
	s_add_u32 s12, s12, 0x400
	s_addc_u32 s13, s13, 0
	s_waitcnt lgkmcnt(0)
	s_barrier
; __device__ __forceinline__ float bf2f(bf16 x) { return __uint_as_float(((unsigned)x) << 16); }
; __device__ __forceinline__ unsigned f2bf(float f) { return cvt_pk_bf16(f, 0.f) & 0xffffu; }
; __device__ __forceinline__ void rw_post(Frame& F) {
;     ...
;             for (int q = 0; q < 8; ++q) { const int row = rb0 + t0 + q;
;                 const float mean = wsum(y[q]) * (1.f / 64.f); const float dv = y[q] - mean; const float var = wsum(dv * dv) * (1.f / 64.f);
;                 const float yn = dv * (1.f / sqrtf(var + 64e-5f)) * g_ + b_;
;                 OB[(size_t)row * DH + col] = (bf16)f2bf((yn + rk[q] * vv[q]) * bf2f(gg[q])); }
	ds_read_b32 v80, v154 offset:0
	ds_read_b32 v81, v154 offset:16384
	ds_read_u16 v83, v156 offset:0
	ds_read_b32 v85, v154 offset:2048
	ds_read_b32 v86, v154 offset:18432
	ds_read_u16 v88, v156 offset:1024
	ds_read_b32 v90, v154 offset:4096
	ds_read_b32 v91, v154 offset:20480
	ds_read_u16 v93, v156 offset:2048
	ds_read_b32 v95, v154 offset:6144
	ds_read_b32 v96, v154 offset:22528
	ds_read_u16 v98, v156 offset:3072
	ds_read_b32 v100, v154 offset:8192
	ds_read_b32 v101, v154 offset:24576
	ds_read_u16 v103, v156 offset:4096
	ds_read_b32 v105, v154 offset:10240
	ds_read_b32 v106, v154 offset:26624
	ds_read_u16 v108, v156 offset:5120
	ds_read_b32 v110, v154 offset:12288
	ds_read_b32 v111, v154 offset:28672
	ds_read_u16 v113, v156 offset:6144
	ds_read_b32 v115, v154 offset:14336
	ds_read_b32 v116, v154 offset:30720
	ds_read_u16 v118, v156 offset:7168
	s_waitcnt lgkmcnt(12)
	v_add_f32_e32 v80, v80, v56
	v_add_f32_e32 v85, v85, v57
	v_add_f32_e32 v90, v90, v58
	v_add_f32_e32 v95, v95, v59
	v_add_f32_dpp v168, v80, v80 quad_perm:[1,0,3,2] row_mask:0xf bank_mask:0xf bound_ctrl:1
	v_add_f32_dpp v174, v85, v85 quad_perm:[1,0,3,2] row_mask:0xf bank_mask:0xf bound_ctrl:1
	v_add_f32_dpp v241, v90, v90 quad_perm:[1,0,3,2] row_mask:0xf bank_mask:0xf bound_ctrl:1
	v_add_f32_dpp v247, v95, v95 quad_perm:[1,0,3,2] row_mask:0xf bank_mask:0xf bound_ctrl:1
	v_add_f32_dpp v168, v168, v168 quad_perm:[2,3,0,1] row_mask:0xf bank_mask:0xf bound_ctrl:1
	v_add_f32_dpp v174, v174, v174 quad_perm:[2,3,0,1] row_mask:0xf bank_mask:0xf bound_ctrl:1
	v_add_f32_dpp v241, v241, v241 quad_perm:[2,3,0,1] row_mask:0xf bank_mask:0xf bound_ctrl:1
	v_add_f32_dpp v247, v247, v247 quad_perm:[2,3,0,1] row_mask:0xf bank_mask:0xf bound_ctrl:1
	v_add_f32_dpp v168, v168, v168 row_half_mirror row_mask:0xf bank_mask:0xf bound_ctrl:1
	v_add_f32_dpp v174, v174, v174 row_half_mirror row_mask:0xf bank_mask:0xf bound_ctrl:1
	v_add_f32_dpp v241, v241, v241 row_half_mirror row_mask:0xf bank_mask:0xf bound_ctrl:1
	v_add_f32_dpp v247, v247, v247 row_half_mirror row_mask:0xf bank_mask:0xf bound_ctrl:1
	v_add_f32_dpp v168, v168, v168 row_mirror row_mask:0xf bank_mask:0xf bound_ctrl:1
	v_add_f32_dpp v174, v174, v174 row_mirror row_mask:0xf bank_mask:0xf bound_ctrl:1
	v_add_f32_dpp v241, v241, v241 row_mirror row_mask:0xf bank_mask:0xf bound_ctrl:1
	v_add_f32_dpp v247, v247, v247 row_mirror row_mask:0xf bank_mask:0xf bound_ctrl:1
	v_readlane_b32 s36, v168, 16
	v_readlane_b32 s40, v174, 16
	v_readlane_b32 s44, v241, 16
	v_readlane_b32 s48, v247, 16
	v_readlane_b32 s37, v168, 48
	v_readlane_b32 s41, v174, 48
	v_readlane_b32 s45, v241, 48
	v_readlane_b32 s49, v247, 48
	v_readlane_b32 s38, v168, 0
	v_readlane_b32 s42, v174, 0
	v_readlane_b32 s46, v241, 0
	v_readlane_b32 s50, v247, 0
	v_readlane_b32 s39, v168, 32
	v_readlane_b32 s43, v174, 32
	v_readlane_b32 s47, v241, 32
	v_readlane_b32 s51, v247, 32
	v_mov_b32_e32 v168, s36
	v_mov_b32_e32 v174, s40
	v_mov_b32_e32 v241, s44
	v_mov_b32_e32 v247, s48
	v_mov_b32_e32 v169, s37
	v_mov_b32_e32 v175, s41
	v_mov_b32_e32 v242, s45
	v_mov_b32_e32 v248, s49
	v_add_f32_e32 v168, s38, v168
	v_add_f32_e32 v174, s42, v174
	v_add_f32_e32 v241, s46, v241
	v_add_f32_e32 v247, s50, v247
	v_add_f32_e32 v169, s39, v169
	v_add_f32_e32 v175, s43, v175
	v_add_f32_e32 v242, s47, v242
	v_add_f32_e32 v248, s51, v248
	v_add_f32_e32 v168, v168, v169
	v_add_f32_e32 v174, v174, v175
	v_add_f32_e32 v241, v241, v242
	v_add_f32_e32 v247, v247, v248
	v_fmamk_f32 v80, v168, 0xbc800000, v80
	v_fmamk_f32 v85, v174, 0xbc800000, v85
	v_fmamk_f32 v90, v241, 0xbc800000, v90
	v_fmamk_f32 v95, v247, 0xbc800000, v95
	v_mul_f32_e32 v168, v80, v80
	v_mul_f32_e32 v174, v85, v85
	v_mul_f32_e32 v241, v90, v90
	v_mul_f32_e32 v247, v95, v95
	v_mov_b32_dpp v168, v168 quad_perm:[1,0,3,2] row_mask:0xf bank_mask:0xf bound_ctrl:1
	v_mov_b32_dpp v174, v174 quad_perm:[1,0,3,2] row_mask:0xf bank_mask:0xf bound_ctrl:1
	v_mov_b32_dpp v241, v241 quad_perm:[1,0,3,2] row_mask:0xf bank_mask:0xf bound_ctrl:1
	v_mov_b32_dpp v247, v247 quad_perm:[1,0,3,2] row_mask:0xf bank_mask:0xf bound_ctrl:1
	v_fmac_f32_e32 v168, v80, v80
	v_fmac_f32_e32 v174, v85, v85
	v_fmac_f32_e32 v241, v90, v90
	v_fmac_f32_e32 v247, v95, v95
	v_add_f32_dpp v168, v168, v168 quad_perm:[2,3,0,1] row_mask:0xf bank_mask:0xf bound_ctrl:1
	v_add_f32_dpp v174, v174, v174 quad_perm:[2,3,0,1] row_mask:0xf bank_mask:0xf bound_ctrl:1
	v_add_f32_dpp v241, v241, v241 quad_perm:[2,3,0,1] row_mask:0xf bank_mask:0xf bound_ctrl:1
	v_add_f32_dpp v247, v247, v247 quad_perm:[2,3,0,1] row_mask:0xf bank_mask:0xf bound_ctrl:1
	v_add_f32_dpp v168, v168, v168 row_half_mirror row_mask:0xf bank_mask:0xf bound_ctrl:1
	v_add_f32_dpp v174, v174, v174 row_half_mirror row_mask:0xf bank_mask:0xf bound_ctrl:1
	v_add_f32_dpp v241, v241, v241 row_half_mirror row_mask:0xf bank_mask:0xf bound_ctrl:1
	v_add_f32_dpp v247, v247, v247 row_half_mirror row_mask:0xf bank_mask:0xf bound_ctrl:1
	v_add_f32_dpp v168, v168, v168 row_mirror row_mask:0xf bank_mask:0xf bound_ctrl:1
	v_add_f32_dpp v174, v174, v174 row_mirror row_mask:0xf bank_mask:0xf bound_ctrl:1
	v_add_f32_dpp v241, v241, v241 row_mirror row_mask:0xf bank_mask:0xf bound_ctrl:1
	v_add_f32_dpp v247, v247, v247 row_mirror row_mask:0xf bank_mask:0xf bound_ctrl:1
	v_readlane_b32 s36, v168, 16
	v_readlane_b32 s40, v174, 16
	v_readlane_b32 s44, v241, 16
	v_readlane_b32 s48, v247, 16
	v_readlane_b32 s37, v168, 48
	v_readlane_b32 s41, v174, 48
	v_readlane_b32 s45, v241, 48
	v_readlane_b32 s49, v247, 48
	v_readlane_b32 s38, v168, 0
	v_readlane_b32 s42, v174, 0
	v_readlane_b32 s46, v241, 0
	v_readlane_b32 s50, v247, 0
	v_readlane_b32 s39, v168, 32
; __device__ __forceinline__ float bf2f(bf16 x) { return __uint_as_float(((unsigned)x) << 16); }
; __device__ __forceinline__ unsigned f2bf(float f) { return cvt_pk_bf16(f, 0.f) & 0xffffu; }
; __device__ __forceinline__ void rw_post(Frame& F) {
;     ...
;             for (int q = 0; q < 8; ++q) { const int row = rb0 + t0 + q;
;                 const float mean = wsum(y[q]) * (1.f / 64.f); const float dv = y[q] - mean; const float var = wsum(dv * dv) * (1.f / 64.f);
;                 const float yn = dv * (1.f / sqrtf(var + 64e-5f)) * g_ + b_;
;                 OB[(size_t)row * DH + col] = (bf16)f2bf((yn + rk[q] * vv[q]) * bf2f(gg[q])); }
	v_readlane_b32 s43, v174, 32
	v_readlane_b32 s47, v241, 32
	v_readlane_b32 s51, v247, 32
	v_mov_b32_e32 v168, s36
	v_mov_b32_e32 v174, s40
	v_mov_b32_e32 v241, s44
	v_mov_b32_e32 v247, s48
	v_mov_b32_e32 v169, s37
	v_mov_b32_e32 v175, s41
	v_mov_b32_e32 v242, s45
	v_mov_b32_e32 v248, s49
	v_add_f32_e32 v168, s38, v168
	v_add_f32_e32 v174, s42, v174
	v_add_f32_e32 v241, s46, v241
	v_add_f32_e32 v247, s50, v247
	v_add_f32_e32 v169, s39, v169
	v_add_f32_e32 v175, s43, v175
	v_add_f32_e32 v242, s47, v242
	v_add_f32_e32 v248, s51, v248
	v_add_f32_e32 v168, v168, v169
	v_add_f32_e32 v174, v174, v175
	v_add_f32_e32 v241, v241, v242
	v_add_f32_e32 v247, v247, v248
	v_fmamk_f32 v168, v168, 0x3c800000, v9
	v_fmamk_f32 v174, v174, 0x3c800000, v9
	v_fmamk_f32 v241, v241, 0x3c800000, v9
	v_fmamk_f32 v247, v247, 0x3c800000, v9
	v_readfirstlane_b32 s40, v174
	v_readfirstlane_b32 s44, v241
	v_readfirstlane_b32 s48, v247
	v_writelane_b32 v168, s40, 1
	v_writelane_b32 v168, s44, 2
	v_writelane_b32 v168, s48, 3
	v_mul_f32_e32 v169, 0x4f800000, v168
	v_cmp_gt_f32_e64 s[52:53], s68, v168
	v_mov_b32_e32 v170, v168
	s_nop 1
	v_cndmask_b32_e64 v168, v170, v169, s[52:53]
	v_sqrt_f32_e32 v169, v168
	s_nop 0
	v_add_u32_e32 v170, -1, v169
	v_fma_f32 v171, -v170, v169, v168
	v_cmp_ge_f32_e64 s[60:61], 0, v171
	v_add_u32_e32 v171, 1, v169
	s_nop 1
	v_cndmask_b32_e64 v170, v169, v170, s[60:61]
	v_fma_f32 v169, -v171, v169, v168
	v_cmp_lt_f32_e64 s[60:61], 0, v169
	s_nop 1
	v_cndmask_b32_e64 v169, v170, v171, s[60:61]
	v_mul_f32_e32 v170, 0x37800000, v169
	v_cndmask_b32_e64 v169, v169, v170, s[52:53]
	v_cmp_class_f32_e64 s[60:61], v168, v8
	s_nop 1
	v_cndmask_b32_e64 v168, v169, v168, s[60:61]
	v_div_scale_f32 v169, s[60:61], v168, v168, 1.0
	v_rcp_f32_e32 v170, v169
	s_nop 0
	v_fma_f32 v171, -v169, v170, 1.0
	v_fmac_f32_e32 v170, v171, v170
	v_div_scale_f32 v171, vcc, 1.0, v168, 1.0
	v_mul_f32_e32 v172, v171, v170
	v_fma_f32 v173, -v169, v172, v171
	v_fmac_f32_e32 v172, v173, v170
	v_fma_f32 v169, -v169, v172, v171
	v_div_fmas_f32 v169, v169, v170, v172
	v_div_fixup_f32 v168, v169, v168, 1.0
	s_nop 0
	v_readlane_b32 s37, v168, 0
	v_readlane_b32 s41, v168, 1
	v_readlane_b32 s45, v168, 2
	v_readlane_b32 s49, v168, 3
	v_mul_f32_e32 v80, s37, v80
	v_mul_f32_e32 v85, s41, v85
	v_mul_f32_e32 v90, s45, v90
	v_mul_f32_e32 v95, s49, v95
	v_lshlrev_b32_e32 v83, 16, v83
	v_lshlrev_b32_e32 v88, 16, v88
	v_lshlrev_b32_e32 v93, 16, v93
	v_lshlrev_b32_e32 v98, 16, v98
	v_fma_f32 v80, v6, v80, v7
	v_fma_f32 v85, v6, v85, v7
	v_fma_f32 v90, v6, v90, v7
	v_fma_f32 v95, v6, v95, v7
	v_fmac_f32_e32 v80, s69, v81
	v_fmac_f32_e32 v85, s70, v86
	v_fmac_f32_e32 v90, s71, v91
	v_fmac_f32_e32 v95, s72, v96
	v_mul_f32_e32 v80, v80, v83
	v_mul_f32_e32 v85, v85, v88
	v_mul_f32_e32 v90, v90, v93
	v_mul_f32_e32 v95, v95, v98
	v_cvt_pk_bf16_f32 v169, v80, v80
	v_cvt_pk_bf16_f32 v175, v85, v85
	v_cvt_pk_bf16_f32 v242, v90, v90
	v_cvt_pk_bf16_f32 v248, v95, v95
	global_store_short v2, v169, s[28:29]
	s_add_u32 s28, s28, 0x1000
	s_addc_u32 s29, s29, 0
	global_store_short v2, v175, s[28:29]
	s_add_u32 s28, s28, 0x1000
	s_addc_u32 s29, s29, 0
	global_store_short v2, v242, s[28:29]
	s_add_u32 s28, s28, 0x1000
	s_addc_u32 s29, s29, 0
	global_store_short v2, v248, s[28:29]
	s_add_u32 s28, s28, 0x1000
	s_addc_u32 s29, s29, 0
	s_waitcnt lgkmcnt(0)
	v_add_f32_e32 v100, v100, v72
	v_add_f32_e32 v105, v105, v73
	v_add_f32_e32 v110, v110, v74
	v_add_f32_e32 v115, v115, v75
	v_add_f32_dpp v168, v100, v100 quad_perm:[1,0,3,2] row_mask:0xf bank_mask:0xf bound_ctrl:1
	v_add_f32_dpp v174, v105, v105 quad_perm:[1,0,3,2] row_mask:0xf bank_mask:0xf bound_ctrl:1
	v_add_f32_dpp v241, v110, v110 quad_perm:[1,0,3,2] row_mask:0xf bank_mask:0xf bound_ctrl:1
	v_add_f32_dpp v247, v115, v115 quad_perm:[1,0,3,2] row_mask:0xf bank_mask:0xf bound_ctrl:1
	v_add_f32_dpp v168, v168, v168 quad_perm:[2,3,0,1] row_mask:0xf bank_mask:0xf bound_ctrl:1
	v_add_f32_dpp v174, v174, v174 quad_perm:[2,3,0,1] row_mask:0xf bank_mask:0xf bound_ctrl:1
	v_add_f32_dpp v241, v241, v241 quad_perm:[2,3,0,1] row_mask:0xf bank_mask:0xf bound_ctrl:1
	v_add_f32_dpp v247, v247, v247 quad_perm:[2,3,0,1] row_mask:0xf bank_mask:0xf bound_ctrl:1
	v_add_f32_dpp v168, v168, v168 row_half_mirror row_mask:0xf bank_mask:0xf bound_ctrl:1
	v_add_f32_dpp v174, v174, v174 row_half_mirror row_mask:0xf bank_mask:0xf bound_ctrl:1
	v_add_f32_dpp v241, v241, v241 row_half_mirror row_mask:0xf bank_mask:0xf bound_ctrl:1
	v_add_f32_dpp v247, v247, v247 row_half_mirror row_mask:0xf bank_mask:0xf bound_ctrl:1
	v_add_f32_dpp v168, v168, v168 row_mirror row_mask:0xf bank_mask:0xf bound_ctrl:1
	v_add_f32_dpp v174, v174, v174 row_mirror row_mask:0xf bank_mask:0xf bound_ctrl:1
	v_add_f32_dpp v241, v241, v241 row_mirror row_mask:0xf bank_mask:0xf bound_ctrl:1
	v_add_f32_dpp v247, v247, v247 row_mirror row_mask:0xf bank_mask:0xf bound_ctrl:1
	v_readlane_b32 s36, v168, 16
	v_readlane_b32 s40, v174, 16
	v_readlane_b32 s44, v241, 16
	v_readlane_b32 s48, v247, 16
	v_readlane_b32 s37, v168, 48
	v_readlane_b32 s41, v174, 48
	v_readlane_b32 s45, v241, 48
	v_readlane_b32 s49, v247, 48
	v_readlane_b32 s38, v168, 0
	v_readlane_b32 s42, v174, 0
	v_readlane_b32 s46, v241, 0
	v_readlane_b32 s50, v247, 0
	v_readlane_b32 s39, v168, 32
	v_readlane_b32 s43, v174, 32
	v_readlane_b32 s47, v241, 32
	v_readlane_b32 s51, v247, 32
	v_mov_b32_e32 v168, s36
	v_mov_b32_e32 v174, s40
	v_mov_b32_e32 v241, s44
	v_mov_b32_e32 v247, s48
	v_mov_b32_e32 v169, s37
	v_mov_b32_e32 v175, s41
	v_mov_b32_e32 v242, s45
	v_mov_b32_e32 v248, s49
	v_add_f32_e32 v168, s38, v168
	v_add_f32_e32 v174, s42, v174
	v_add_f32_e32 v241, s46, v241
; __device__ __forceinline__ float bf2f(bf16 x) { return __uint_as_float(((unsigned)x) << 16); }
; __device__ __forceinline__ unsigned f2bf(float f) { return cvt_pk_bf16(f, 0.f) & 0xffffu; }
; #define POST_LD(Y_, V_, G_, R_, C_, t) do { _Pragma("unroll") for (int q = 0; q < 8; ++q) { const size_t o_ = (size_t)((t) + q) * DH; Y_[q] = yp[o_]; V_[q] = vp[o_]; G_[q] = gp[o_]; R_[q] = rp[((t) + q) * 32]; C_[q] = cp[o_]; } } while (0)
; __device__ __forceinline__ void rw_post(Frame& F) {
;     ...
;         POST_LD(y, vv, gg, rk, cc, 0);
;         for (int t0 = 0; t0 < 64; t0 += 8) {
;             float ny[8], nv[8], nr[8], nc[8]; bf16 ng[8];
;             const int tn = t0 + 8 < 64 ? t0 + 8 : t0;
;             POST_LD(ny, nv, ng, nr, nc, tn);
;     ...
;             for (int q = 0; q < 8; ++q) { const int row = rb0 + t0 + q;
;                 const float mean = wsum(y[q]) * (1.f / 64.f); const float dv = y[q] - mean; const float var = wsum(dv * dv) * (1.f / 64.f);
;                 const float yn = dv * (1.f / sqrtf(var + 64e-5f)) * g_ + b_;
;                 OB[(size_t)row * DH + col] = (bf16)f2bf((yn + rk[q] * vv[q]) * bf2f(gg[q])); }
	v_add_f32_e32 v247, s50, v247
	v_add_f32_e32 v169, s39, v169
	v_add_f32_e32 v175, s43, v175
	v_add_f32_e32 v242, s47, v242
	v_add_f32_e32 v248, s51, v248
	v_add_f32_e32 v168, v168, v169
	v_add_f32_e32 v174, v174, v175
	v_add_f32_e32 v241, v241, v242
	v_add_f32_e32 v247, v247, v248
	v_fmamk_f32 v100, v168, 0xbc800000, v100
	v_fmamk_f32 v105, v174, 0xbc800000, v105
	v_fmamk_f32 v110, v241, 0xbc800000, v110
	v_fmamk_f32 v115, v247, 0xbc800000, v115
	v_mul_f32_e32 v168, v100, v100
	v_mul_f32_e32 v174, v105, v105
	v_mul_f32_e32 v241, v110, v110
	v_mul_f32_e32 v247, v115, v115
	v_mov_b32_dpp v168, v168 quad_perm:[1,0,3,2] row_mask:0xf bank_mask:0xf bound_ctrl:1
	v_mov_b32_dpp v174, v174 quad_perm:[1,0,3,2] row_mask:0xf bank_mask:0xf bound_ctrl:1
	v_mov_b32_dpp v241, v241 quad_perm:[1,0,3,2] row_mask:0xf bank_mask:0xf bound_ctrl:1
	v_mov_b32_dpp v247, v247 quad_perm:[1,0,3,2] row_mask:0xf bank_mask:0xf bound_ctrl:1
	v_fmac_f32_e32 v168, v100, v100
	v_fmac_f32_e32 v174, v105, v105
	v_fmac_f32_e32 v241, v110, v110
	v_fmac_f32_e32 v247, v115, v115
	v_add_f32_dpp v168, v168, v168 quad_perm:[2,3,0,1] row_mask:0xf bank_mask:0xf bound_ctrl:1
	v_add_f32_dpp v174, v174, v174 quad_perm:[2,3,0,1] row_mask:0xf bank_mask:0xf bound_ctrl:1
	v_add_f32_dpp v241, v241, v241 quad_perm:[2,3,0,1] row_mask:0xf bank_mask:0xf bound_ctrl:1
	v_add_f32_dpp v247, v247, v247 quad_perm:[2,3,0,1] row_mask:0xf bank_mask:0xf bound_ctrl:1
	v_add_f32_dpp v168, v168, v168 row_half_mirror row_mask:0xf bank_mask:0xf bound_ctrl:1
	v_add_f32_dpp v174, v174, v174 row_half_mirror row_mask:0xf bank_mask:0xf bound_ctrl:1
	v_add_f32_dpp v241, v241, v241 row_half_mirror row_mask:0xf bank_mask:0xf bound_ctrl:1
	v_add_f32_dpp v247, v247, v247 row_half_mirror row_mask:0xf bank_mask:0xf bound_ctrl:1
	v_add_f32_dpp v168, v168, v168 row_mirror row_mask:0xf bank_mask:0xf bound_ctrl:1
	v_add_f32_dpp v174, v174, v174 row_mirror row_mask:0xf bank_mask:0xf bound_ctrl:1
	v_add_f32_dpp v241, v241, v241 row_mirror row_mask:0xf bank_mask:0xf bound_ctrl:1
	v_add_f32_dpp v247, v247, v247 row_mirror row_mask:0xf bank_mask:0xf bound_ctrl:1
	v_readlane_b32 s36, v168, 16
	v_readlane_b32 s40, v174, 16
	v_readlane_b32 s44, v241, 16
	v_readlane_b32 s48, v247, 16
	v_readlane_b32 s37, v168, 48
	v_readlane_b32 s41, v174, 48
	v_readlane_b32 s45, v241, 48
	v_readlane_b32 s49, v247, 48
	v_readlane_b32 s38, v168, 0
	v_readlane_b32 s42, v174, 0
	v_readlane_b32 s46, v241, 0
	v_readlane_b32 s50, v247, 0
	v_readlane_b32 s39, v168, 32
	v_readlane_b32 s43, v174, 32
	v_readlane_b32 s47, v241, 32
	v_readlane_b32 s51, v247, 32
	v_mov_b32_e32 v168, s36
	v_mov_b32_e32 v174, s40
	v_mov_b32_e32 v241, s44
	v_mov_b32_e32 v247, s48
	v_mov_b32_e32 v169, s37
	v_mov_b32_e32 v175, s41
	v_mov_b32_e32 v242, s45
	v_mov_b32_e32 v248, s49
	v_add_f32_e32 v168, s38, v168
	v_add_f32_e32 v174, s42, v174
	v_add_f32_e32 v241, s46, v241
	v_add_f32_e32 v247, s50, v247
	v_add_f32_e32 v169, s39, v169
	v_add_f32_e32 v175, s43, v175
	v_add_f32_e32 v242, s47, v242
	v_add_f32_e32 v248, s51, v248
	v_add_f32_e32 v168, v168, v169
	v_add_f32_e32 v174, v174, v175
	v_add_f32_e32 v241, v241, v242
	v_add_f32_e32 v247, v247, v248
	v_fmamk_f32 v168, v168, 0x3c800000, v9
	v_fmamk_f32 v174, v174, 0x3c800000, v9
	v_fmamk_f32 v241, v241, 0x3c800000, v9
	v_fmamk_f32 v247, v247, 0x3c800000, v9
	v_readfirstlane_b32 s40, v174
	v_readfirstlane_b32 s44, v241
	v_readfirstlane_b32 s48, v247
	v_writelane_b32 v168, s40, 1
	v_writelane_b32 v168, s44, 2
	v_writelane_b32 v168, s48, 3
	v_mul_f32_e32 v169, 0x4f800000, v168
	v_cmp_gt_f32_e64 s[52:53], s68, v168
	v_mov_b32_e32 v170, v168
	s_nop 1
	v_cndmask_b32_e64 v168, v170, v169, s[52:53]
	v_sqrt_f32_e32 v169, v168
	s_nop 0
	v_add_u32_e32 v170, -1, v169
	v_fma_f32 v171, -v170, v169, v168
	v_cmp_ge_f32_e64 s[60:61], 0, v171
	v_add_u32_e32 v171, 1, v169
	s_nop 1
	v_cndmask_b32_e64 v170, v169, v170, s[60:61]
	v_fma_f32 v169, -v171, v169, v168
	v_cmp_lt_f32_e64 s[60:61], 0, v169
	s_nop 1
	v_cndmask_b32_e64 v169, v170, v171, s[60:61]
	v_mul_f32_e32 v170, 0x37800000, v169
	v_cndmask_b32_e64 v169, v169, v170, s[52:53]
	v_cmp_class_f32_e64 s[60:61], v168, v8
	s_nop 1
	v_cndmask_b32_e64 v168, v169, v168, s[60:61]
	v_div_scale_f32 v169, s[60:61], v168, v168, 1.0
	v_rcp_f32_e32 v170, v169
	s_nop 0
	v_fma_f32 v171, -v169, v170, 1.0
	v_fmac_f32_e32 v170, v171, v170
	v_div_scale_f32 v171, vcc, 1.0, v168, 1.0
	v_mul_f32_e32 v172, v171, v170
	v_fma_f32 v173, -v169, v172, v171
	v_fmac_f32_e32 v172, v173, v170
	v_fma_f32 v169, -v169, v172, v171
	v_div_fmas_f32 v169, v169, v170, v172
	v_div_fixup_f32 v168, v169, v168, 1.0
	s_nop 0
	v_readlane_b32 s37, v168, 0
	v_readlane_b32 s41, v168, 1
	v_readlane_b32 s45, v168, 2
	v_readlane_b32 s49, v168, 3
	v_mul_f32_e32 v100, s37, v100
	v_mul_f32_e32 v105, s41, v105
	v_mul_f32_e32 v110, s45, v110
	v_mul_f32_e32 v115, s49, v115
	v_lshlrev_b32_e32 v103, 16, v103
	v_lshlrev_b32_e32 v108, 16, v108
	v_lshlrev_b32_e32 v113, 16, v113
	v_lshlrev_b32_e32 v118, 16, v118
	v_fma_f32 v100, v6, v100, v7
	v_fma_f32 v105, v6, v105, v7
	v_fma_f32 v110, v6, v110, v7
	v_fma_f32 v115, v6, v115, v7
	v_fmac_f32_e32 v100, s73, v101
	v_fmac_f32_e32 v105, s26, v106
	v_fmac_f32_e32 v110, s27, v111
	v_fmac_f32_e32 v115, s32, v116
	v_mul_f32_e32 v100, v100, v103
	v_mul_f32_e32 v105, v105, v108
	v_mul_f32_e32 v110, v110, v113
	v_mul_f32_e32 v115, v115, v118
	v_cvt_pk_bf16_f32 v169, v100, v100
	v_cvt_pk_bf16_f32 v175, v105, v105
	v_cvt_pk_bf16_f32 v242, v110, v110
	v_cvt_pk_bf16_f32 v248, v115, v115
	global_store_short v2, v169, s[28:29]
	s_add_u32 s28, s28, 0x1000
	s_addc_u32 s29, s29, 0
	global_store_short v2, v175, s[28:29]
	s_add_u32 s28, s28, 0x1000
	s_addc_u32 s29, s29, 0
	global_store_short v2, v242, s[28:29]
	s_add_u32 s28, s28, 0x1000
	s_addc_u32 s29, s29, 0
	global_store_short v2, v248, s[28:29]
	s_add_u32 s28, s28, 0x1000
	s_addc_u32 s29, s29, 0
	s_waitcnt vmcnt(8)
	ds_write_b128 v13, v[120:123] offset:0
	ds_write_b128 v13, v[124:127] offset:1024
	ds_write_b128 v13, v[128:131] offset:16384
	ds_write_b128 v13, v[132:135] offset:17408
	ds_write_b128 v15, v[136:139]
	v_readlane_b32 s69, v159, 0
	v_readlane_b32 s70, v159, 1
	v_readlane_b32 s71, v159, 2
	v_readlane_b32 s72, v159, 3
	v_readlane_b32 s73, v159, 4
	v_readlane_b32 s26, v159, 5
	v_readlane_b32 s27, v159, 6
	v_readlane_b32 s32, v159, 7
	s_waitcnt lgkmcnt(0)
	s_barrier
; __device__ __forceinline__ float bf2f(bf16 x) { return __uint_as_float(((unsigned)x) << 16); }
; __device__ __forceinline__ unsigned f2bf(float f) { return cvt_pk_bf16(f, 0.f) & 0xffffu; }
; __device__ __forceinline__ void rw_post(Frame& F) {
;     ...
;             for (int q = 0; q < 8; ++q) { const int row = rb0 + t0 + q;
;                 const float mean = wsum(y[q]) * (1.f / 64.f); const float dv = y[q] - mean; const float var = wsum(dv * dv) * (1.f / 64.f);
;                 const float yn = dv * (1.f / sqrtf(var + 64e-5f)) * g_ + b_;
;                 OB[(size_t)row * DH + col] = (bf16)f2bf((yn + rk[q] * vv[q]) * bf2f(gg[q])); }
	ds_read_b32 v80, v155 offset:0
	ds_read_b32 v81, v155 offset:16384
	ds_read_u16 v83, v157 offset:0
	ds_read_b32 v85, v155 offset:2048
	ds_read_b32 v86, v155 offset:18432
	ds_read_u16 v88, v157 offset:1024
	ds_read_b32 v90, v155 offset:4096
	ds_read_b32 v91, v155 offset:20480
	ds_read_u16 v93, v157 offset:2048
	ds_read_b32 v95, v155 offset:6144
	ds_read_b32 v96, v155 offset:22528
	ds_read_u16 v98, v157 offset:3072
	ds_read_b32 v100, v155 offset:8192
	ds_read_b32 v101, v155 offset:24576
	ds_read_u16 v103, v157 offset:4096
	ds_read_b32 v105, v155 offset:10240
	ds_read_b32 v106, v155 offset:26624
	ds_read_u16 v108, v157 offset:5120
	ds_read_b32 v110, v155 offset:12288
	ds_read_b32 v111, v155 offset:28672
	ds_read_u16 v113, v157 offset:6144
	ds_read_b32 v115, v155 offset:14336
	ds_read_b32 v116, v155 offset:30720
	ds_read_u16 v118, v157 offset:7168
	s_waitcnt lgkmcnt(12)
	v_add_f32_e32 v80, v80, v60
	v_add_f32_e32 v85, v85, v61
	v_add_f32_e32 v90, v90, v62
	v_add_f32_e32 v95, v95, v63
	v_add_f32_dpp v168, v80, v80 quad_perm:[1,0,3,2] row_mask:0xf bank_mask:0xf bound_ctrl:1
	v_add_f32_dpp v174, v85, v85 quad_perm:[1,0,3,2] row_mask:0xf bank_mask:0xf bound_ctrl:1
	v_add_f32_dpp v241, v90, v90 quad_perm:[1,0,3,2] row_mask:0xf bank_mask:0xf bound_ctrl:1
	v_add_f32_dpp v247, v95, v95 quad_perm:[1,0,3,2] row_mask:0xf bank_mask:0xf bound_ctrl:1
	v_add_f32_dpp v168, v168, v168 quad_perm:[2,3,0,1] row_mask:0xf bank_mask:0xf bound_ctrl:1
	v_add_f32_dpp v174, v174, v174 quad_perm:[2,3,0,1] row_mask:0xf bank_mask:0xf bound_ctrl:1
	v_add_f32_dpp v241, v241, v241 quad_perm:[2,3,0,1] row_mask:0xf bank_mask:0xf bound_ctrl:1
	v_add_f32_dpp v247, v247, v247 quad_perm:[2,3,0,1] row_mask:0xf bank_mask:0xf bound_ctrl:1
	v_add_f32_dpp v168, v168, v168 row_half_mirror row_mask:0xf bank_mask:0xf bound_ctrl:1
	v_add_f32_dpp v174, v174, v174 row_half_mirror row_mask:0xf bank_mask:0xf bound_ctrl:1
	v_add_f32_dpp v241, v241, v241 row_half_mirror row_mask:0xf bank_mask:0xf bound_ctrl:1
	v_add_f32_dpp v247, v247, v247 row_half_mirror row_mask:0xf bank_mask:0xf bound_ctrl:1
	v_add_f32_dpp v168, v168, v168 row_mirror row_mask:0xf bank_mask:0xf bound_ctrl:1
	v_add_f32_dpp v174, v174, v174 row_mirror row_mask:0xf bank_mask:0xf bound_ctrl:1
	v_add_f32_dpp v241, v241, v241 row_mirror row_mask:0xf bank_mask:0xf bound_ctrl:1
	v_add_f32_dpp v247, v247, v247 row_mirror row_mask:0xf bank_mask:0xf bound_ctrl:1
	v_readlane_b32 s36, v168, 16
	v_readlane_b32 s40, v174, 16
	v_readlane_b32 s44, v241, 16
	v_readlane_b32 s48, v247, 16
	v_readlane_b32 s37, v168, 48
	v_readlane_b32 s41, v174, 48
	v_readlane_b32 s45, v241, 48
	v_readlane_b32 s49, v247, 48
	v_readlane_b32 s38, v168, 0
	v_readlane_b32 s42, v174, 0
	v_readlane_b32 s46, v241, 0
	v_readlane_b32 s50, v247, 0
	v_readlane_b32 s39, v168, 32
	v_readlane_b32 s43, v174, 32
	v_readlane_b32 s47, v241, 32
	v_readlane_b32 s51, v247, 32
	v_mov_b32_e32 v168, s36
	v_mov_b32_e32 v174, s40
	v_mov_b32_e32 v241, s44
	v_mov_b32_e32 v247, s48
	v_mov_b32_e32 v169, s37
	v_mov_b32_e32 v175, s41
	v_mov_b32_e32 v242, s45
	v_mov_b32_e32 v248, s49
	v_add_f32_e32 v168, s38, v168
	v_add_f32_e32 v174, s42, v174
	v_add_f32_e32 v241, s46, v241
	v_add_f32_e32 v247, s50, v247
	v_add_f32_e32 v169, s39, v169
	v_add_f32_e32 v175, s43, v175
	v_add_f32_e32 v242, s47, v242
	v_add_f32_e32 v248, s51, v248
	v_add_f32_e32 v168, v168, v169
	v_add_f32_e32 v174, v174, v175
	v_add_f32_e32 v241, v241, v242
	v_add_f32_e32 v247, v247, v248
	v_fmamk_f32 v80, v168, 0xbc800000, v80
	v_fmamk_f32 v85, v174, 0xbc800000, v85
	v_fmamk_f32 v90, v241, 0xbc800000, v90
	v_fmamk_f32 v95, v247, 0xbc800000, v95
	v_mul_f32_e32 v168, v80, v80
	v_mul_f32_e32 v174, v85, v85
	v_mul_f32_e32 v241, v90, v90
	v_mul_f32_e32 v247, v95, v95
	v_mov_b32_dpp v168, v168 quad_perm:[1,0,3,2] row_mask:0xf bank_mask:0xf bound_ctrl:1
	v_mov_b32_dpp v174, v174 quad_perm:[1,0,3,2] row_mask:0xf bank_mask:0xf bound_ctrl:1
	v_mov_b32_dpp v241, v241 quad_perm:[1,0,3,2] row_mask:0xf bank_mask:0xf bound_ctrl:1
	v_mov_b32_dpp v247, v247 quad_perm:[1,0,3,2] row_mask:0xf bank_mask:0xf bound_ctrl:1
	v_fmac_f32_e32 v168, v80, v80
	v_fmac_f32_e32 v174, v85, v85
	v_fmac_f32_e32 v241, v90, v90
	v_fmac_f32_e32 v247, v95, v95
	v_add_f32_dpp v168, v168, v168 quad_perm:[2,3,0,1] row_mask:0xf bank_mask:0xf bound_ctrl:1
	v_add_f32_dpp v174, v174, v174 quad_perm:[2,3,0,1] row_mask:0xf bank_mask:0xf bound_ctrl:1
	v_add_f32_dpp v241, v241, v241 quad_perm:[2,3,0,1] row_mask:0xf bank_mask:0xf bound_ctrl:1
	v_add_f32_dpp v247, v247, v247 quad_perm:[2,3,0,1] row_mask:0xf bank_mask:0xf bound_ctrl:1
	v_add_f32_dpp v168, v168, v168 row_half_mirror row_mask:0xf bank_mask:0xf bound_ctrl:1
	v_add_f32_dpp v174, v174, v174 row_half_mirror row_mask:0xf bank_mask:0xf bound_ctrl:1
	v_add_f32_dpp v241, v241, v241 row_half_mirror row_mask:0xf bank_mask:0xf bound_ctrl:1
	v_add_f32_dpp v247, v247, v247 row_half_mirror row_mask:0xf bank_mask:0xf bound_ctrl:1
	v_add_f32_dpp v168, v168, v168 row_mirror row_mask:0xf bank_mask:0xf bound_ctrl:1
	v_add_f32_dpp v174, v174, v174 row_mirror row_mask:0xf bank_mask:0xf bound_ctrl:1
	v_add_f32_dpp v241, v241, v241 row_mirror row_mask:0xf bank_mask:0xf bound_ctrl:1
	v_add_f32_dpp v247, v247, v247 row_mirror row_mask:0xf bank_mask:0xf bound_ctrl:1
	v_readlane_b32 s36, v168, 16
	v_readlane_b32 s40, v174, 16
	v_readlane_b32 s44, v241, 16
	v_readlane_b32 s48, v247, 16
	v_readlane_b32 s37, v168, 48
	v_readlane_b32 s41, v174, 48
	v_readlane_b32 s45, v241, 48
	v_readlane_b32 s49, v247, 48
	v_readlane_b32 s38, v168, 0
	v_readlane_b32 s42, v174, 0
	v_readlane_b32 s46, v241, 0
	v_readlane_b32 s50, v247, 0
	v_readlane_b32 s39, v168, 32
; __device__ __forceinline__ float bf2f(bf16 x) { return __uint_as_float(((unsigned)x) << 16); }
; __device__ __forceinline__ unsigned f2bf(float f) { return cvt_pk_bf16(f, 0.f) & 0xffffu; }
; __device__ __forceinline__ void rw_post(Frame& F) {
;     ...
;             for (int q = 0; q < 8; ++q) { const int row = rb0 + t0 + q;
;                 const float mean = wsum(y[q]) * (1.f / 64.f); const float dv = y[q] - mean; const float var = wsum(dv * dv) * (1.f / 64.f);
;                 const float yn = dv * (1.f / sqrtf(var + 64e-5f)) * g_ + b_;
;                 OB[(size_t)row * DH + col] = (bf16)f2bf((yn + rk[q] * vv[q]) * bf2f(gg[q])); }
	v_readlane_b32 s43, v174, 32
	v_readlane_b32 s47, v241, 32
	v_readlane_b32 s51, v247, 32
	v_mov_b32_e32 v168, s36
	v_mov_b32_e32 v174, s40
	v_mov_b32_e32 v241, s44
	v_mov_b32_e32 v247, s48
	v_mov_b32_e32 v169, s37
	v_mov_b32_e32 v175, s41
	v_mov_b32_e32 v242, s45
	v_mov_b32_e32 v248, s49
	v_add_f32_e32 v168, s38, v168
	v_add_f32_e32 v174, s42, v174
	v_add_f32_e32 v241, s46, v241
	v_add_f32_e32 v247, s50, v247
	v_add_f32_e32 v169, s39, v169
	v_add_f32_e32 v175, s43, v175
	v_add_f32_e32 v242, s47, v242
	v_add_f32_e32 v248, s51, v248
	v_add_f32_e32 v168, v168, v169
	v_add_f32_e32 v174, v174, v175
	v_add_f32_e32 v241, v241, v242
	v_add_f32_e32 v247, v247, v248
	v_fmamk_f32 v168, v168, 0x3c800000, v9
	v_fmamk_f32 v174, v174, 0x3c800000, v9
	v_fmamk_f32 v241, v241, 0x3c800000, v9
	v_fmamk_f32 v247, v247, 0x3c800000, v9
	v_readfirstlane_b32 s40, v174
	v_readfirstlane_b32 s44, v241
	v_readfirstlane_b32 s48, v247
	v_writelane_b32 v168, s40, 1
	v_writelane_b32 v168, s44, 2
	v_writelane_b32 v168, s48, 3
	v_mul_f32_e32 v169, 0x4f800000, v168
	v_cmp_gt_f32_e64 s[52:53], s68, v168
	v_mov_b32_e32 v170, v168
	s_nop 1
	v_cndmask_b32_e64 v168, v170, v169, s[52:53]
	v_sqrt_f32_e32 v169, v168
	s_nop 0
	v_add_u32_e32 v170, -1, v169
	v_fma_f32 v171, -v170, v169, v168
	v_cmp_ge_f32_e64 s[60:61], 0, v171
	v_add_u32_e32 v171, 1, v169
	s_nop 1
	v_cndmask_b32_e64 v170, v169, v170, s[60:61]
	v_fma_f32 v169, -v171, v169, v168
	v_cmp_lt_f32_e64 s[60:61], 0, v169
	s_nop 1
	v_cndmask_b32_e64 v169, v170, v171, s[60:61]
	v_mul_f32_e32 v170, 0x37800000, v169
	v_cndmask_b32_e64 v169, v169, v170, s[52:53]
	v_cmp_class_f32_e64 s[60:61], v168, v8
	s_nop 1
	v_cndmask_b32_e64 v168, v169, v168, s[60:61]
	v_div_scale_f32 v169, s[60:61], v168, v168, 1.0
	v_rcp_f32_e32 v170, v169
	s_nop 0
	v_fma_f32 v171, -v169, v170, 1.0
	v_fmac_f32_e32 v170, v171, v170
	v_div_scale_f32 v171, vcc, 1.0, v168, 1.0
	v_mul_f32_e32 v172, v171, v170
	v_fma_f32 v173, -v169, v172, v171
	v_fmac_f32_e32 v172, v173, v170
	v_fma_f32 v169, -v169, v172, v171
	v_div_fmas_f32 v169, v169, v170, v172
	v_div_fixup_f32 v168, v169, v168, 1.0
	s_nop 0
	v_readlane_b32 s37, v168, 0
	v_readlane_b32 s41, v168, 1
	v_readlane_b32 s45, v168, 2
	v_readlane_b32 s49, v168, 3
	v_mul_f32_e32 v80, s37, v80
	v_mul_f32_e32 v85, s41, v85
	v_mul_f32_e32 v90, s45, v90
	v_mul_f32_e32 v95, s49, v95
	v_lshlrev_b32_e32 v83, 16, v83
	v_lshlrev_b32_e32 v88, 16, v88
	v_lshlrev_b32_e32 v93, 16, v93
	v_lshlrev_b32_e32 v98, 16, v98
	v_fma_f32 v80, v6, v80, v7
	v_fma_f32 v85, v6, v85, v7
	v_fma_f32 v90, v6, v90, v7
	v_fma_f32 v95, v6, v95, v7
	v_fmac_f32_e32 v80, s69, v81
	v_fmac_f32_e32 v85, s70, v86
	v_fmac_f32_e32 v90, s71, v91
	v_fmac_f32_e32 v95, s72, v96
	v_mul_f32_e32 v80, v80, v83
	v_mul_f32_e32 v85, v85, v88
	v_mul_f32_e32 v90, v90, v93
	v_mul_f32_e32 v95, v95, v98
	v_cvt_pk_bf16_f32 v169, v80, v80
	v_cvt_pk_bf16_f32 v175, v85, v85
	v_cvt_pk_bf16_f32 v242, v90, v90
	v_cvt_pk_bf16_f32 v248, v95, v95
	global_store_short v2, v169, s[28:29]
	s_add_u32 s28, s28, 0x1000
	s_addc_u32 s29, s29, 0
	global_store_short v2, v175, s[28:29]
	s_add_u32 s28, s28, 0x1000
	s_addc_u32 s29, s29, 0
	global_store_short v2, v242, s[28:29]
	s_add_u32 s28, s28, 0x1000
	s_addc_u32 s29, s29, 0
	global_store_short v2, v248, s[28:29]
	s_add_u32 s28, s28, 0x1000
	s_addc_u32 s29, s29, 0
	s_waitcnt lgkmcnt(0)
	v_add_f32_e32 v100, v100, v76
	v_add_f32_e32 v105, v105, v77
	v_add_f32_e32 v110, v110, v78
	v_add_f32_e32 v115, v115, v79
	v_add_f32_dpp v168, v100, v100 quad_perm:[1,0,3,2] row_mask:0xf bank_mask:0xf bound_ctrl:1
	v_add_f32_dpp v174, v105, v105 quad_perm:[1,0,3,2] row_mask:0xf bank_mask:0xf bound_ctrl:1
	v_add_f32_dpp v241, v110, v110 quad_perm:[1,0,3,2] row_mask:0xf bank_mask:0xf bound_ctrl:1
	v_add_f32_dpp v247, v115, v115 quad_perm:[1,0,3,2] row_mask:0xf bank_mask:0xf bound_ctrl:1
	v_add_f32_dpp v168, v168, v168 quad_perm:[2,3,0,1] row_mask:0xf bank_mask:0xf bound_ctrl:1
	v_add_f32_dpp v174, v174, v174 quad_perm:[2,3,0,1] row_mask:0xf bank_mask:0xf bound_ctrl:1
	v_add_f32_dpp v241, v241, v241 quad_perm:[2,3,0,1] row_mask:0xf bank_mask:0xf bound_ctrl:1
	v_add_f32_dpp v247, v247, v247 quad_perm:[2,3,0,1] row_mask:0xf bank_mask:0xf bound_ctrl:1
	v_add_f32_dpp v168, v168, v168 row_half_mirror row_mask:0xf bank_mask:0xf bound_ctrl:1
	v_add_f32_dpp v174, v174, v174 row_half_mirror row_mask:0xf bank_mask:0xf bound_ctrl:1
	v_add_f32_dpp v241, v241, v241 row_half_mirror row_mask:0xf bank_mask:0xf bound_ctrl:1
	v_add_f32_dpp v247, v247, v247 row_half_mirror row_mask:0xf bank_mask:0xf bound_ctrl:1
	v_add_f32_dpp v168, v168, v168 row_mirror row_mask:0xf bank_mask:0xf bound_ctrl:1
	v_add_f32_dpp v174, v174, v174 row_mirror row_mask:0xf bank_mask:0xf bound_ctrl:1
	v_add_f32_dpp v241, v241, v241 row_mirror row_mask:0xf bank_mask:0xf bound_ctrl:1
	v_add_f32_dpp v247, v247, v247 row_mirror row_mask:0xf bank_mask:0xf bound_ctrl:1
	v_readlane_b32 s36, v168, 16
	v_readlane_b32 s40, v174, 16
	v_readlane_b32 s44, v241, 16
	v_readlane_b32 s48, v247, 16
	v_readlane_b32 s37, v168, 48
	v_readlane_b32 s41, v174, 48
	v_readlane_b32 s45, v241, 48
	v_readlane_b32 s49, v247, 48
	v_readlane_b32 s38, v168, 0
	v_readlane_b32 s42, v174, 0
	v_readlane_b32 s46, v241, 0
	v_readlane_b32 s50, v247, 0
	v_readlane_b32 s39, v168, 32
	v_readlane_b32 s43, v174, 32
	v_readlane_b32 s47, v241, 32
	v_readlane_b32 s51, v247, 32
	v_mov_b32_e32 v168, s36
	v_mov_b32_e32 v174, s40
	v_mov_b32_e32 v241, s44
	v_mov_b32_e32 v247, s48
	v_mov_b32_e32 v169, s37
	v_mov_b32_e32 v175, s41
	v_mov_b32_e32 v242, s45
	v_mov_b32_e32 v248, s49
	v_add_f32_e32 v168, s38, v168
	v_add_f32_e32 v174, s42, v174
	v_add_f32_e32 v241, s46, v241
; __device__ __forceinline__ float bf2f(bf16 x) { return __uint_as_float(((unsigned)x) << 16); }
; __device__ __forceinline__ unsigned f2bf(float f) { return cvt_pk_bf16(f, 0.f) & 0xffffu; }
; __device__ __forceinline__ void rw_post(Frame& F) {
;     ...
;     for (int u = F.gw; u < 32 * (MR / 64); u += F.NGW) { const int h = u & 31, rb0 = (u >> 5) * 64, col = h * 64 + lane;
;     ...
;             for (int q = 0; q < 8; ++q) { const int row = rb0 + t0 + q;
;                 const float mean = wsum(y[q]) * (1.f / 64.f); const float dv = y[q] - mean; const float var = wsum(dv * dv) * (1.f / 64.f);
;                 const float yn = dv * (1.f / sqrtf(var + 64e-5f)) * g_ + b_;
;                 OB[(size_t)row * DH + col] = (bf16)f2bf((yn + rk[q] * vv[q]) * bf2f(gg[q])); }
	v_add_f32_e32 v247, s50, v247
	v_add_f32_e32 v169, s39, v169
	v_add_f32_e32 v175, s43, v175
	v_add_f32_e32 v242, s47, v242
	v_add_f32_e32 v248, s51, v248
	v_add_f32_e32 v168, v168, v169
	v_add_f32_e32 v174, v174, v175
	v_add_f32_e32 v241, v241, v242
	v_add_f32_e32 v247, v247, v248
	v_fmamk_f32 v100, v168, 0xbc800000, v100
	v_fmamk_f32 v105, v174, 0xbc800000, v105
	v_fmamk_f32 v110, v241, 0xbc800000, v110
	v_fmamk_f32 v115, v247, 0xbc800000, v115
	v_mul_f32_e32 v168, v100, v100
	v_mul_f32_e32 v174, v105, v105
	v_mul_f32_e32 v241, v110, v110
	v_mul_f32_e32 v247, v115, v115
	v_mov_b32_dpp v168, v168 quad_perm:[1,0,3,2] row_mask:0xf bank_mask:0xf bound_ctrl:1
	v_mov_b32_dpp v174, v174 quad_perm:[1,0,3,2] row_mask:0xf bank_mask:0xf bound_ctrl:1
	v_mov_b32_dpp v241, v241 quad_perm:[1,0,3,2] row_mask:0xf bank_mask:0xf bound_ctrl:1
	v_mov_b32_dpp v247, v247 quad_perm:[1,0,3,2] row_mask:0xf bank_mask:0xf bound_ctrl:1
	v_fmac_f32_e32 v168, v100, v100
	v_fmac_f32_e32 v174, v105, v105
	v_fmac_f32_e32 v241, v110, v110
	v_fmac_f32_e32 v247, v115, v115
	v_add_f32_dpp v168, v168, v168 quad_perm:[2,3,0,1] row_mask:0xf bank_mask:0xf bound_ctrl:1
	v_add_f32_dpp v174, v174, v174 quad_perm:[2,3,0,1] row_mask:0xf bank_mask:0xf bound_ctrl:1
	v_add_f32_dpp v241, v241, v241 quad_perm:[2,3,0,1] row_mask:0xf bank_mask:0xf bound_ctrl:1
	v_add_f32_dpp v247, v247, v247 quad_perm:[2,3,0,1] row_mask:0xf bank_mask:0xf bound_ctrl:1
	v_add_f32_dpp v168, v168, v168 row_half_mirror row_mask:0xf bank_mask:0xf bound_ctrl:1
	v_add_f32_dpp v174, v174, v174 row_half_mirror row_mask:0xf bank_mask:0xf bound_ctrl:1
	v_add_f32_dpp v241, v241, v241 row_half_mirror row_mask:0xf bank_mask:0xf bound_ctrl:1
	v_add_f32_dpp v247, v247, v247 row_half_mirror row_mask:0xf bank_mask:0xf bound_ctrl:1
	v_add_f32_dpp v168, v168, v168 row_mirror row_mask:0xf bank_mask:0xf bound_ctrl:1
	v_add_f32_dpp v174, v174, v174 row_mirror row_mask:0xf bank_mask:0xf bound_ctrl:1
	v_add_f32_dpp v241, v241, v241 row_mirror row_mask:0xf bank_mask:0xf bound_ctrl:1
	v_add_f32_dpp v247, v247, v247 row_mirror row_mask:0xf bank_mask:0xf bound_ctrl:1
	v_readlane_b32 s36, v168, 16
	v_readlane_b32 s40, v174, 16
	v_readlane_b32 s44, v241, 16
	v_readlane_b32 s48, v247, 16
	v_readlane_b32 s37, v168, 48
	v_readlane_b32 s41, v174, 48
	v_readlane_b32 s45, v241, 48
	v_readlane_b32 s49, v247, 48
	v_readlane_b32 s38, v168, 0
	v_readlane_b32 s42, v174, 0
	v_readlane_b32 s46, v241, 0
	v_readlane_b32 s50, v247, 0
	v_readlane_b32 s39, v168, 32
	v_readlane_b32 s43, v174, 32
	v_readlane_b32 s47, v241, 32
	v_readlane_b32 s51, v247, 32
	v_mov_b32_e32 v168, s36
	v_mov_b32_e32 v174, s40
	v_mov_b32_e32 v241, s44
	v_mov_b32_e32 v247, s48
	v_mov_b32_e32 v169, s37
	v_mov_b32_e32 v175, s41
	v_mov_b32_e32 v242, s45
	v_mov_b32_e32 v248, s49
	v_add_f32_e32 v168, s38, v168
	v_add_f32_e32 v174, s42, v174
	v_add_f32_e32 v241, s46, v241
	v_add_f32_e32 v247, s50, v247
	v_add_f32_e32 v169, s39, v169
	v_add_f32_e32 v175, s43, v175
	v_add_f32_e32 v242, s47, v242
	v_add_f32_e32 v248, s51, v248
	v_add_f32_e32 v168, v168, v169
	v_add_f32_e32 v174, v174, v175
	v_add_f32_e32 v241, v241, v242
	v_add_f32_e32 v247, v247, v248
	v_fmamk_f32 v168, v168, 0x3c800000, v9
	v_fmamk_f32 v174, v174, 0x3c800000, v9
	v_fmamk_f32 v241, v241, 0x3c800000, v9
	v_fmamk_f32 v247, v247, 0x3c800000, v9
	v_readfirstlane_b32 s40, v174
	v_readfirstlane_b32 s44, v241
	v_readfirstlane_b32 s48, v247
	v_writelane_b32 v168, s40, 1
	v_writelane_b32 v168, s44, 2
	v_writelane_b32 v168, s48, 3
	v_mul_f32_e32 v169, 0x4f800000, v168
	v_cmp_gt_f32_e64 s[52:53], s68, v168
	v_mov_b32_e32 v170, v168
	s_nop 1
	v_cndmask_b32_e64 v168, v170, v169, s[52:53]
	v_sqrt_f32_e32 v169, v168
	s_nop 0
	v_add_u32_e32 v170, -1, v169
	v_fma_f32 v171, -v170, v169, v168
	v_cmp_ge_f32_e64 s[60:61], 0, v171
	v_add_u32_e32 v171, 1, v169
	s_nop 1
	v_cndmask_b32_e64 v170, v169, v170, s[60:61]
	v_fma_f32 v169, -v171, v169, v168
	v_cmp_lt_f32_e64 s[60:61], 0, v169
	s_nop 1
	v_cndmask_b32_e64 v169, v170, v171, s[60:61]
	v_mul_f32_e32 v170, 0x37800000, v169
	v_cndmask_b32_e64 v169, v169, v170, s[52:53]
	v_cmp_class_f32_e64 s[60:61], v168, v8
	s_nop 1
	v_cndmask_b32_e64 v168, v169, v168, s[60:61]
	v_div_scale_f32 v169, s[60:61], v168, v168, 1.0
	v_rcp_f32_e32 v170, v169
	s_nop 0
	v_fma_f32 v171, -v169, v170, 1.0
	v_fmac_f32_e32 v170, v171, v170
	v_div_scale_f32 v171, vcc, 1.0, v168, 1.0
	v_mul_f32_e32 v172, v171, v170
	v_fma_f32 v173, -v169, v172, v171
	v_fmac_f32_e32 v172, v173, v170
	v_fma_f32 v169, -v169, v172, v171
	v_div_fmas_f32 v169, v169, v170, v172
	v_div_fixup_f32 v168, v169, v168, 1.0
	s_nop 0
	v_readlane_b32 s37, v168, 0
	v_readlane_b32 s41, v168, 1
	v_readlane_b32 s45, v168, 2
	v_readlane_b32 s49, v168, 3
	v_mul_f32_e32 v100, s37, v100
	v_mul_f32_e32 v105, s41, v105
	v_mul_f32_e32 v110, s45, v110
	v_mul_f32_e32 v115, s49, v115
	v_lshlrev_b32_e32 v103, 16, v103
	v_lshlrev_b32_e32 v108, 16, v108
	v_lshlrev_b32_e32 v113, 16, v113
	v_lshlrev_b32_e32 v118, 16, v118
	v_fma_f32 v100, v6, v100, v7
	v_fma_f32 v105, v6, v105, v7
	v_fma_f32 v110, v6, v110, v7
	v_fma_f32 v115, v6, v115, v7
	v_fmac_f32_e32 v100, s73, v101
	v_fmac_f32_e32 v105, s26, v106
	v_fmac_f32_e32 v110, s27, v111
	v_fmac_f32_e32 v115, s32, v116
	v_mul_f32_e32 v100, v100, v103
	v_mul_f32_e32 v105, v105, v108
	v_mul_f32_e32 v110, v110, v113
	v_mul_f32_e32 v115, v115, v118
	v_cvt_pk_bf16_f32 v169, v100, v100
	v_cvt_pk_bf16_f32 v175, v105, v105
	v_cvt_pk_bf16_f32 v242, v110, v110
	v_cvt_pk_bf16_f32 v248, v115, v115
	global_store_short v2, v169, s[28:29]
	s_add_u32 s28, s28, 0x1000
	s_addc_u32 s29, s29, 0
	global_store_short v2, v175, s[28:29]
	s_add_u32 s28, s28, 0x1000
	s_addc_u32 s29, s29, 0
	global_store_short v2, v242, s[28:29]
	s_add_u32 s28, s28, 0x1000
	s_addc_u32 s29, s29, 0
	global_store_short v2, v248, s[28:29]
	s_add_u32 s28, s28, 0x1000
	s_addc_u32 s29, s29, 0
	s_add_i32 s20, s20, s92
	s_cmpk_lt_i32 s20, 0x2040
	s_cbranch_scc1 .Lpo_unit
